# static s_setprio 1 for the odd wave slot of each SIMD inside the four DMA GEMM k-loops (reset to 0 after the loop), on top of v27
# speedup vs baseline: 1.0033x; 1.0033x over previous
; DI int otid() { int t = threadIdx.x; asm volatile("" : "+v"(t)); return t; }
; #define GEMM_DMA(kt) { GEMM_DMA_A(kt) GEMM_DMA_B(kt) }
; template <int EPI>
; __device__ __forceinline__ void gemm_tile_dma(const bft* __restrict__ A, int lda, const bft* __restrict__ Bt, int K, int row0, int col0,
;                                               char* smem, const EpiArgs& e) {
;   const int tid = otid(), wave = tid >> 6, lane = tid & 63;
;   const int wm = wave >> 2, wn = wave & 3, r16 = lane & 15, g = lane >> 4;
;   f32x4 accL[4][4], accH[4][4];
; #pragma unroll
;   for (int i = 0; i < 4; ++i)
; #pragma unroll
;     for (int j = 0; j < 4; ++j) { accL[i][j] = (f32x4){0.f, 0.f, 0.f, 0.f}; accH[i][j] = (f32x4){0.f, 0.f, 0.f, 0.f}; }
;   const int lr = tid >> 2, pc = tid & 3;
;   const int kcs = (pc ^ ((4 - ((lr >> 2) & 3)) & 3)) * 8;
;   const int rco = (g ^ ((4 - ((r16 >> 2) & 3)) & 3)) * 8;
;   const bft* ag = A + (size_t)(row0 + lr) * lda + kcs;
;   const bft* bg = Bt + (size_t)(col0 + lr) * K + kcs;
;   const unsigned lds_a = (unsigned)(size_t)smem + (unsigned)(((wm * 128 + r16) * 32 + rco) * 2);
;   const unsigned lds_b = (unsigned)(size_t)smem + 16384u + (unsigned)(((wn * 64 + r16) * 32 + rco) * 2);
;   const int nk = K / 32;
;     ...
;   GEMM_DMA(0);
;   GEMM_DMA(1);
;   GEMM_DMA(2);
; template <int EPI, bool RMS>
; __device__ __forceinline__ void gemm_phase(const bft* A, int lda, const bft* Bt, int K, int ntn, char* smem, const EpiArgs& e) {
;   const int G8 = gridDim.x >> 3, xcd = blockIdx.x & 7, loc = blockIdx.x >> 3;
;   constexpr int RT = 34;
;   const int per = RT * ntn;
;   for (int idx = loc; idx < per; idx += G8) {
;     const int grp = idx / (8 * ntn);
;     const int within = idx - grp * (8 * ntn);
;     const int rig = (grp < RT / 8) ? 8 : RT % 8;
;     const int tm = xcd * RT + grp * 8 + within % rig, tn = within / rig;
.LBB0_218:
	s_and_b32 s6, s27, 0xffff
	s_mul_hi_u32 s7, s6, 0x3333334
	s_mul_i32 s6, s6, 0xcccd
	s_lshr_b32 s6, s6, 22
	s_lshl_b32 s9, s7, 3
	s_mul_i32 s7, s6, 0xffb0
	s_add_i32 s10, s7, s27
	s_lshl_b32 s11, s6, 3
	s_cmpk_lt_u32 s27, 0x140
	s_cselect_b32 s12, 8, 2
	s_sext_i32_i16 s6, s10
	v_cvt_f32_ubyte0_e32 v1, s12
	v_cvt_f32_i32_e32 v0, s6
	v_rcp_iflag_f32_e32 v2, v1
	s_ashr_i32 s6, s6, 30
	s_or_b32 s13, s6, 1
	v_mov_b32_e32 v133, v196
	v_mul_f32_e32 v2, v0, v2
	v_trunc_f32_e32 v2, v2
	v_fma_f32 v0, -v2, v1, v0
	v_cvt_i32_f32_e32 v2, v2
	v_cmp_ge_f32_e64 s[6:7], |v0|, v1
	s_and_b64 s[6:7], s[6:7], exec
	s_cselect_b32 s6, s13, 0
	v_readfirstlane_b32 s7, v2
	s_add_i32 s6, s7, s6
	s_sext_i32_i16 s7, s6
	s_mul_i32 s6, s6, s12
	s_sub_i32 s6, s10, s6
	s_sext_i32_i16 s6, s6
	s_add_i32 s6, s3, s6
	s_add_i32 s10, s6, s11
	v_lshrrev_b32_e32 v0, 4, v133
	s_waitcnt lgkmcnt(0)
	v_sub_u32_e32 v9, 0, v0
	v_lshlrev_b32_e32 v0, 2, v133
	s_lshl_b32 s11, s10, 8
	v_ashrrev_i32_e32 v8, 2, v133
	v_xor_b32_e32 v2, v133, v9
	v_and_b32_e32 v0, 48, v0
	s_lshl_b32 s12, s7, 8
	v_sub_u32_e32 v10, 0, v0
	v_add_u32_e32 v0, s11, v8
	v_lshlrev_b32_e32 v2, 4, v2
	v_ashrrev_i32_e32 v1, 31, v0
	v_and_b32_e32 v160, 48, v2
	v_add_u32_e32 v2, s12, v8
	v_lshlrev_b64 v[0:1], 11, v[0:1]
	v_ashrrev_i32_e32 v3, 31, v2
	v_readlane_b32 s14, v254, 35
	v_lshlrev_b32_e32 v137, 4, v133
	v_lshl_add_u64 v[0:1], s[62:63], 0, v[0:1]
	v_lshlrev_b64 v[2:3], 11, v[2:3]
	v_readlane_b32 s15, v254, 36
	v_readfirstlane_b32 s7, v137
	v_add_u32_e32 v13, 0x2000, v137
	v_lshl_add_u64 v[0:1], v[0:1], 0, v[160:161]
	v_lshl_add_u64 v[4:5], s[14:15], 0, v[2:3]
	v_ashrrev_i32_e32 v6, 1, v133
	s_mov_b32 m0, s7
	s_mov_b64 s[14:15], 0x40000
	v_readfirstlane_b32 s7, v13
	v_and_b32_e32 v132, 0xffffff80, v6
	global_load_lds_dwordx4 v[0:1], off
	v_lshl_add_u64 v[6:7], v[0:1], 0, s[14:15]
	s_mov_b32 m0, s7
	v_add_u32_e32 v13, 0x6000, v137
	global_load_lds_dwordx4 v[6:7], off
	v_add_u32_e32 v6, 0x4000, v137
	v_lshl_add_u64 v[4:5], v[4:5], 0, v[160:161]
	v_readfirstlane_b32 s7, v6
	s_mov_b32 m0, s7
	v_readfirstlane_b32 s7, v13
	v_add_u32_e32 v13, 0x8000, v137
	global_load_lds_dwordx4 v[4:5], off
	v_lshl_add_u64 v[6:7], v[4:5], 0, s[14:15]
	s_mov_b32 m0, s7
	v_readfirstlane_b32 s7, v13
	v_add_u32_e32 v13, 0xa000, v137
	global_load_lds_dwordx4 v[6:7], off
	v_lshl_add_u64 v[6:7], v[0:1], 0, 64
	s_mov_b32 m0, s7
	s_mov_b64 s[14:15], 0x40040
	v_readfirstlane_b32 s7, v13
	v_add_u32_e32 v13, 0xc000, v137
	global_load_lds_dwordx4 v[6:7], off
	v_lshl_add_u64 v[6:7], v[0:1], 0, s[14:15]
	s_mov_b32 m0, s7
	v_readfirstlane_b32 s7, v13
	v_add_u32_e32 v13, 0xe000, v137
	global_load_lds_dwordx4 v[6:7], off
	v_lshl_add_u64 v[6:7], v[4:5], 0, 64
	s_mov_b32 m0, s7
	v_readfirstlane_b32 s7, v13
	v_add_u32_e32 v13, 0x10000, v137
	global_load_lds_dwordx4 v[6:7], off
	v_lshl_add_u64 v[6:7], v[4:5], 0, s[14:15]
	s_mov_b32 m0, s7
	s_mov_b64 s[14:15], 0x80
	v_readfirstlane_b32 s7, v13
	global_load_lds_dwordx4 v[6:7], off
	v_lshl_add_u64 v[6:7], v[0:1], 0, s[14:15]
	s_mov_b32 m0, s7
	s_mov_b64 s[16:17], 0x40080
	global_load_lds_dwordx4 v[6:7], off
	v_add_u32_e32 v6, 0x12000, v137
	v_lshl_add_u64 v[0:1], v[0:1], 0, s[16:17]
	v_readfirstlane_b32 s7, v6
	v_add_u32_e32 v6, 0x14000, v137
	s_mov_b32 m0, s7
	v_readfirstlane_b32 s7, v6
	global_load_lds_dwordx4 v[0:1], off
	v_lshl_add_u64 v[0:1], v[4:5], 0, s[14:15]
	s_mov_b32 m0, s7
	v_lshlrev_b32_e32 v12, 6, v133
	global_load_lds_dwordx4 v[0:1], off
	v_lshl_add_u64 v[0:1], v[4:5], 0, s[16:17]
	v_add_u32_e32 v4, 0x16000, v137
	v_bitop3_b32 v10, v133, 48, v10 bitop3:0x48
	v_readfirstlane_b32 s7, v4
	s_mov_b32 m0, s7
	s_add_i32 s6, s6, s9
	global_load_lds_dwordx4 v[0:1], off
	v_and_b32_e32 v0, 0x33c0, v12
	v_or3_b32 v136, v0, v10, s18
	v_bitop3_b32 v0, v133, 3, v9 bitop3:0x48
	s_lshl_b32 s34, s6, 8
	v_lshlrev_b32_e32 v4, 4, v0
	v_add_u32_e32 v0, s34, v8
	v_ashrrev_i32_e32 v1, 31, v0
	v_lshlrev_b64 v[0:1], 11, v[0:1]
	v_and_b32_e32 v135, 15, v133
	v_or_b32_e32 v0, v0, v4
	v_or_b32_e32 v11, v132, v135
	v_or_b32_e32 v2, v2, v4
	s_waitcnt vmcnt(0)
	v_lshl_add_u64 v[130:131], s[90:91], 0, v[0:1]
	v_mov_b32_e32 v0, 0
	s_mov_b32 s8, 0
	v_lshl_or_b32 v134, v11, 6, v10
	v_lshl_add_u64 v[128:129], s[90:91], 0, v[2:3]
	s_mov_b64 s[6:7], 0
	v_mov_b32_e32 v1, v0
	v_mov_b32_e32 v2, v0
	v_mov_b32_e32 v3, v0
	v_mov_b32_e32 v4, v0
	v_mov_b32_e32 v5, v0
	v_mov_b32_e32 v6, v0
	v_mov_b32_e32 v7, v0
	v_mov_b32_e32 v8, v0
	v_mov_b32_e32 v9, v0
	v_mov_b32_e32 v10, v0
	v_mov_b32_e32 v11, v0
	v_mov_b32_e32 v12, v0
	v_mov_b32_e32 v13, v0
	v_mov_b32_e32 v14, v0
	v_mov_b32_e32 v15, v0
	v_mov_b32_e32 v16, v0
	v_mov_b32_e32 v17, v0
	v_mov_b32_e32 v18, v0
	v_mov_b32_e32 v19, v0
	v_mov_b32_e32 v20, v0
	v_mov_b32_e32 v21, v0
	v_mov_b32_e32 v22, v0
	s_waitcnt vmcnt(0)
; #define ROW4(accv, r, av)                                                                              \
;     accv[r][0] = MFMA16(av, b0, accv[r][0]); accv[r][1] = MFMA16(av, b1, accv[r][1]);                      \
;     accv[r][2] = MFMA16(av, b2, accv[r][2]); accv[r][3] = MFMA16(av, b3, accv[r][3]);
; template <int EPI>
; __device__ __forceinline__ void gemm_tile_dma(const bft* __restrict__ A, int lda, const bft* __restrict__ Bt, int K, int row0, int col0,
;                                               char* smem, const EpiArgs& e) {
;     ...
;   f32x4 accL[4][4], accH[4][4];
; #pragma unroll
;   for (int i = 0; i < 4; ++i)
; #pragma unroll
;     for (int j = 0; j < 4; ++j) { accL[i][j] = (f32x4){0.f, 0.f, 0.f, 0.f}; accH[i][j] = (f32x4){0.f, 0.f, 0.f, 0.f}; }
;     ...
;   for (int kt = 0; kt < nk; ++kt) {
;     if (kt + 2 < nk) asm volatile("s_waitcnt vmcnt(8)" ::: "memory");
;     else if (kt + 1 < nk) asm volatile("s_waitcnt vmcnt(4)" ::: "memory");
;     else asm volatile("s_waitcnt vmcnt(0)" ::: "memory");
;     __builtin_amdgcn_s_barrier();
;     asm volatile("" ::: "memory");
;     const bool pf = kt + 3 < nk;
;     const unsigned so = (unsigned)(kt & 3) * GST;
;     bf16x8 a0, a1, a2, a3, b0, b1, b2, b3;
;     asm volatile(
;         "ds_read_b128 %0, %8\n\t"
;         "ds_read_b128 %1, %8 offset:1024\n\t"
;         "ds_read_b128 %2, %8 offset:2048\n\t"
;         "ds_read_b128 %3, %8 offset:3072\n\t"
;         "ds_read_b128 %4, %9\n\t"
;         "ds_read_b128 %5, %9 offset:1024\n\t"
;         "ds_read_b128 %6, %9 offset:2048\n\t"
;         "ds_read_b128 %7, %9 offset:3072\n\t"
;         "s_waitcnt lgkmcnt(0)"
;         : "=&v"(a0), "=&v"(a1), "=&v"(a2), "=&v"(a3), "=&v"(b0), "=&v"(b1), "=&v"(b2), "=&v"(b3)
;         : "v"(lds_a + so), "v"(lds_b + so)
;         : "memory");
;     ...
;     ROW4(accL, 0, a0) ROW4(accL, 1, a1)
;     if (pf) GEMM_DMA_A(kt + 3)
;     ROW4(accL, 2, a2) ROW4(accL, 3, a3)
;     asm volatile(
;         "ds_read_b128 %0, %4 offset:4096\n\t"
;         "ds_read_b128 %1, %4 offset:5120\n\t"
;         "ds_read_b128 %2, %4 offset:6144\n\t"
;         "ds_read_b128 %3, %4 offset:7168\n\t"
;         "s_waitcnt lgkmcnt(0)"
;         : "=&v"(a0), "=&v"(a1), "=&v"(a2), "=&v"(a3)
;         : "v"(lds_a + so)
;         : "memory");
;     ROW4(accH, 0, a0) ROW4(accH, 1, a1)
;     if (pf) GEMM_DMA_B(kt + 3)
;     ROW4(accH, 2, a2) ROW4(accH, 3, a3)
;     ...
;   }
	v_mov_b32_e32 v23, v0
	v_mov_b32_e32 v24, v0
	v_mov_b32_e32 v25, v0
	v_mov_b32_e32 v26, v0
	v_mov_b32_e32 v27, v0
	v_mov_b32_e32 v28, v0
	v_mov_b32_e32 v29, v0
	v_mov_b32_e32 v30, v0
	v_mov_b32_e32 v31, v0
	v_mov_b32_e32 v32, v0
	v_mov_b32_e32 v33, v0
	v_mov_b32_e32 v34, v0
	v_mov_b32_e32 v35, v0
	v_mov_b32_e32 v36, v0
	v_mov_b32_e32 v37, v0
	v_mov_b32_e32 v38, v0
	v_mov_b32_e32 v39, v0
	v_mov_b32_e32 v40, v0
	v_mov_b32_e32 v41, v0
	v_mov_b32_e32 v42, v0
	v_mov_b32_e32 v43, v0
	v_mov_b32_e32 v44, v0
	v_mov_b32_e32 v45, v0
	v_mov_b32_e32 v46, v0
	v_mov_b32_e32 v47, v0
	v_mov_b32_e32 v48, v0
	v_mov_b32_e32 v49, v0
	v_mov_b32_e32 v50, v0
	v_mov_b32_e32 v51, v0
	v_mov_b32_e32 v52, v0
	v_mov_b32_e32 v53, v0
	v_mov_b32_e32 v54, v0
	v_mov_b32_e32 v55, v0
	v_mov_b32_e32 v56, v0
	v_mov_b32_e32 v57, v0
	v_mov_b32_e32 v58, v0
	v_mov_b32_e32 v59, v0
	v_mov_b32_e32 v60, v0
	v_mov_b32_e32 v61, v0
	v_mov_b32_e32 v62, v0
	v_mov_b32_e32 v63, v0
	v_mov_b32_e32 v64, v0
	v_mov_b32_e32 v65, v0
	v_mov_b32_e32 v66, v0
	v_mov_b32_e32 v67, v0
	v_mov_b32_e32 v68, v0
	v_mov_b32_e32 v69, v0
	v_mov_b32_e32 v70, v0
	v_mov_b32_e32 v71, v0
	v_mov_b32_e32 v72, v0
	v_mov_b32_e32 v73, v0
	v_mov_b32_e32 v74, v0
	v_mov_b32_e32 v75, v0
	v_mov_b32_e32 v76, v0
	v_mov_b32_e32 v77, v0
	v_mov_b32_e32 v78, v0
	v_mov_b32_e32 v79, v0
	v_mov_b32_e32 v80, v0
	v_mov_b32_e32 v81, v0
	v_mov_b32_e32 v82, v0
	v_mov_b32_e32 v83, v0
	v_mov_b32_e32 v84, v0
	v_mov_b32_e32 v85, v0
	v_mov_b32_e32 v86, v0
	v_mov_b32_e32 v87, v0
	v_mov_b32_e32 v88, v0
	v_mov_b32_e32 v89, v0
	v_mov_b32_e32 v90, v0
	v_mov_b32_e32 v91, v0
	v_mov_b32_e32 v92, v0
	v_mov_b32_e32 v93, v0
	v_mov_b32_e32 v94, v0
	v_mov_b32_e32 v95, v0
	v_mov_b32_e32 v96, v0
	v_mov_b32_e32 v97, v0
	v_mov_b32_e32 v98, v0
	v_mov_b32_e32 v99, v0
	v_mov_b32_e32 v100, v0
	v_mov_b32_e32 v101, v0
	v_mov_b32_e32 v102, v0
	v_mov_b32_e32 v103, v0
	v_mov_b32_e32 v104, v0
	v_mov_b32_e32 v105, v0
	v_mov_b32_e32 v106, v0
	v_mov_b32_e32 v107, v0
	v_mov_b32_e32 v108, v0
	v_mov_b32_e32 v109, v0
	v_mov_b32_e32 v110, v0
	v_mov_b32_e32 v111, v0
	v_mov_b32_e32 v116, v0
	v_mov_b32_e32 v117, v0
	v_mov_b32_e32 v118, v0
	v_mov_b32_e32 v119, v0
	v_mov_b32_e32 v120, v0
	v_mov_b32_e32 v121, v0
	v_mov_b32_e32 v122, v0
	v_mov_b32_e32 v123, v0
	v_mov_b32_e32 v124, v0
	v_mov_b32_e32 v125, v0
	v_mov_b32_e32 v126, v0
	v_mov_b32_e32 v127, v0
	v_mov_b32_e32 v112, v0
	v_mov_b32_e32 v113, v0
	v_mov_b32_e32 v114, v0
	v_mov_b32_e32 v115, v0
	s_getreg_b32 s16, hwreg(HW_REG_HW_ID, 0, 1)
	s_cmp_eq_u32 s16, 1
	s_cbranch_scc0 .Lgprio3_skip
	s_setprio 1
.Lgprio3_skip:
.LBB0_219:
	s_and_b32 s9, s8, 0x18000
	v_add_u32_e32 v158, s9, v134
	v_or_b32_e32 v159, s9, v136
	s_add_i32 s9, s8, 0x18000
	s_waitcnt vmcnt(8)
	s_barrier
	s_and_b32 s9, s9, 0x18000
	ds_read_b128 v[138:141], v158
	ds_read_b128 v[142:145], v158 offset:1024
	ds_read_b128 v[146:149], v158 offset:2048
	ds_read_b128 v[150:153], v158 offset:3072
	ds_read_b128 v[154:157], v159
	ds_read_b128 v[162:165], v159 offset:1024
	ds_read_b128 v[166:169], v159 offset:2048
	ds_read_b128 v[170:173], v159 offset:3072
	s_waitcnt lgkmcnt(0)
	v_add_u32_e32 v159, s9, v137
	v_mfma_f32_16x16x32_bf16 v[124:127], v[138:141], v[154:157], v[124:127]
	v_readfirstlane_b32 s9, v159
	s_mov_b32 m0, s9
	s_mov_b64 s[14:15], 0x3b8000c0
	v_mfma_f32_16x16x32_bf16 v[120:123], v[138:141], v[162:165], v[120:123]
	v_mfma_f32_16x16x32_bf16 v[116:119], v[138:141], v[166:169], v[116:119]
	v_mfma_f32_16x16x32_bf16 v[108:111], v[138:141], v[170:173], v[108:111]
	v_lshl_add_u64 v[138:139], v[130:131], 0, s[6:7]
	v_lshl_add_u64 v[140:141], v[138:139], 0, s[28:29]
	v_lshl_add_u64 v[138:139], v[138:139], 0, s[20:21]
	v_mfma_f32_16x16x32_bf16 v[104:107], v[142:145], v[154:157], v[104:107]
	global_load_lds_dwordx4 v[140:141], off
	v_mfma_f32_16x16x32_bf16 v[100:103], v[142:145], v[162:165], v[100:103]
	v_mfma_f32_16x16x32_bf16 v[96:99], v[142:145], v[166:169], v[96:99]
	v_mfma_f32_16x16x32_bf16 v[92:95], v[142:145], v[170:173], v[92:95]
	v_add_u32_e32 v142, 0x2000, v159
	s_nop 0
	v_readfirstlane_b32 s13, v142
	s_mov_b32 m0, s13
	v_mfma_f32_16x16x32_bf16 v[88:91], v[146:149], v[154:157], v[88:91]
	global_load_lds_dwordx4 v[138:139], off
	v_mfma_f32_16x16x32_bf16 v[84:87], v[146:149], v[162:165], v[84:87]
	v_mfma_f32_16x16x32_bf16 v[80:83], v[146:149], v[166:169], v[80:83]
	v_mfma_f32_16x16x32_bf16 v[76:79], v[146:149], v[170:173], v[76:79]
	v_mfma_f32_16x16x32_bf16 v[72:75], v[150:153], v[154:157], v[72:75]
	v_mfma_f32_16x16x32_bf16 v[68:71], v[150:153], v[162:165], v[68:71]
	v_mfma_f32_16x16x32_bf16 v[64:67], v[150:153], v[166:169], v[64:67]
	v_mfma_f32_16x16x32_bf16 v[60:63], v[150:153], v[170:173], v[60:63]
	ds_read_b128 v[138:141], v158 offset:4096
	ds_read_b128 v[142:145], v158 offset:5120
	ds_read_b128 v[146:149], v158 offset:6144
	ds_read_b128 v[150:153], v158 offset:7168
	s_waitcnt lgkmcnt(0)
	s_nop 0
	v_mfma_f32_16x16x32_bf16 v[44:47], v[142:145], v[154:157], v[44:47]
	v_mfma_f32_16x16x32_bf16 v[40:43], v[142:145], v[162:165], v[40:43]
	v_mfma_f32_16x16x32_bf16 v[36:39], v[142:145], v[166:169], v[36:39]
	v_mfma_f32_16x16x32_bf16 v[32:35], v[142:145], v[170:173], v[32:35]
	v_add_u32_e32 v142, 0x4000, v159
	v_add_u32_e32 v143, 0x6000, v159
	v_readfirstlane_b32 s9, v142
	v_mfma_f32_16x16x32_bf16 v[112:115], v[138:141], v[154:157], v[112:115]
	v_readfirstlane_b32 s13, v143
	s_mov_b32 m0, s9
	v_mfma_f32_16x16x32_bf16 v[56:59], v[138:141], v[162:165], v[56:59]
	v_mfma_f32_16x16x32_bf16 v[52:55], v[138:141], v[166:169], v[52:55]
	v_mfma_f32_16x16x32_bf16 v[48:51], v[138:141], v[170:173], v[48:51]
	v_lshl_add_u64 v[138:139], v[128:129], 0, s[6:7]
	v_lshl_add_u64 v[140:141], v[138:139], 0, s[14:15]
	s_mov_b64 s[14:15], 0x3b8400c0
	v_lshl_add_u64 v[138:139], v[138:139], 0, s[14:15]
	global_load_lds_dwordx4 v[140:141], off
	s_mov_b32 m0, s13
	v_mfma_f32_16x16x32_bf16 v[28:31], v[146:149], v[154:157], v[28:31]
	global_load_lds_dwordx4 v[138:139], off
	s_add_u32 s6, s6, 64
	v_mfma_f32_16x16x32_bf16 v[24:27], v[146:149], v[162:165], v[24:27]
	s_addc_u32 s7, s7, 0
	s_add_i32 s8, s8, 0x8000
	s_cmpk_eq_i32 s6, 0x740
	v_mfma_f32_16x16x32_bf16 v[20:23], v[146:149], v[166:169], v[20:23]
	v_mfma_f32_16x16x32_bf16 v[16:19], v[146:149], v[170:173], v[16:19]
	v_mfma_f32_16x16x32_bf16 v[12:15], v[150:153], v[154:157], v[12:15]
	v_mfma_f32_16x16x32_bf16 v[8:11], v[150:153], v[162:165], v[8:11]
	v_mfma_f32_16x16x32_bf16 v[4:7], v[150:153], v[166:169], v[4:7]
	v_mfma_f32_16x16x32_bf16 v[0:3], v[150:153], v[170:173], v[0:3]
	s_cbranch_scc0 .LBB0_219
; #define ROW4(accv, r, av)                                                                              \
;     accv[r][0] = MFMA16(av, b0, accv[r][0]); accv[r][1] = MFMA16(av, b1, accv[r][1]);                      \
;     accv[r][2] = MFMA16(av, b2, accv[r][2]); accv[r][3] = MFMA16(av, b3, accv[r][3]);
; template <int EPI>
; __device__ __forceinline__ void gemm_tile_dma(const bft* __restrict__ A, int lda, const bft* __restrict__ Bt, int K, int row0, int col0,
;                                               char* smem, const EpiArgs& e) {
;     ...
;   for (int kt = 0; kt < nk; ++kt) {
;     if (kt + 2 < nk) asm volatile("s_waitcnt vmcnt(8)" ::: "memory");
;     else if (kt + 1 < nk) asm volatile("s_waitcnt vmcnt(4)" ::: "memory");
;     else asm volatile("s_waitcnt vmcnt(0)" ::: "memory");
;     __builtin_amdgcn_s_barrier();
;     asm volatile("" ::: "memory");
;     const bool pf = kt + 3 < nk;
;     const unsigned so = (unsigned)(kt & 3) * GST;
;     bf16x8 a0, a1, a2, a3, b0, b1, b2, b3;
;     asm volatile(
;         "ds_read_b128 %0, %8\n\t"
;         "ds_read_b128 %1, %8 offset:1024\n\t"
;         "ds_read_b128 %2, %8 offset:2048\n\t"
;         "ds_read_b128 %3, %8 offset:3072\n\t"
;         "ds_read_b128 %4, %9\n\t"
;         "ds_read_b128 %5, %9 offset:1024\n\t"
;         "ds_read_b128 %6, %9 offset:2048\n\t"
;         "ds_read_b128 %7, %9 offset:3072\n\t"
;         "s_waitcnt lgkmcnt(0)"
;         : "=&v"(a0), "=&v"(a1), "=&v"(a2), "=&v"(a3), "=&v"(b0), "=&v"(b1), "=&v"(b2), "=&v"(b3)
;         : "v"(lds_a + so), "v"(lds_b + so)
;         : "memory");
;     ...
;     ROW4(accL, 0, a0) ROW4(accL, 1, a1)
;     if (pf) GEMM_DMA_A(kt + 3)
;     ROW4(accL, 2, a2) ROW4(accL, 3, a3)
;     asm volatile(
;         "ds_read_b128 %0, %4 offset:4096\n\t"
;         "ds_read_b128 %1, %4 offset:5120\n\t"
;         "ds_read_b128 %2, %4 offset:6144\n\t"
;         "ds_read_b128 %3, %4 offset:7168\n\t"
;         "s_waitcnt lgkmcnt(0)"
;         : "=&v"(a0), "=&v"(a1), "=&v"(a2), "=&v"(a3)
;         : "v"(lds_a + so)
;         : "memory");
;     ROW4(accH, 0, a0) ROW4(accH, 1, a1)
;     if (pf) GEMM_DMA_B(kt + 3)
;     ROW4(accH, 2, a2) ROW4(accH, 3, a3)
;     ...
;   }
	s_setprio 0
	s_waitcnt vmcnt(8)
	s_barrier
	v_add_u32_e32 v137, 0x8000, v134
	v_or_b32_e32 v158, 0x8000, v136
	ds_read_b128 v[128:131], v137
	ds_read_b128 v[138:141], v137 offset:1024
	ds_read_b128 v[142:145], v137 offset:2048
	ds_read_b128 v[146:149], v137 offset:3072
	ds_read_b128 v[150:153], v158
	ds_read_b128 v[154:157], v158 offset:1024
	ds_read_b128 v[162:165], v158 offset:2048
	ds_read_b128 v[166:169], v158 offset:3072
	s_waitcnt lgkmcnt(0)
	v_or_b32_e32 v158, 0x10000, v136
	v_mfma_f32_16x16x32_bf16 v[124:127], v[128:131], v[150:153], v[124:127]
	v_or_b32_e32 v160, 0x18000, v136
	s_movk_i32 s6, 0x4400
	v_mfma_f32_16x16x32_bf16 v[120:123], v[128:131], v[154:157], v[120:123]
	v_mfma_f32_16x16x32_bf16 v[116:119], v[128:131], v[162:165], v[116:119]
	v_mfma_f32_16x16x32_bf16 v[108:111], v[128:131], v[166:169], v[108:111]
	v_mfma_f32_16x16x32_bf16 v[104:107], v[138:141], v[150:153], v[104:107]
	v_mfma_f32_16x16x32_bf16 v[100:103], v[138:141], v[154:157], v[100:103]
	v_mfma_f32_16x16x32_bf16 v[96:99], v[138:141], v[162:165], v[96:99]
	v_mfma_f32_16x16x32_bf16 v[92:95], v[138:141], v[166:169], v[92:95]
	v_mfma_f32_16x16x32_bf16 v[88:91], v[142:145], v[150:153], v[88:91]
	v_mfma_f32_16x16x32_bf16 v[84:87], v[142:145], v[154:157], v[84:87]
	v_mfma_f32_16x16x32_bf16 v[80:83], v[142:145], v[162:165], v[80:83]
	v_mfma_f32_16x16x32_bf16 v[76:79], v[142:145], v[166:169], v[76:79]
	v_mfma_f32_16x16x32_bf16 v[72:75], v[146:149], v[150:153], v[72:75]
	v_mfma_f32_16x16x32_bf16 v[68:71], v[146:149], v[154:157], v[68:71]
	v_mfma_f32_16x16x32_bf16 v[64:67], v[146:149], v[162:165], v[64:67]
	v_mfma_f32_16x16x32_bf16 v[60:63], v[146:149], v[166:169], v[60:63]
	ds_read_b128 v[128:131], v137 offset:4096
	ds_read_b128 v[138:141], v137 offset:5120
	ds_read_b128 v[142:145], v137 offset:6144
	ds_read_b128 v[146:149], v137 offset:7168
	s_waitcnt lgkmcnt(0)
	s_waitcnt vmcnt(4)
	s_barrier
	v_mfma_f32_16x16x32_bf16 v[112:115], v[128:131], v[150:153], v[112:115]
	v_add_u32_e32 v137, 0x10000, v134
	v_add_u32_e32 v134, 0x18000, v134
	v_mfma_f32_16x16x32_bf16 v[56:59], v[128:131], v[154:157], v[56:59]
	v_mfma_f32_16x16x32_bf16 v[52:55], v[128:131], v[162:165], v[52:55]
	v_mfma_f32_16x16x32_bf16 v[48:51], v[128:131], v[166:169], v[48:51]
	v_mfma_f32_16x16x32_bf16 v[44:47], v[138:141], v[150:153], v[44:47]
	v_mfma_f32_16x16x32_bf16 v[40:43], v[138:141], v[154:157], v[40:43]
	v_mfma_f32_16x16x32_bf16 v[36:39], v[138:141], v[162:165], v[36:39]
	v_mfma_f32_16x16x32_bf16 v[32:35], v[138:141], v[166:169], v[32:35]
	v_mfma_f32_16x16x32_bf16 v[28:31], v[142:145], v[150:153], v[28:31]
	v_mfma_f32_16x16x32_bf16 v[24:27], v[142:145], v[154:157], v[24:27]
	v_mfma_f32_16x16x32_bf16 v[20:23], v[142:145], v[162:165], v[20:23]
	v_mfma_f32_16x16x32_bf16 v[16:19], v[142:145], v[166:169], v[16:19]
	v_mfma_f32_16x16x32_bf16 v[12:15], v[146:149], v[150:153], v[12:15]
	v_mfma_f32_16x16x32_bf16 v[8:11], v[146:149], v[154:157], v[8:11]
	v_mfma_f32_16x16x32_bf16 v[4:7], v[146:149], v[162:165], v[4:7]
	v_mfma_f32_16x16x32_bf16 v[0:3], v[146:149], v[166:169], v[0:3]
	ds_read_b128 v[128:131], v137
	ds_read_b128 v[138:141], v137 offset:1024
	ds_read_b128 v[142:145], v137 offset:2048
	ds_read_b128 v[146:149], v137 offset:3072
	ds_read_b128 v[150:153], v158
	ds_read_b128 v[154:157], v158 offset:1024
	ds_read_b128 v[162:165], v158 offset:2048
	ds_read_b128 v[166:169], v158 offset:3072
	s_waitcnt lgkmcnt(0)
	s_nop 0
	v_mfma_f32_16x16x32_bf16 v[124:127], v[128:131], v[150:153], v[124:127]
	v_mfma_f32_16x16x32_bf16 v[120:123], v[128:131], v[154:157], v[120:123]
	v_mfma_f32_16x16x32_bf16 v[116:119], v[128:131], v[162:165], v[116:119]
	v_mfma_f32_16x16x32_bf16 v[108:111], v[128:131], v[166:169], v[108:111]
	v_mfma_f32_16x16x32_bf16 v[104:107], v[138:141], v[150:153], v[104:107]
	v_mfma_f32_16x16x32_bf16 v[100:103], v[138:141], v[154:157], v[100:103]
	v_mfma_f32_16x16x32_bf16 v[96:99], v[138:141], v[162:165], v[96:99]
	v_mfma_f32_16x16x32_bf16 v[92:95], v[138:141], v[166:169], v[92:95]
	v_mfma_f32_16x16x32_bf16 v[88:91], v[142:145], v[150:153], v[88:91]
	v_mfma_f32_16x16x32_bf16 v[84:87], v[142:145], v[154:157], v[84:87]
	v_mfma_f32_16x16x32_bf16 v[80:83], v[142:145], v[162:165], v[80:83]
	v_mfma_f32_16x16x32_bf16 v[76:79], v[142:145], v[166:169], v[76:79]
	v_mfma_f32_16x16x32_bf16 v[72:75], v[146:149], v[150:153], v[72:75]
	v_mfma_f32_16x16x32_bf16 v[68:71], v[146:149], v[154:157], v[68:71]
	v_mfma_f32_16x16x32_bf16 v[64:67], v[146:149], v[162:165], v[64:67]
	v_mfma_f32_16x16x32_bf16 v[60:63], v[146:149], v[166:169], v[60:63]
	ds_read_b128 v[128:131], v137 offset:4096
	ds_read_b128 v[138:141], v137 offset:5120
	ds_read_b128 v[142:145], v137 offset:6144
	ds_read_b128 v[146:149], v137 offset:7168
	s_waitcnt lgkmcnt(0)
	s_waitcnt vmcnt(0)
	s_barrier
; #define ROW4(accv, r, av)                                                                              \
;     accv[r][0] = MFMA16(av, b0, accv[r][0]); accv[r][1] = MFMA16(av, b1, accv[r][1]);                      \
;     accv[r][2] = MFMA16(av, b2, accv[r][2]); accv[r][3] = MFMA16(av, b3, accv[r][3]);
; template <int EPI>
; DI void epilogue_tile(const EpiArgs& e, int row0, int wrow, int wcol, f32x4 (&acc)[4][4], char* smem, const float* rsm, int wave, int lane,
;                       bool final_sync = true) {
;     ...
;       if (transposed) {
;         *(f32x4*)(stage + lcol * STG + lrow) = (f32x4){v[0], v[1], v[2], v[3]};
;       } else {
; #pragma unroll
;         for (int j = 0; j < 4; ++j) stage[(lrow + j) * STG + lcol] = v[j];
; template <int EPI>
; __device__ __forceinline__ void gemm_tile_dma(const bft* __restrict__ A, int lda, const bft* __restrict__ Bt, int K, int row0, int col0,
;                                               char* smem, const EpiArgs& e) {
;     ...
;     ROW4(accL, 0, a0) ROW4(accL, 1, a1)
;     if (pf) GEMM_DMA_A(kt + 3)
;     ROW4(accL, 2, a2) ROW4(accL, 3, a3)
;     asm volatile(
;         "ds_read_b128 %0, %4 offset:4096\n\t"
;         "ds_read_b128 %1, %4 offset:5120\n\t"
;         "ds_read_b128 %2, %4 offset:6144\n\t"
;         "ds_read_b128 %3, %4 offset:7168\n\t"
;         "s_waitcnt lgkmcnt(0)"
;         : "=&v"(a0), "=&v"(a1), "=&v"(a2), "=&v"(a3)
;         : "v"(lds_a + so)
;         : "memory");
;     ROW4(accH, 0, a0) ROW4(accH, 1, a1)
;     if (pf) GEMM_DMA_B(kt + 3)
;     ROW4(accH, 2, a2) ROW4(accH, 3, a3)
;     ...
;   }
;     ...
;   __syncthreads();
;   epilogue_tile<EPI>(e, row0, row0 + wm * 128, col0 + wn * 64, accL, smem, nullptr, wave, lane, false);
	v_mfma_f32_16x16x32_bf16 v[170:173], v[128:131], v[150:153], v[112:115]
	v_mfma_f32_16x16x32_bf16 v[56:59], v[128:131], v[154:157], v[56:59]
	v_mfma_f32_16x16x32_bf16 v[52:55], v[128:131], v[162:165], v[52:55]
	v_mfma_f32_16x16x32_bf16 v[48:51], v[128:131], v[166:169], v[48:51]
	v_mfma_f32_16x16x32_bf16 v[44:47], v[138:141], v[150:153], v[44:47]
	v_mfma_f32_16x16x32_bf16 v[40:43], v[138:141], v[154:157], v[40:43]
	v_mfma_f32_16x16x32_bf16 v[36:39], v[138:141], v[162:165], v[36:39]
	v_mfma_f32_16x16x32_bf16 v[32:35], v[138:141], v[166:169], v[32:35]
	v_mfma_f32_16x16x32_bf16 v[28:31], v[142:145], v[150:153], v[28:31]
	v_mfma_f32_16x16x32_bf16 v[24:27], v[142:145], v[154:157], v[24:27]
	v_mfma_f32_16x16x32_bf16 v[20:23], v[142:145], v[162:165], v[20:23]
	v_mfma_f32_16x16x32_bf16 v[16:19], v[142:145], v[166:169], v[16:19]
	v_mfma_f32_16x16x32_bf16 v[12:15], v[146:149], v[150:153], v[12:15]
	v_mfma_f32_16x16x32_bf16 v[8:11], v[146:149], v[154:157], v[8:11]
	v_mfma_f32_16x16x32_bf16 v[4:7], v[146:149], v[162:165], v[4:7]
	v_mfma_f32_16x16x32_bf16 v[0:3], v[146:149], v[166:169], v[0:3]
	ds_read_b128 v[112:115], v134
	ds_read_b128 v[128:131], v134 offset:1024
	ds_read_b128 v[136:139], v134 offset:2048
	ds_read_b128 v[140:143], v134 offset:3072
	ds_read_b128 v[144:147], v160
	ds_read_b128 v[148:151], v160 offset:1024
	ds_read_b128 v[152:155], v160 offset:2048
	ds_read_b128 v[156:159], v160 offset:3072
	s_waitcnt lgkmcnt(0)
	s_nop 0
	v_mfma_f32_16x16x32_bf16 v[124:127], v[112:115], v[144:147], v[124:127]
	v_mfma_f32_16x16x32_bf16 v[120:123], v[112:115], v[148:151], v[120:123]
	v_mfma_f32_16x16x32_bf16 v[116:119], v[112:115], v[152:155], v[116:119]
	v_mfma_f32_16x16x32_bf16 v[112:115], v[112:115], v[156:159], v[108:111]
	v_mfma_f32_16x16x32_bf16 v[108:111], v[128:131], v[144:147], v[104:107]
	v_mfma_f32_16x16x32_bf16 v[104:107], v[128:131], v[148:151], v[100:103]
	v_mfma_f32_16x16x32_bf16 v[100:103], v[128:131], v[152:155], v[96:99]
	v_mfma_f32_16x16x32_bf16 v[96:99], v[128:131], v[156:159], v[92:95]
	v_mfma_f32_16x16x32_bf16 v[92:95], v[136:139], v[144:147], v[88:91]
	v_mfma_f32_16x16x32_bf16 v[88:91], v[136:139], v[148:151], v[84:87]
	v_mfma_f32_16x16x32_bf16 v[84:87], v[136:139], v[152:155], v[80:83]
	v_mfma_f32_16x16x32_bf16 v[80:83], v[136:139], v[156:159], v[76:79]
	v_mfma_f32_16x16x32_bf16 v[76:79], v[140:143], v[144:147], v[72:75]
	v_mfma_f32_16x16x32_bf16 v[72:75], v[140:143], v[148:151], v[68:71]
	v_mfma_f32_16x16x32_bf16 v[68:71], v[140:143], v[152:155], v[64:67]
	v_mfma_f32_16x16x32_bf16 v[64:67], v[140:143], v[156:159], v[60:63]
	ds_read_b128 v[128:131], v134 offset:4096
	ds_read_b128 v[136:139], v134 offset:5120
	ds_read_b128 v[140:143], v134 offset:6144
	ds_read_b128 v[162:165], v134 offset:7168
	s_waitcnt lgkmcnt(0)
	s_waitcnt vmcnt(0) lgkmcnt(0)
	s_barrier
	v_mfma_f32_16x16x32_bf16 v[60:63], v[128:131], v[144:147], v[170:173]
	v_mfma_f32_16x16x32_bf16 v[56:59], v[128:131], v[148:151], v[56:59]
	v_mfma_f32_16x16x32_bf16 v[52:55], v[128:131], v[152:155], v[52:55]
	v_mfma_f32_16x16x32_bf16 v[48:51], v[128:131], v[156:159], v[48:51]
	v_lshrrev_b32_e32 v129, 6, v133
	v_mfma_f32_16x16x32_bf16 v[44:47], v[136:139], v[144:147], v[44:47]
	v_mfma_f32_16x16x32_bf16 v[40:43], v[136:139], v[148:151], v[40:43]
	v_mfma_f32_16x16x32_bf16 v[36:39], v[136:139], v[152:155], v[36:39]
	v_mfma_f32_16x16x32_bf16 v[32:35], v[136:139], v[156:159], v[32:35]
	v_and_b32_e32 v137, 0xc0, v133
	v_mul_lo_u32 v136, v129, s6
	v_bfe_u32 v129, v133, 2, 4
	v_mfma_f32_16x16x32_bf16 v[28:31], v[140:143], v[144:147], v[28:31]
	v_or_b32_e32 v128, s12, v137
	s_movk_i32 s6, 0x500
	v_and_b32_e32 v139, 12, v129
	v_mfma_f32_16x16x32_bf16 v[24:27], v[140:143], v[148:151], v[24:27]
	v_lshl_add_u32 v138, v135, 2, v136
	v_cmp_gt_i32_e64 s[6:7], s6, v128
	v_mad_u32_u24 v130, v139, s35, v138
	v_mfma_f32_16x16x32_bf16 v[20:23], v[140:143], v[152:155], v[20:23]
	v_mfma_f32_16x16x32_bf16 v[16:19], v[140:143], v[156:159], v[16:19]
	v_or_b32_e32 v140, 3, v129
	v_mad_u32_u24 v134, v140, s35, v138
	v_mfma_f32_16x16x32_bf16 v[12:15], v[162:165], v[144:147], v[12:15]
	v_mfma_f32_16x16x32_bf16 v[8:11], v[162:165], v[148:151], v[8:11]
	v_mfma_f32_16x16x32_bf16 v[4:7], v[162:165], v[152:155], v[4:7]
	v_mfma_f32_16x16x32_bf16 v[0:3], v[162:165], v[156:159], v[0:3]
	s_and_saveexec_b64 s[8:9], s[6:7]
	s_xor_b64 s[8:9], exec, s[8:9]
	s_cbranch_execz .LBB0_222
	ds_write2_b32 v130, v124, v125 offset1:68
	ds_write_b32 v130, v126 offset:544
	ds_write_b32 v134, v127

; DI int otid() { int t = threadIdx.x; asm volatile("" : "+v"(t)); return t; }
; #define GEMM_DMA(kt) { GEMM_DMA_A(kt) GEMM_DMA_B(kt) }
; template <int EPI>
; __device__ __forceinline__ void gemm_tile_dma(const bft* __restrict__ A, int lda, const bft* __restrict__ Bt, int K, int row0, int col0,
;                                               char* smem, const EpiArgs& e) {
;   const int tid = otid(), wave = tid >> 6, lane = tid & 63;
;   const int wm = wave >> 2, wn = wave & 3, r16 = lane & 15, g = lane >> 4;
;   f32x4 accL[4][4], accH[4][4];
; #pragma unroll
;   for (int i = 0; i < 4; ++i)
; #pragma unroll
;     for (int j = 0; j < 4; ++j) { accL[i][j] = (f32x4){0.f, 0.f, 0.f, 0.f}; accH[i][j] = (f32x4){0.f, 0.f, 0.f, 0.f}; }
;   const int lr = tid >> 2, pc = tid & 3;
;   const int kcs = (pc ^ ((4 - ((lr >> 2) & 3)) & 3)) * 8;
;   const int rco = (g ^ ((4 - ((r16 >> 2) & 3)) & 3)) * 8;
;   const bft* ag = A + (size_t)(row0 + lr) * lda + kcs;
;   const bft* bg = Bt + (size_t)(col0 + lr) * K + kcs;
;   const unsigned lds_a = (unsigned)(size_t)smem + (unsigned)(((wm * 128 + r16) * 32 + rco) * 2);
;   const unsigned lds_b = (unsigned)(size_t)smem + 16384u + (unsigned)(((wn * 64 + r16) * 32 + rco) * 2);
;   const int nk = K / 32;
;     ...
;   GEMM_DMA(0);
;   GEMM_DMA(1);
;   GEMM_DMA(2);
; template <int EPI, bool RMS>
; __device__ __forceinline__ void gemm_phase(const bft* A, int lda, const bft* Bt, int K, int ntn, char* smem, const EpiArgs& e) {
;   const int G8 = gridDim.x >> 3, xcd = blockIdx.x & 7, loc = blockIdx.x >> 3;
;   constexpr int RT = 34;
;   const int per = RT * ntn;
;   for (int idx = loc; idx < per; idx += G8) {
;     const int grp = idx / (8 * ntn);
;     const int within = idx - grp * (8 * ntn);
;     const int rig = (grp < RT / 8) ? 8 : RT % 8;
;     const int tm = xcd * RT + grp * 8 + within % rig, tn = within / rig;
;     if constexpr (RMS) gemm_tile<EPI, RMS>(A, lda, Bt, K, tm * 256, tn * 128, smem, e);
;     else gemm_tile_dma<EPI>(A, lda, Bt, K, tm * 256, tn * 256, smem, e);
.LBB0_1286:
	s_lshr_b32 s15, s16, 2
	s_and_b32 s14, s16, 31
	s_and_b32 s15, s15, 56
	s_cmpk_lt_u32 s16, 0x80
	s_cselect_b32 s17, 7, 1
	s_cselect_b32 s34, 3, 1
	s_and_b32 s17, s17, s16
	s_add_i32 s27, s3, s17
	s_add_i32 s27, s27, s15
	v_mov_b32_e32 v188, v196
	s_lshl_b32 s17, s27, 8
	s_lshr_b32 s14, s14, s34
	v_ashrrev_i32_e32 v4, 2, v188
	v_lshrrev_b32_e32 v0, 4, v188
	v_sub_u32_e32 v10, 0, v0
	v_add_u32_e32 v0, s17, v4
	v_xor_b32_e32 v5, v188, v10
	v_ashrrev_i32_e32 v1, 31, v0
	v_lshlrev_b64 v[0:1], 11, v[0:1]
	v_lshlrev_b32_e32 v5, 4, v5
	v_lshlrev_b32_e32 v190, 4, v188
	s_lshl_b32 s34, s14, 8
	v_lshl_add_u64 v[2:3], s[62:63], 0, v[0:1]
	v_and_b32_e32 v160, 48, v5
	v_readfirstlane_b32 s14, v190
	v_add_u32_e32 v11, 0x2000, v190
	v_lshl_add_u64 v[2:3], v[2:3], 0, v[160:161]
	v_add_u32_e32 v4, s34, v4
	v_ashrrev_i32_e32 v8, 1, v188
	s_mov_b32 m0, s14
	s_mov_b64 s[40:41], 0x40000
	v_readfirstlane_b32 s14, v11
	v_ashrrev_i32_e32 v5, 31, v4
	v_and_b32_e32 v189, 0xffffff80, v8
	global_load_lds_dwordx4 v[2:3], off
	v_lshl_add_u64 v[8:9], v[2:3], 0, s[40:41]
	s_mov_b32 m0, s14
	v_lshlrev_b64 v[4:5], 11, v[4:5]
	global_load_lds_dwordx4 v[8:9], off
	v_add_u32_e32 v8, 0x4000, v190
	v_lshl_add_u64 v[6:7], s[24:25], 0, v[4:5]
	v_readfirstlane_b32 s14, v8
	v_add_u32_e32 v11, 0x6000, v190
	v_lshl_add_u64 v[6:7], v[6:7], 0, v[160:161]
	s_mov_b32 m0, s14
	v_readfirstlane_b32 s14, v11
	v_add_u32_e32 v11, 0x8000, v190
	global_load_lds_dwordx4 v[6:7], off
	v_lshl_add_u64 v[8:9], v[6:7], 0, s[40:41]
	s_mov_b32 m0, s14
	v_readfirstlane_b32 s14, v11
	v_add_u32_e32 v11, 0xa000, v190
	global_load_lds_dwordx4 v[8:9], off
	v_lshl_add_u64 v[8:9], v[2:3], 0, 64
	s_mov_b32 m0, s14
	s_mov_b64 s[40:41], 0x40040
	v_readfirstlane_b32 s14, v11
	v_add_u32_e32 v11, 0xc000, v190
	global_load_lds_dwordx4 v[8:9], off
	v_lshl_add_u64 v[8:9], v[2:3], 0, s[40:41]
	s_mov_b32 m0, s14
	v_readfirstlane_b32 s14, v11
	v_add_u32_e32 v11, 0xe000, v190
	global_load_lds_dwordx4 v[8:9], off
	v_lshl_add_u64 v[8:9], v[6:7], 0, 64
	s_mov_b32 m0, s14
	v_readfirstlane_b32 s14, v11
	v_add_u32_e32 v11, 0x10000, v190
	global_load_lds_dwordx4 v[8:9], off
	v_lshl_add_u64 v[8:9], v[6:7], 0, s[40:41]
	s_mov_b32 m0, s14
	s_mov_b64 s[40:41], 0x80
	v_readfirstlane_b32 s14, v11
	global_load_lds_dwordx4 v[8:9], off
	v_lshl_add_u64 v[8:9], v[2:3], 0, s[40:41]
	s_mov_b32 m0, s14
	s_mov_b64 s[44:45], 0x40080
	global_load_lds_dwordx4 v[8:9], off
	v_add_u32_e32 v8, 0x12000, v190
	v_lshl_add_u64 v[2:3], v[2:3], 0, s[44:45]
	v_readfirstlane_b32 s14, v8
	v_add_u32_e32 v8, 0x14000, v190
	s_mov_b32 m0, s14
	v_readfirstlane_b32 s14, v8
	global_load_lds_dwordx4 v[2:3], off
	v_lshl_add_u64 v[2:3], v[6:7], 0, s[40:41]
	s_mov_b32 m0, s14
	v_and_b32_e32 v182, 15, v188
	global_load_lds_dwordx4 v[2:3], off
	v_lshl_add_u64 v[2:3], v[6:7], 0, s[44:45]
	v_add_u32_e32 v6, 0x16000, v190
	s_waitcnt vmcnt(0)
	v_mov_b32_e32 v28, 0
	v_readfirstlane_b32 s14, v6
	s_mov_b32 m0, s14
	v_lshlrev_b32_e32 v6, 6, v188
	global_load_lds_dwordx4 v[2:3], off
	v_lshlrev_b32_e32 v2, 2, v188
	v_and_b32_e32 v2, 48, v2
	v_sub_u32_e32 v2, 0, v2
	v_bitop3_b32 v2, v188, 48, v2 bitop3:0x48
	v_or_b32_e32 v3, v189, v182
	v_and_b32_e32 v6, 0x33c0, v6
	v_lshl_or_b32 v133, v3, 6, v2
	v_or3_b32 v132, v6, v2, s42
	v_bitop3_b32 v2, v188, 3, v10 bitop3:0x48
	v_lshlrev_b32_e32 v2, 4, v2
	v_or_b32_e32 v4, v4, v2
	v_or_b32_e32 v0, v0, v2
	s_mov_b32 s38, 0
	v_lshl_add_u64 v[128:129], s[90:91], 0, v[4:5]
	v_lshl_add_u64 v[130:131], s[90:91], 0, v[0:1]
	s_mov_b64 s[14:15], 0
	v_mov_b32_e32 v29, v28
	v_mov_b32_e32 v30, v28
	v_mov_b32_e32 v31, v28
	v_mov_b32_e32 v32, v28
	v_mov_b32_e32 v33, v28
	v_mov_b32_e32 v34, v28
	v_mov_b32_e32 v35, v28
	v_mov_b32_e32 v24, v28
	v_mov_b32_e32 v25, v28
	v_mov_b32_e32 v26, v28
	v_mov_b32_e32 v27, v28
	v_mov_b32_e32 v36, v28
	v_mov_b32_e32 v37, v28
	v_mov_b32_e32 v38, v28
	v_mov_b32_e32 v39, v28
	v_mov_b32_e32 v20, v28
	v_mov_b32_e32 v21, v28
	v_mov_b32_e32 v22, v28
	v_mov_b32_e32 v23, v28
	v_mov_b32_e32 v40, v28
	v_mov_b32_e32 v41, v28
	v_mov_b32_e32 v42, v28
	v_mov_b32_e32 v43, v28
	v_mov_b32_e32 v16, v28
	v_mov_b32_e32 v17, v28
	v_mov_b32_e32 v18, v28
	v_mov_b32_e32 v19, v28
	v_mov_b32_e32 v44, v28
	v_mov_b32_e32 v45, v28
	v_mov_b32_e32 v46, v28
	v_mov_b32_e32 v47, v28
	v_mov_b32_e32 v12, v28
	v_mov_b32_e32 v13, v28
	v_mov_b32_e32 v14, v28
	v_mov_b32_e32 v15, v28
	v_mov_b32_e32 v48, v28
	v_mov_b32_e32 v49, v28
	v_mov_b32_e32 v50, v28
	v_mov_b32_e32 v51, v28
	v_mov_b32_e32 v8, v28
	v_mov_b32_e32 v9, v28
	v_mov_b32_e32 v10, v28
	v_mov_b32_e32 v11, v28
	v_mov_b32_e32 v52, v28
	v_mov_b32_e32 v53, v28
	v_mov_b32_e32 v54, v28
	v_mov_b32_e32 v55, v28
	v_mov_b32_e32 v4, v28
	v_mov_b32_e32 v5, v28
	v_mov_b32_e32 v6, v28
	v_mov_b32_e32 v7, v28
	v_mov_b32_e32 v56, v28
	v_mov_b32_e32 v57, v28
	v_mov_b32_e32 v58, v28
	v_mov_b32_e32 v59, v28
	v_mov_b32_e32 v0, v28
	v_mov_b32_e32 v1, v28
	v_mov_b32_e32 v2, v28
	v_mov_b32_e32 v3, v28
	v_mov_b32_e32 v60, v28
	v_mov_b32_e32 v61, v28
	v_mov_b32_e32 v62, v28
	v_mov_b32_e32 v63, v28
	v_mov_b32_e32 v64, v28
	v_mov_b32_e32 v65, v28
	v_mov_b32_e32 v66, v28
	v_mov_b32_e32 v67, v28
	v_mov_b32_e32 v68, v28
	v_mov_b32_e32 v69, v28
	v_mov_b32_e32 v70, v28
	v_mov_b32_e32 v71, v28
	v_mov_b32_e32 v72, v28
	v_mov_b32_e32 v73, v28
	v_mov_b32_e32 v74, v28
	v_mov_b32_e32 v75, v28
	v_mov_b32_e32 v76, v28
	v_mov_b32_e32 v77, v28
	v_mov_b32_e32 v78, v28
	v_mov_b32_e32 v79, v28
	v_mov_b32_e32 v80, v28
	v_mov_b32_e32 v81, v28
	v_mov_b32_e32 v82, v28
	v_mov_b32_e32 v83, v28
	v_mov_b32_e32 v84, v28
	v_mov_b32_e32 v85, v28
	v_mov_b32_e32 v86, v28
	v_mov_b32_e32 v87, v28
	v_mov_b32_e32 v88, v28
	v_mov_b32_e32 v89, v28
	v_mov_b32_e32 v90, v28
	v_mov_b32_e32 v91, v28
	v_mov_b32_e32 v92, v28
	v_mov_b32_e32 v93, v28
	v_mov_b32_e32 v94, v28
	v_mov_b32_e32 v95, v28
	v_mov_b32_e32 v96, v28
	v_mov_b32_e32 v97, v28
	v_mov_b32_e32 v98, v28
	v_mov_b32_e32 v99, v28
	v_mov_b32_e32 v100, v28
	v_mov_b32_e32 v101, v28
	v_mov_b32_e32 v102, v28
	v_mov_b32_e32 v103, v28
	v_mov_b32_e32 v104, v28
	v_mov_b32_e32 v105, v28
	v_mov_b32_e32 v106, v28
	v_mov_b32_e32 v107, v28
	v_mov_b32_e32 v108, v28
	v_mov_b32_e32 v109, v28
	v_mov_b32_e32 v110, v28
	v_mov_b32_e32 v111, v28
	v_mov_b32_e32 v116, v28
	v_mov_b32_e32 v117, v28
	v_mov_b32_e32 v118, v28
	v_mov_b32_e32 v119, v28
	v_mov_b32_e32 v120, v28
	v_mov_b32_e32 v121, v28
	v_mov_b32_e32 v122, v28
	v_mov_b32_e32 v123, v28
	v_mov_b32_e32 v124, v28
	v_mov_b32_e32 v125, v28
	v_mov_b32_e32 v126, v28
	v_mov_b32_e32 v127, v28
	v_mov_b32_e32 v112, v28
	v_mov_b32_e32 v113, v28
	v_mov_b32_e32 v114, v28
	v_mov_b32_e32 v115, v28
	s_getreg_b32 s32, hwreg(HW_REG_HW_ID, 0, 1)
	s_cmp_eq_u32 s32, 1
	s_cbranch_scc0 .Lgprio2_skip
	s_setprio 1
; #define ROW4(accv, r, av)                                                                              \
;     accv[r][0] = MFMA16(av, b0, accv[r][0]); accv[r][1] = MFMA16(av, b1, accv[r][1]);                      \
;     accv[r][2] = MFMA16(av, b2, accv[r][2]); accv[r][3] = MFMA16(av, b3, accv[r][3]);
; template <int EPI>
; __device__ __forceinline__ void gemm_tile_dma(const bft* __restrict__ A, int lda, const bft* __restrict__ Bt, int K, int row0, int col0,
;                                               char* smem, const EpiArgs& e) {
;     ...
;   for (int kt = 0; kt < nk; ++kt) {
;     if (kt + 2 < nk) asm volatile("s_waitcnt vmcnt(8)" ::: "memory");
;     else if (kt + 1 < nk) asm volatile("s_waitcnt vmcnt(4)" ::: "memory");
;     else asm volatile("s_waitcnt vmcnt(0)" ::: "memory");
;     __builtin_amdgcn_s_barrier();
;     asm volatile("" ::: "memory");
;     const bool pf = kt + 3 < nk;
;     const unsigned so = (unsigned)(kt & 3) * GST;
;     bf16x8 a0, a1, a2, a3, b0, b1, b2, b3;
;     asm volatile(
;         "ds_read_b128 %0, %8\n\t"
;         "ds_read_b128 %1, %8 offset:1024\n\t"
;         "ds_read_b128 %2, %8 offset:2048\n\t"
;         "ds_read_b128 %3, %8 offset:3072\n\t"
;         "ds_read_b128 %4, %9\n\t"
;         "ds_read_b128 %5, %9 offset:1024\n\t"
;         "ds_read_b128 %6, %9 offset:2048\n\t"
;         "ds_read_b128 %7, %9 offset:3072\n\t"
;         "s_waitcnt lgkmcnt(0)"
;         : "=&v"(a0), "=&v"(a1), "=&v"(a2), "=&v"(a3), "=&v"(b0), "=&v"(b1), "=&v"(b2), "=&v"(b3)
;         : "v"(lds_a + so), "v"(lds_b + so)
;         : "memory");
;     ...
;     ROW4(accL, 0, a0) ROW4(accL, 1, a1)
;     if (pf) GEMM_DMA_A(kt + 3)
;     ROW4(accL, 2, a2) ROW4(accL, 3, a3)
;     asm volatile(
;         "ds_read_b128 %0, %4 offset:4096\n\t"
;         "ds_read_b128 %1, %4 offset:5120\n\t"
;         "ds_read_b128 %2, %4 offset:6144\n\t"
;         "ds_read_b128 %3, %4 offset:7168\n\t"
;         "s_waitcnt lgkmcnt(0)"
;         : "=&v"(a0), "=&v"(a1), "=&v"(a2), "=&v"(a3)
;         : "v"(lds_a + so)
;         : "memory");
;     ROW4(accH, 0, a0) ROW4(accH, 1, a1)
;     if (pf) GEMM_DMA_B(kt + 3)
;     ROW4(accH, 2, a2) ROW4(accH, 3, a3)
;     ...
;   }
.Lgprio2_skip:
.LBB0_1287:
	s_and_b32 s39, s38, 0x18000
	v_add_u32_e32 v158, s39, v133
	v_or_b32_e32 v159, s39, v132
	s_add_i32 s39, s38, 0x18000
	s_waitcnt vmcnt(8)
	s_barrier
	s_and_b32 s39, s39, 0x18000
	ds_read_b128 v[134:137], v158
	ds_read_b128 v[138:141], v158 offset:1024
	ds_read_b128 v[142:145], v158 offset:2048
	ds_read_b128 v[146:149], v158 offset:3072
	ds_read_b128 v[150:153], v159
	ds_read_b128 v[154:157], v159 offset:1024
	ds_read_b128 v[162:165], v159 offset:2048
	ds_read_b128 v[166:169], v159 offset:3072
	s_waitcnt lgkmcnt(0)
	v_add_u32_e32 v159, s39, v190
	v_mfma_f32_16x16x32_bf16 v[124:127], v[134:137], v[150:153], v[124:127]
	v_readfirstlane_b32 s39, v159
	s_mov_b32 m0, s39
	v_mfma_f32_16x16x32_bf16 v[120:123], v[134:137], v[154:157], v[120:123]
	v_mfma_f32_16x16x32_bf16 v[116:119], v[134:137], v[162:165], v[116:119]
	v_mfma_f32_16x16x32_bf16 v[108:111], v[134:137], v[166:169], v[108:111]
	v_lshl_add_u64 v[134:135], v[130:131], 0, s[14:15]
	v_lshl_add_u64 v[136:137], v[134:135], 0, s[28:29]
	v_lshl_add_u64 v[134:135], v[134:135], 0, s[20:21]
	v_mfma_f32_16x16x32_bf16 v[104:107], v[138:141], v[150:153], v[104:107]
	global_load_lds_dwordx4 v[136:137], off
	v_mfma_f32_16x16x32_bf16 v[100:103], v[138:141], v[154:157], v[100:103]
	v_mfma_f32_16x16x32_bf16 v[96:99], v[138:141], v[162:165], v[96:99]
	v_mfma_f32_16x16x32_bf16 v[92:95], v[138:141], v[166:169], v[92:95]
	v_add_u32_e32 v138, 0x2000, v159
	s_nop 0
	v_readfirstlane_b32 s40, v138
	s_mov_b32 m0, s40
	v_mfma_f32_16x16x32_bf16 v[88:91], v[142:145], v[150:153], v[88:91]
	global_load_lds_dwordx4 v[134:135], off
	s_mov_b64 s[40:41], 0x3bd800c0
	v_mfma_f32_16x16x32_bf16 v[84:87], v[142:145], v[154:157], v[84:87]
	v_mfma_f32_16x16x32_bf16 v[80:83], v[142:145], v[162:165], v[80:83]
	v_mfma_f32_16x16x32_bf16 v[76:79], v[142:145], v[166:169], v[76:79]
	v_mfma_f32_16x16x32_bf16 v[72:75], v[146:149], v[150:153], v[72:75]
	v_mfma_f32_16x16x32_bf16 v[68:71], v[146:149], v[154:157], v[68:71]
	v_mfma_f32_16x16x32_bf16 v[64:67], v[146:149], v[162:165], v[64:67]
	v_mfma_f32_16x16x32_bf16 v[60:63], v[146:149], v[166:169], v[60:63]
	ds_read_b128 v[134:137], v158 offset:4096
	ds_read_b128 v[138:141], v158 offset:5120
	ds_read_b128 v[142:145], v158 offset:6144
	ds_read_b128 v[146:149], v158 offset:7168
	s_waitcnt lgkmcnt(0)
	s_nop 0
	v_mfma_f32_16x16x32_bf16 v[112:115], v[134:137], v[150:153], v[112:115]
	v_mfma_f32_16x16x32_bf16 v[0:3], v[134:137], v[154:157], v[0:3]
	v_mfma_f32_16x16x32_bf16 v[56:59], v[134:137], v[162:165], v[56:59]
	v_mfma_f32_16x16x32_bf16 v[4:7], v[134:137], v[166:169], v[4:7]
	v_lshl_add_u64 v[134:135], v[128:129], 0, s[14:15]
	v_lshl_add_u64 v[136:137], v[134:135], 0, s[40:41]
	s_mov_b64 s[40:41], 0x3bdc00c0
	v_mfma_f32_16x16x32_bf16 v[52:55], v[138:141], v[150:153], v[52:55]
	v_lshl_add_u64 v[134:135], v[134:135], 0, s[40:41]
	s_add_u32 s14, s14, 64
	s_addc_u32 s15, s15, 0
	v_mfma_f32_16x16x32_bf16 v[8:11], v[138:141], v[154:157], v[8:11]
	s_add_i32 s38, s38, 0x8000
	s_cmpk_eq_i32 s14, 0x740
	v_mfma_f32_16x16x32_bf16 v[48:51], v[138:141], v[162:165], v[48:51]
	v_mfma_f32_16x16x32_bf16 v[12:15], v[138:141], v[166:169], v[12:15]
	v_add_u32_e32 v138, 0x4000, v159
	v_add_u32_e32 v139, 0x6000, v159
	v_readfirstlane_b32 s39, v138
	v_readfirstlane_b32 s40, v139
	s_mov_b32 m0, s39
	v_mfma_f32_16x16x32_bf16 v[44:47], v[142:145], v[150:153], v[44:47]
	global_load_lds_dwordx4 v[136:137], off
	s_mov_b32 m0, s40
	v_mfma_f32_16x16x32_bf16 v[16:19], v[142:145], v[154:157], v[16:19]
	global_load_lds_dwordx4 v[134:135], off
	v_mfma_f32_16x16x32_bf16 v[40:43], v[142:145], v[162:165], v[40:43]
	v_mfma_f32_16x16x32_bf16 v[20:23], v[142:145], v[166:169], v[20:23]
	v_mfma_f32_16x16x32_bf16 v[36:39], v[146:149], v[150:153], v[36:39]
	v_mfma_f32_16x16x32_bf16 v[24:27], v[146:149], v[154:157], v[24:27]
	v_mfma_f32_16x16x32_bf16 v[32:35], v[146:149], v[162:165], v[32:35]
	v_mfma_f32_16x16x32_bf16 v[28:31], v[146:149], v[166:169], v[28:31]
	s_cbranch_scc0 .LBB0_1287
	s_setprio 0
	s_waitcnt vmcnt(8)
	s_barrier
	v_add_u32_e32 v158, 0x8000, v133
	v_or_b32_e32 v159, 0x8000, v132
	ds_read_b128 v[128:131], v158
	ds_read_b128 v[134:137], v158 offset:1024
	ds_read_b128 v[138:141], v158 offset:2048
	ds_read_b128 v[142:145], v158 offset:3072
	ds_read_b128 v[146:149], v159
	ds_read_b128 v[150:153], v159 offset:1024
	ds_read_b128 v[154:157], v159 offset:2048
	ds_read_b128 v[162:165], v159 offset:3072
	s_waitcnt lgkmcnt(0)
	v_or_b32_e32 v159, 0x10000, v132
	v_mfma_f32_16x16x32_bf16 v[124:127], v[128:131], v[146:149], v[124:127]
	v_add_u32_e32 v160, 0x18000, v133
	v_or_b32_e32 v132, 0x18000, v132
	s_movk_i32 s14, 0x4400
	v_mfma_f32_16x16x32_bf16 v[120:123], v[128:131], v[150:153], v[120:123]
	s_mul_i32 s15, s17, 0xf0f0f0f1
	v_and_b32_e32 v183, 63, v188
	v_or_b32_e32 v199, 48, v183
	v_mfma_f32_16x16x32_bf16 v[116:119], v[128:131], v[154:157], v[116:119]
	v_mfma_f32_16x16x32_bf16 v[108:111], v[128:131], v[162:165], v[108:111]
	v_mfma_f32_16x16x32_bf16 v[104:107], v[134:137], v[146:149], v[104:107]
	v_mfma_f32_16x16x32_bf16 v[100:103], v[134:137], v[150:153], v[100:103]
	v_mfma_f32_16x16x32_bf16 v[96:99], v[134:137], v[154:157], v[96:99]
	v_mfma_f32_16x16x32_bf16 v[92:95], v[134:137], v[162:165], v[92:95]
	v_mfma_f32_16x16x32_bf16 v[88:91], v[138:141], v[146:149], v[88:91]
	v_mfma_f32_16x16x32_bf16 v[84:87], v[138:141], v[150:153], v[84:87]
	v_mfma_f32_16x16x32_bf16 v[80:83], v[138:141], v[154:157], v[80:83]
	v_mfma_f32_16x16x32_bf16 v[76:79], v[138:141], v[162:165], v[76:79]
	v_mfma_f32_16x16x32_bf16 v[72:75], v[142:145], v[146:149], v[72:75]
	v_mfma_f32_16x16x32_bf16 v[68:71], v[142:145], v[150:153], v[68:71]
	v_mfma_f32_16x16x32_bf16 v[64:67], v[142:145], v[154:157], v[64:67]
	v_mfma_f32_16x16x32_bf16 v[60:63], v[142:145], v[162:165], v[60:63]
	ds_read_b128 v[128:131], v158 offset:4096
	ds_read_b128 v[134:137], v158 offset:5120
	ds_read_b128 v[138:141], v158 offset:6144
	ds_read_b128 v[142:145], v158 offset:7168
	s_waitcnt lgkmcnt(0)
	s_waitcnt vmcnt(4)
	s_barrier
; #define ROW4(accv, r, av)                                                                              \
;     accv[r][0] = MFMA16(av, b0, accv[r][0]); accv[r][1] = MFMA16(av, b1, accv[r][1]);                      \
;     accv[r][2] = MFMA16(av, b2, accv[r][2]); accv[r][3] = MFMA16(av, b3, accv[r][3]);
; template <int EPI>
; __device__ __forceinline__ void gemm_tile_dma(const bft* __restrict__ A, int lda, const bft* __restrict__ Bt, int K, int row0, int col0,
;                                               char* smem, const EpiArgs& e) {
;     ...
;   for (int kt = 0; kt < nk; ++kt) {
;     if (kt + 2 < nk) asm volatile("s_waitcnt vmcnt(8)" ::: "memory");
;     else if (kt + 1 < nk) asm volatile("s_waitcnt vmcnt(4)" ::: "memory");
;     else asm volatile("s_waitcnt vmcnt(0)" ::: "memory");
;     __builtin_amdgcn_s_barrier();
;     asm volatile("" ::: "memory");
;     const bool pf = kt + 3 < nk;
;     const unsigned so = (unsigned)(kt & 3) * GST;
;     bf16x8 a0, a1, a2, a3, b0, b1, b2, b3;
;     asm volatile(
;         "ds_read_b128 %0, %8\n\t"
;         "ds_read_b128 %1, %8 offset:1024\n\t"
;         "ds_read_b128 %2, %8 offset:2048\n\t"
;         "ds_read_b128 %3, %8 offset:3072\n\t"
;         "ds_read_b128 %4, %9\n\t"
;         "ds_read_b128 %5, %9 offset:1024\n\t"
;         "ds_read_b128 %6, %9 offset:2048\n\t"
;         "ds_read_b128 %7, %9 offset:3072\n\t"
;         "s_waitcnt lgkmcnt(0)"
;         : "=&v"(a0), "=&v"(a1), "=&v"(a2), "=&v"(a3), "=&v"(b0), "=&v"(b1), "=&v"(b2), "=&v"(b3)
;         : "v"(lds_a + so), "v"(lds_b + so)
;         : "memory");
;     ...
;     ROW4(accL, 0, a0) ROW4(accL, 1, a1)
;     if (pf) GEMM_DMA_A(kt + 3)
;     ROW4(accL, 2, a2) ROW4(accL, 3, a3)
;     asm volatile(
;         "ds_read_b128 %0, %4 offset:4096\n\t"
;         "ds_read_b128 %1, %4 offset:5120\n\t"
;         "ds_read_b128 %2, %4 offset:6144\n\t"
;         "ds_read_b128 %3, %4 offset:7168\n\t"
;         "s_waitcnt lgkmcnt(0)"
;         : "=&v"(a0), "=&v"(a1), "=&v"(a2), "=&v"(a3)
;         : "v"(lds_a + so)
;         : "memory");
;     ROW4(accH, 0, a0) ROW4(accH, 1, a1)
;     if (pf) GEMM_DMA_B(kt + 3)
;     ROW4(accH, 2, a2) ROW4(accH, 3, a3)
;     ...
;   }
	v_mfma_f32_16x16x32_bf16 v[112:115], v[128:131], v[146:149], v[112:115]
	v_add_u32_e32 v158, 0x10000, v133
	v_mfma_f32_16x16x32_bf16 v[0:3], v[128:131], v[150:153], v[0:3]
	v_mfma_f32_16x16x32_bf16 v[56:59], v[128:131], v[154:157], v[56:59]
	v_mfma_f32_16x16x32_bf16 v[4:7], v[128:131], v[162:165], v[4:7]
	v_mfma_f32_16x16x32_bf16 v[52:55], v[134:137], v[146:149], v[52:55]
	v_mfma_f32_16x16x32_bf16 v[8:11], v[134:137], v[150:153], v[8:11]
	v_mfma_f32_16x16x32_bf16 v[48:51], v[134:137], v[154:157], v[48:51]
	v_mfma_f32_16x16x32_bf16 v[12:15], v[134:137], v[162:165], v[12:15]
	v_mfma_f32_16x16x32_bf16 v[44:47], v[138:141], v[146:149], v[44:47]
	v_mfma_f32_16x16x32_bf16 v[16:19], v[138:141], v[150:153], v[16:19]
	v_mfma_f32_16x16x32_bf16 v[128:131], v[138:141], v[154:157], v[40:43]
	v_mfma_f32_16x16x32_bf16 v[20:23], v[138:141], v[162:165], v[20:23]
	v_mfma_f32_16x16x32_bf16 v[134:137], v[142:145], v[146:149], v[36:39]
	v_mfma_f32_16x16x32_bf16 v[24:27], v[142:145], v[150:153], v[24:27]
	v_mfma_f32_16x16x32_bf16 v[32:35], v[142:145], v[154:157], v[32:35]
	v_mfma_f32_16x16x32_bf16 v[28:31], v[142:145], v[162:165], v[28:31]
	ds_read_b128 v[138:141], v158
	ds_read_b128 v[142:145], v158 offset:1024
	ds_read_b128 v[146:149], v158 offset:2048
	ds_read_b128 v[150:153], v158 offset:3072
	ds_read_b128 v[154:157], v159
	ds_read_b128 v[40:43], v159 offset:1024
	ds_read_b128 v[162:165], v159 offset:2048
	ds_read_b128 v[36:39], v159 offset:3072
	s_waitcnt lgkmcnt(0)
	s_nop 0
	v_mfma_f32_16x16x32_bf16 v[124:127], v[138:141], v[154:157], v[124:127]
	v_mfma_f32_16x16x32_bf16 v[120:123], v[138:141], v[40:43], v[120:123]
	v_mfma_f32_16x16x32_bf16 v[116:119], v[138:141], v[162:165], v[116:119]
	v_mfma_f32_16x16x32_bf16 v[108:111], v[138:141], v[36:39], v[108:111]
	v_mfma_f32_16x16x32_bf16 v[104:107], v[142:145], v[154:157], v[104:107]
	v_mfma_f32_16x16x32_bf16 v[100:103], v[142:145], v[40:43], v[100:103]
	v_mfma_f32_16x16x32_bf16 v[96:99], v[142:145], v[162:165], v[96:99]
	v_mfma_f32_16x16x32_bf16 v[138:141], v[142:145], v[36:39], v[92:95]
	v_mfma_f32_16x16x32_bf16 v[142:145], v[146:149], v[154:157], v[88:91]
	v_mfma_f32_16x16x32_bf16 v[178:181], v[146:149], v[40:43], v[84:87]
	v_mfma_f32_16x16x32_bf16 v[184:187], v[146:149], v[162:165], v[80:83]
	v_mfma_f32_16x16x32_bf16 v[76:79], v[146:149], v[36:39], v[76:79]
	v_mfma_f32_16x16x32_bf16 v[192:195], v[150:153], v[154:157], v[72:75]
	v_mfma_f32_16x16x32_bf16 v[210:213], v[150:153], v[40:43], v[68:71]
	v_mfma_f32_16x16x32_bf16 v[218:221], v[150:153], v[36:39], v[60:63]
	ds_read_b128 v[88:91], v158 offset:4096
	ds_read_b128 v[84:87], v158 offset:5120
	ds_read_b128 v[68:71], v158 offset:6144
	ds_read_b128 v[60:63], v158 offset:7168
	s_waitcnt lgkmcnt(0)
	s_waitcnt vmcnt(0)
	s_barrier
	v_mfma_f32_16x16x32_bf16 v[214:217], v[150:153], v[162:165], v[64:67]
	v_mfma_f32_16x16x32_bf16 v[222:225], v[88:91], v[154:157], v[112:115]
	v_mfma_f32_16x16x32_bf16 v[64:67], v[88:91], v[162:165], v[56:59]
	v_mfma_f32_16x16x32_bf16 v[226:229], v[84:87], v[154:157], v[52:55]
	v_mfma_f32_16x16x32_bf16 v[72:75], v[84:87], v[162:165], v[48:51]
	v_mfma_f32_16x16x32_bf16 v[80:83], v[68:71], v[162:165], v[128:131]
	v_mfma_f32_16x16x32_bf16 v[56:59], v[60:63], v[162:165], v[32:35]
	ds_read_b128 v[32:35], v160
	ds_read_b128 v[112:115], v160 offset:1024
	ds_read_b128 v[128:131], v160 offset:2048
	ds_read_b128 v[234:237], v160 offset:3072
	ds_read_b128 v[238:241], v132
	ds_read_b128 v[52:55], v132 offset:1024
	ds_read_b128 v[92:95], v132 offset:2048
	ds_read_b128 v[48:51], v132 offset:3072
	s_waitcnt lgkmcnt(0)
	s_nop 0
	v_mfma_f32_16x16x32_bf16 v[148:151], v[112:115], v[48:51], v[138:141]
	v_mfma_f32_16x16x32_bf16 v[144:147], v[128:131], v[238:241], v[142:145]
	v_mfma_f32_16x16x32_bf16 v[140:143], v[128:131], v[52:55], v[178:181]
	s_nop 2
	v_lshrrev_b32_e32 v178, 6, v188
	v_mfma_f32_16x16x32_bf16 v[44:47], v[68:71], v[154:157], v[44:47]
	v_mfma_f32_16x16x32_bf16 v[230:233], v[60:63], v[154:157], v[134:137]
	v_mfma_f32_16x16x32_bf16 v[166:169], v[32:35], v[48:51], v[108:111]
	v_mfma_f32_16x16x32_bf16 v[162:165], v[112:115], v[238:241], v[104:107]
	v_mfma_f32_16x16x32_bf16 v[156:159], v[112:115], v[52:55], v[100:103]
	v_mfma_f32_16x16x32_bf16 v[152:155], v[112:115], v[92:95], v[96:99]
	ds_read_b128 v[112:115], v160 offset:4096
	ds_read_b128 v[108:111], v160 offset:5120
	ds_read_b128 v[104:107], v160 offset:6144
	ds_read_b128 v[100:103], v160 offset:7168
	s_waitcnt lgkmcnt(0)
	v_and_b32_e32 v160, 0xc0, v188
	s_waitcnt vmcnt(0) lgkmcnt(0)
	v_mfma_f32_16x16x32_bf16 v[136:139], v[128:131], v[92:95], v[184:187]
	s_barrier
; template <int EPI>
; DI void epilogue_tile(const EpiArgs& e, int row0, int wrow, int wcol, f32x4 (&acc)[4][4], char* smem, const float* rsm, int wave, int lane,
;                       bool final_sync = true) {
;     ...
;   const int b = row0 / NTOK, n0 = wrow - b * NTOK;
;   const int mi_mod = (row0 % NTOK) < CTXL ? 16 : b;
;   bool transposed = false;
;   if constexpr (EPI == EPI_IN) transposed = wcol >= 1280;
;   if constexpr (EPI == EPI_KV) transposed = (wcol & 64) != 0;
; #pragma unroll
;   for (int mi = 0; mi < 4; ++mi)
; #pragma unroll
;     for (int ni = 0; ni < 4; ++ni) {
;       const int lrow = mi * 16 + 4 * g, lcol = ni * 16 + r16;
;       const int col = wcol + lcol;
;       float v[4];
; #pragma unroll
;       for (int j = 0; j < 4; ++j) v[j] = acc[mi][ni][j];
;       if constexpr (EPI == EPI_Q || EPI == EPI_KV) {
; #pragma unroll
;         for (int j = 0; j < 4; ++j) v[j] *= rsm[lrow + j];
;       }
;       if constexpr (EPI == EPI_Q) {
;         const int d = col % 96;
;         if (d >= 64) {
;           const int i = d & 7;
;           const bool second = (d & 8) != 0;
;           const bool colrope = d >= 80;
;           const float inv = exp2f(-(float)i * (13.287712379549449f / 8.f));
; #pragma unroll
;           for (int j = 0; j < 4; ++j) {
;             const float partner = __shfl_xor(v[j], 8);
;             const int nn = n0 + lrow + j;
;             float cs = 1.f, sn = 0.f;
;             if (nn >= CTXL) {
;               const int t = nn - CTXL;
;               const float pos = (float)(colrope ? (t & 63) : (t >> 6));
;               { const float a_ = pos * inv; sn = __sinf(a_); cs = __cosf(a_); }
;             }
;             v[j] = second ? (v[j] * cs + partner * sn) : (v[j] * cs - partner * sn);
;           }
;         }
;       }
;       if constexpr (EPI == EPI_RES) {
;         const float gg = e.gate[(size_t)mi_mod * 6144 + col], bb = e.bias[col];
; #pragma unroll
;         for (int j = 0; j < 4; ++j) v[j] = gg * (v[j] + bb);
;       }
;       if constexpr (EPI == EPI_FF1) {
;         const float bb = e.bias[col];
; #pragma unroll
;         for (int j = 0; j < 4; ++j) { const float t = fmaxf(v[j] + bb, 0.f); v[j] = t * t; }
;       }
;       if (transposed) {
;         *(f32x4*)(stage + lcol * STG + lrow) = (f32x4){v[0], v[1], v[2], v[3]};
;       } else {
; #pragma unroll
	v_mfma_f32_16x16x32_bf16 v[132:135], v[128:131], v[48:51], v[76:79]
	v_mfma_f32_16x16x32_bf16 v[128:131], v[234:237], v[238:241], v[192:195]
	s_nop 2
	v_mul_lo_u32 v195, v178, s14
	s_mul_hi_u32 s14, s27, 0xf0f0f10
	v_mfma_f32_16x16x32_bf16 v[242:245], v[32:35], v[238:241], v[124:127]
	s_mulk_i32 s14, 0x6000
	v_mov_b32_e32 v178, 0x60000
	v_lshl_or_b32 v192, v182, 2, v195
	v_mfma_f32_16x16x32_bf16 v[124:127], v[234:237], v[52:55], v[210:213]
	v_lshl_or_b32 v191, v199, 2, v195
	s_nop 1
	v_or_b32_e32 v211, s34, v160
	v_alignbit_b32 v160, s15, s15, 8
	s_mov_b32 s15, 0xf0f0f
	v_cmp_lt_u32_e32 vcc, s15, v160
	v_mov_b32_e32 v160, s14
	v_mfma_f32_16x16x32_bf16 v[174:177], v[32:35], v[52:55], v[120:123]
	v_cndmask_b32_e32 v160, v178, v160, vcc
	v_lshl_add_u64 v[186:187], s[12:13], 0, v[160:161]
	v_or_b32_e32 v160, v211, v182
	v_lshlrev_b32_e32 v160, 2, v160
	v_readfirstlane_b32 s14, v186
	v_readfirstlane_b32 s15, v187
	v_mfma_f32_16x16x32_bf16 v[120:123], v[234:237], v[92:95], v[214:217]
	v_bfe_u32 v212, v188, 2, 4
	v_and_b32_e32 v198, 12, v212
	v_lshl_add_u64 v[178:179], v[186:187], 0, v[160:161]
	global_load_dword v215, v160, s[10:11]
	global_load_dword v214, v160, s[14:15]
	v_lshl_add_u64 v[180:181], s[10:11], 0, v[160:161]
	v_mad_u32_u24 v213, v198, s35, v192
	v_or_b32_e32 v200, 3, v212
	v_mad_u32_u24 v201, v200, s35, v192
	v_mfma_f32_16x16x32_bf16 v[170:173], v[32:35], v[92:95], v[116:119]
	v_mul_u32_u24_e32 v193, 0x110, v198
	v_mul_u32_u24_e32 v194, 0x110, v200
	s_waitcnt vmcnt(1)
	v_add_f32_e32 v160, v242, v215
	s_waitcnt vmcnt(0)
	v_mul_f32_e32 v160, v214, v160
	v_add_f32_e32 v183, v243, v215
	v_add_f32_e32 v184, v244, v215
	v_mul_f32_e32 v183, v214, v183
	v_mul_f32_e32 v184, v214, v184
	ds_write_b32 v213, v160
	ds_write_b32 v213, v183 offset:272
	ds_write_b32 v213, v184 offset:544
	v_add_lshl_u32 v160, v211, v182, 2
	global_load_dword v216, v160, s[14:15] offset:64
	global_load_dword v217, v160, s[10:11] offset:64
	v_add_f32_e32 v185, v245, v215
	v_mul_f32_e32 v185, v214, v185
	ds_write_b32 v201, v185
	v_lshl_add_u64 v[182:183], v[186:187], 0, v[160:161]
	v_lshl_add_u64 v[184:185], s[10:11], 0, v[160:161]
	v_add_f32_e32 v162, v162, v215
	v_add_f32_e32 v163, v163, v215
	v_mul_f32_e32 v162, v214, v162
	v_mul_f32_e32 v163, v214, v163
	v_add_f32_e32 v164, v164, v215
	v_mul_f32_e32 v164, v214, v164
	v_add_f32_e32 v165, v165, v215
	v_mul_f32_e32 v165, v214, v165
	v_add_f32_e32 v144, v144, v215
	v_add_f32_e32 v145, v145, v215
	v_mul_f32_e32 v144, v214, v144
	v_mul_f32_e32 v145, v214, v145
	v_add_f32_e32 v146, v146, v215
	v_mul_f32_e32 v146, v214, v146
	v_add_f32_e32 v147, v147, v215
	v_mfma_f32_16x16x32_bf16 v[116:119], v[234:237], v[48:51], v[218:221]
	v_mul_f32_e32 v147, v214, v147
	v_add_f32_e32 v128, v128, v215
	v_add_f32_e32 v129, v129, v215
	v_mul_f32_e32 v128, v214, v128
	v_mul_f32_e32 v129, v214, v129
	v_add_f32_e32 v130, v130, v215
	v_mul_f32_e32 v130, v214, v130
	v_add_f32_e32 v131, v131, v215
	v_mul_f32_e32 v131, v214, v131
	v_mfma_f32_16x16x32_bf16 v[96:99], v[112:115], v[238:241], v[222:225]
	s_waitcnt vmcnt(0)
	v_add_f32_e32 v174, v174, v217
	v_mul_f32_e32 v174, v216, v174
	v_add_f32_e32 v175, v175, v217
	v_add_f32_e32 v176, v176, v217
	v_add_f32_e32 v177, v177, v217
	v_mul_f32_e32 v175, v216, v175
	v_mul_f32_e32 v176, v216, v176
	v_mul_f32_e32 v177, v216, v177
	ds_write_b32 v213, v174 offset:64
	ds_write_b32 v213, v175 offset:336
	ds_write_b32 v213, v176 offset:608
	ds_write_b32 v201, v177 offset:64
	global_load_dword v174, v160, s[14:15] offset:128
	global_load_dword v175, v160, s[10:11] offset:128
	v_mad_u32_u24 v177, v198, s35, v191
	v_add_f32_e32 v156, v156, v217
	v_mul_f32_e32 v156, v216, v156
	v_add_f32_e32 v157, v157, v217
	v_add_f32_e32 v158, v158, v217
	v_add_f32_e32 v159, v159, v217
	v_mul_f32_e32 v157, v216, v157
	v_mul_f32_e32 v158, v216, v158
	v_mul_f32_e32 v159, v216, v159
	v_add_f32_e32 v140, v140, v217
	v_mul_f32_e32 v140, v216, v140
	v_add_f32_e32 v141, v141, v217
	v_add_f32_e32 v142, v142, v217
	v_add_f32_e32 v143, v143, v217
	v_mul_f32_e32 v141, v216, v141
	v_mul_f32_e32 v142, v216, v142
	v_mul_f32_e32 v143, v216, v143
	v_add_f32_e32 v124, v124, v217
	v_mul_f32_e32 v124, v216, v124
	v_add_f32_e32 v125, v125, v217
	v_add_f32_e32 v126, v126, v217
	v_add_f32_e32 v127, v127, v217
	v_mul_f32_e32 v125, v216, v125
	v_mul_f32_e32 v126, v216, v126
	v_mul_f32_e32 v127, v216, v127
	v_mfma_f32_16x16x32_bf16 v[76:79], v[108:111], v[238:241], v[226:229]
	s_waitcnt vmcnt(0)
; template <int EPI>
; DI void epilogue_tile(const EpiArgs& e, int row0, int wrow, int wcol, f32x4 (&acc)[4][4], char* smem, const float* rsm, int wave, int lane,
;                       bool final_sync = true) {
;     ...
;       if constexpr (EPI == EPI_RES) {
;         const float gg = e.gate[(size_t)mi_mod * 6144 + col], bb = e.bias[col];
; #pragma unroll
;         for (int j = 0; j < 4; ++j) v[j] = gg * (v[j] + bb);
;       }
;       if constexpr (EPI == EPI_FF1) {
;         const float bb = e.bias[col];
; #pragma unroll
;         for (int j = 0; j < 4; ++j) { const float t = fmaxf(v[j] + bb, 0.f); v[j] = t * t; }
;       }
;       if (transposed) {
;         *(f32x4*)(stage + lcol * STG + lrow) = (f32x4){v[0], v[1], v[2], v[3]};
;       } else {
; #pragma unroll
;         for (int j = 0; j < 4; ++j) stage[(lrow + j) * STG + lcol] = v[j];
;       }
;     }
;   const int rr = lane >> 3, c8 = (lane & 7) * 8;
; #pragma unroll 4
;   for (int it = 0; it < 8; ++it) {
;     const int sr = it * 8 + rr;
;     const f32x4 v0 = *(const f32x4*)(stage + sr * STG + c8);
;     const f32x4 v1 = *(const f32x4*)(stage + sr * STG + c8 + 4);
;     if constexpr (EPI == EPI_RES) {
;       bft* px = (bft*)(e.ws + OFF_XS) + (size_t)(wrow + sr) * D + wcol + c8;
	v_add_f32_e32 v160, v170, v175
	v_mul_f32_e32 v160, v174, v160
	v_add_f32_e32 v170, v171, v175
	v_add_f32_e32 v171, v172, v175
	v_add_f32_e32 v172, v173, v175
	v_mul_f32_e32 v170, v174, v170
	v_mul_f32_e32 v171, v174, v171
	v_mul_f32_e32 v172, v174, v172
	ds_write_b32 v213, v160 offset:128
	ds_write_b32 v213, v170 offset:400
	ds_write_b32 v213, v171 offset:672
	ds_write_b32 v201, v172 offset:128
	v_or_b32_e32 v160, v211, v199
	v_lshlrev_b32_e32 v160, 2, v160
	v_lshl_add_u64 v[170:171], v[186:187], 0, v[160:161]
	global_load_dword v176, v160, s[14:15]
	v_lshl_add_u64 v[172:173], s[10:11], 0, v[160:161]
	global_load_dword v160, v160, s[10:11]
	v_add_f32_e32 v152, v152, v175
	v_mul_f32_e32 v152, v174, v152
	v_add_f32_e32 v153, v153, v175
	v_add_f32_e32 v154, v154, v175
	v_add_f32_e32 v155, v155, v175
	v_mul_f32_e32 v153, v174, v153
	v_mul_f32_e32 v154, v174, v154
	v_mul_f32_e32 v155, v174, v155
	v_add_f32_e32 v136, v136, v175
	v_mul_f32_e32 v136, v174, v136
	v_add_f32_e32 v137, v137, v175
	v_add_f32_e32 v138, v138, v175
	v_add_f32_e32 v139, v139, v175
	v_mul_f32_e32 v137, v174, v137
	v_mul_f32_e32 v138, v174, v138
	v_mul_f32_e32 v139, v174, v139
	v_add_f32_e32 v120, v120, v175
	v_mul_f32_e32 v120, v174, v120
	v_add_f32_e32 v121, v121, v175
	v_add_f32_e32 v122, v122, v175
	v_add_f32_e32 v123, v123, v175
	v_mul_f32_e32 v121, v174, v121
	v_mul_f32_e32 v122, v174, v122
	v_mul_f32_e32 v123, v174, v123
	v_mfma_f32_16x16x32_bf16 v[44:47], v[104:107], v[238:241], v[44:47]
	s_mov_b32 s14, 0
	s_waitcnt vmcnt(0)
	v_add_f32_e32 v166, v166, v160
	v_add_f32_e32 v167, v167, v160
	v_mul_f32_e32 v166, v176, v166
	v_mul_f32_e32 v167, v176, v167
	v_add_f32_e32 v168, v168, v160
	v_add_f32_e32 v169, v169, v160
	v_mul_f32_e32 v168, v176, v168
	v_mul_f32_e32 v169, v176, v169
	ds_write2_b32 v177, v166, v167 offset1:68
	ds_write_b32 v177, v168 offset:544
	v_mad_u32_u24 v166, v200, s35, v191
	ds_write_b32 v166, v169
	ds_write_b32 v213, v162 offset:4352
	ds_write_b32 v213, v163 offset:4624
	ds_write_b32 v213, v164 offset:4896
	v_or_b32_e32 v163, 19, v212
	v_mad_u32_u24 v164, v163, s35, v192
	v_add_f32_e32 v148, v148, v160
	v_add_f32_e32 v149, v149, v160
	ds_write_b32 v164, v165
	ds_write_b32 v213, v156 offset:4416
	ds_write_b32 v213, v157 offset:4688
	ds_write_b32 v213, v158 offset:4960
	ds_write_b32 v164, v159 offset:64
	ds_write_b32 v213, v152 offset:4480
	ds_write_b32 v213, v153 offset:4752
	ds_write_b32 v213, v154 offset:5024
	ds_write_b32 v164, v155 offset:128
	v_mul_f32_e32 v148, v176, v148
	v_mul_f32_e32 v149, v176, v149
	v_add_f32_e32 v150, v150, v160
	v_add_f32_e32 v151, v151, v160
	v_add_u32_e32 v152, 0x1000, v177
	v_mul_f32_e32 v150, v176, v150
	v_mul_f32_e32 v151, v176, v151
	ds_write2_b32 v152, v148, v149 offset0:64 offset1:132
	ds_write_b32 v177, v150 offset:4896
	v_mad_u32_u24 v148, v163, s35, v191
	ds_write_b32 v148, v151
	ds_write_b32 v213, v144 offset:8704
	ds_write_b32 v213, v145 offset:8976
	ds_write_b32 v213, v146 offset:9248
	v_or_b32_e32 v145, 35, v212
	v_mad_u32_u24 v146, v145, s35, v192
	v_add_f32_e32 v132, v132, v160
	v_add_f32_e32 v133, v133, v160
	ds_write_b32 v146, v147
	ds_write_b32 v213, v140 offset:8768
	ds_write_b32 v213, v141 offset:9040
	ds_write_b32 v213, v142 offset:9312
	ds_write_b32 v146, v143 offset:64
	ds_write_b32 v213, v136 offset:8832
	ds_write_b32 v213, v137 offset:9104
	ds_write_b32 v213, v138 offset:9376
	ds_write_b32 v146, v139 offset:128
	v_mul_f32_e32 v132, v176, v132
	v_mul_f32_e32 v133, v176, v133
	v_add_f32_e32 v134, v134, v160
	v_add_f32_e32 v135, v135, v160
	v_add_u32_e32 v136, 0x2000, v177
	v_mul_f32_e32 v134, v176, v134
	v_mul_f32_e32 v135, v176, v135
	ds_write2_b32 v136, v132, v133 offset0:128 offset1:196
	ds_write_b32 v177, v134 offset:9248
	v_mad_u32_u24 v132, v145, s35, v191
	ds_write_b32 v132, v135
	ds_write_b32 v213, v128 offset:13056
	ds_write_b32 v213, v129 offset:13328
	ds_write_b32 v213, v130 offset:13600
	v_or_b32_e32 v129, 51, v212
	v_mad_u32_u24 v130, v129, s35, v192
	v_add_f32_e32 v116, v116, v160
	v_add_f32_e32 v117, v117, v160
	ds_write_b32 v130, v131
	ds_write_b32 v213, v124 offset:13120
	ds_write_b32 v213, v125 offset:13392
	ds_write_b32 v213, v126 offset:13664
	ds_write_b32 v130, v127 offset:64
	ds_write_b32 v213, v120 offset:13184
	ds_write_b32 v213, v121 offset:13456
	ds_write_b32 v213, v122 offset:13728
	ds_write_b32 v130, v123 offset:128
	v_mul_f32_e32 v116, v176, v116
	v_mul_f32_e32 v117, v176, v117
	v_add_f32_e32 v118, v118, v160
	v_add_f32_e32 v119, v119, v160
	v_add_u32_e32 v120, 0x3200, v177
	v_mul_f32_e32 v118, v176, v118
	v_mul_f32_e32 v119, v176, v119
	ds_write2_b32 v120, v116, v117 offset0:64 offset1:132
	ds_write_b32 v177, v118 offset:13600
	v_mad_u32_u24 v116, v129, s35, v191
	v_mfma_f32_16x16x32_bf16 v[32:35], v[100:103], v[238:241], v[230:233]
	ds_write_b32 v116, v119
	v_bfe_u32 v118, v188, 3, 3
	v_and_b32_e32 v119, 7, v188
	v_lshlrev_b32_e32 v160, 1, v211
	v_add3_u32 v120, v118, s17, v189
	v_mul_u32_u24_e32 v118, 0x110, v118
	v_lshlrev_b32_e32 v119, 5, v119
	v_lshl_add_u64 v[116:117], s[90:91], 0, v[160:161]
	v_and_b32_e32 v160, 0x70, v190
	v_add3_u32 v121, v195, v118, v119
	v_mul_u32_u24_e32 v162, 0x110, v163
	v_mul_u32_u24_e32 v144, 0x110, v145
	v_mul_u32_u24_e32 v128, 0x110, v129
	v_lshl_add_u64 v[116:117], v[116:117], 0, v[160:161]
	v_mov_b32_e32 v122, v121

; DI int otid() { int t = threadIdx.x; asm volatile("" : "+v"(t)); return t; }
; #define GEMM_DMA(kt) { GEMM_DMA_A(kt) GEMM_DMA_B(kt) }
; template <int EPI>
; __device__ __forceinline__ void gemm_tile_dma(const bft* __restrict__ A, int lda, const bft* __restrict__ Bt, int K, int row0, int col0,
;                                               char* smem, const EpiArgs& e) {
;   const int tid = otid(), wave = tid >> 6, lane = tid & 63;
;   const int wm = wave >> 2, wn = wave & 3, r16 = lane & 15, g = lane >> 4;
;   f32x4 accL[4][4], accH[4][4];
; #pragma unroll
;   for (int i = 0; i < 4; ++i)
; #pragma unroll
;     for (int j = 0; j < 4; ++j) { accL[i][j] = (f32x4){0.f, 0.f, 0.f, 0.f}; accH[i][j] = (f32x4){0.f, 0.f, 0.f, 0.f}; }
;   const int lr = tid >> 2, pc = tid & 3;
;   const int kcs = (pc ^ ((4 - ((lr >> 2) & 3)) & 3)) * 8;
;   const int rco = (g ^ ((4 - ((r16 >> 2) & 3)) & 3)) * 8;
;   const bft* ag = A + (size_t)(row0 + lr) * lda + kcs;
;   const bft* bg = Bt + (size_t)(col0 + lr) * K + kcs;
;   const unsigned lds_a = (unsigned)(size_t)smem + (unsigned)(((wm * 128 + r16) * 32 + rco) * 2);
;   const unsigned lds_b = (unsigned)(size_t)smem + 16384u + (unsigned)(((wn * 64 + r16) * 32 + rco) * 2);
;   const int nk = K / 32;
;     ...
;   GEMM_DMA(0);
;   GEMM_DMA(1);
;   GEMM_DMA(2);
; template <int EPI, bool RMS>
; __device__ __forceinline__ void gemm_phase(const bft* A, int lda, const bft* Bt, int K, int ntn, char* smem, const EpiArgs& e) {
;   const int G8 = gridDim.x >> 3, xcd = blockIdx.x & 7, loc = blockIdx.x >> 3;
;   constexpr int RT = 34;
;   const int per = RT * ntn;
;   for (int idx = loc; idx < per; idx += G8) {
;     const int grp = idx / (8 * ntn);
;     const int within = idx - grp * (8 * ntn);
;     const int rig = (grp < RT / 8) ? 8 : RT % 8;
;     const int tm = xcd * RT + grp * 8 + within % rig, tn = within / rig;
;     if constexpr (RMS) gemm_tile<EPI, RMS>(A, lda, Bt, K, tm * 256, tn * 128, smem, e);
;     else gemm_tile_dma<EPI>(A, lda, Bt, K, tm * 256, tn * 256, smem, e);
.LBB0_1311:
	s_lshr_b32 s13, s14, 4
	s_and_b32 s12, s14, 0x7f
	s_and_b32 s13, s13, 56
	s_cmpk_lt_u32 s14, 0x200
	s_cselect_b32 s15, 7, 1
	s_cselect_b32 s16, 3, 1
	s_and_b32 s15, s15, s14
	v_mov_b32_e32 v182, v196
	s_add_i32 s15, s3, s15
	s_add_i32 s15, s15, s13
	v_lshrrev_b32_e32 v0, 4, v182
	v_sub_u32_e32 v10, 0, v0
	v_lshlrev_b32_e32 v0, 2, v182
	s_lshl_b32 s15, s15, 8
	v_ashrrev_i32_e32 v4, 2, v182
	v_and_b32_e32 v0, 48, v0
	v_sub_u32_e32 v11, 0, v0
	v_add_u32_e32 v0, s15, v4
	v_xor_b32_e32 v5, v182, v10
	v_ashrrev_i32_e32 v1, 31, v0
	s_lshr_b32 s12, s12, s16
	v_lshlrev_b64 v[0:1], 11, v[0:1]
	v_lshlrev_b32_e32 v5, 4, v5
	v_lshlrev_b32_e32 v184, 4, v182
	s_lshl_b32 s16, s12, 8
	v_lshl_add_u64 v[2:3], s[62:63], 0, v[0:1]
	v_and_b32_e32 v160, 48, v5
	v_readfirstlane_b32 s12, v184
	v_add_u32_e32 v14, 0x2000, v184
	v_lshl_add_u64 v[2:3], v[2:3], 0, v[160:161]
	v_add_u32_e32 v4, s16, v4
	v_ashrrev_i32_e32 v8, 1, v182
	s_mov_b32 m0, s12
	s_mov_b64 s[38:39], 0x40000
	v_readfirstlane_b32 s12, v14
	v_ashrrev_i32_e32 v5, 31, v4
	v_and_b32_e32 v183, 0xffffff80, v8
	global_load_lds_dwordx4 v[2:3], off
	v_lshl_add_u64 v[8:9], v[2:3], 0, s[38:39]
	s_mov_b32 m0, s12
	v_lshlrev_b64 v[4:5], 11, v[4:5]
	global_load_lds_dwordx4 v[8:9], off
	v_add_u32_e32 v8, 0x4000, v184
	v_lshl_add_u64 v[6:7], s[24:25], 0, v[4:5]
	v_readfirstlane_b32 s12, v8
	v_add_u32_e32 v14, 0x6000, v184
	v_lshl_add_u64 v[6:7], v[6:7], 0, v[160:161]
	s_mov_b32 m0, s12
	v_readfirstlane_b32 s12, v14
	v_add_u32_e32 v14, 0x8000, v184
	global_load_lds_dwordx4 v[6:7], off
	v_lshl_add_u64 v[8:9], v[6:7], 0, s[38:39]
	s_mov_b32 m0, s12
	v_readfirstlane_b32 s12, v14
	v_add_u32_e32 v14, 0xa000, v184
	global_load_lds_dwordx4 v[8:9], off
	v_lshl_add_u64 v[8:9], v[2:3], 0, 64
	s_mov_b32 m0, s12
	s_mov_b64 s[38:39], 0x40040
	v_readfirstlane_b32 s12, v14
	v_add_u32_e32 v14, 0xc000, v184
	global_load_lds_dwordx4 v[8:9], off
	v_lshl_add_u64 v[8:9], v[2:3], 0, s[38:39]
	s_mov_b32 m0, s12
	v_readfirstlane_b32 s12, v14
	v_add_u32_e32 v14, 0xe000, v184
	global_load_lds_dwordx4 v[8:9], off
	v_lshl_add_u64 v[8:9], v[6:7], 0, 64
	s_mov_b32 m0, s12
	v_readfirstlane_b32 s12, v14
	v_add_u32_e32 v14, 0x10000, v184
	global_load_lds_dwordx4 v[8:9], off
	v_lshl_add_u64 v[8:9], v[6:7], 0, s[38:39]
	s_mov_b32 m0, s12
	s_mov_b64 s[38:39], 0x80
	v_readfirstlane_b32 s12, v14
	global_load_lds_dwordx4 v[8:9], off
	v_lshl_add_u64 v[8:9], v[2:3], 0, s[38:39]
	s_mov_b32 m0, s12
	s_mov_b64 s[40:41], 0x40080
	global_load_lds_dwordx4 v[8:9], off
	v_add_u32_e32 v8, 0x12000, v184
	v_lshl_add_u64 v[2:3], v[2:3], 0, s[40:41]
	v_readfirstlane_b32 s12, v8
	v_add_u32_e32 v8, 0x14000, v184
	s_mov_b32 m0, s12
	v_readfirstlane_b32 s12, v8
	global_load_lds_dwordx4 v[2:3], off
	v_lshl_add_u64 v[2:3], v[6:7], 0, s[38:39]
	s_mov_b32 m0, s12
	v_lshlrev_b32_e32 v13, 6, v182
	global_load_lds_dwordx4 v[2:3], off
	v_lshl_add_u64 v[2:3], v[6:7], 0, s[40:41]
	v_add_u32_e32 v6, 0x16000, v184
	v_bitop3_b32 v11, v182, 48, v11 bitop3:0x48
	v_readfirstlane_b32 s12, v6
	s_mov_b32 m0, s12
	v_and_b32_e32 v180, 15, v182
	global_load_lds_dwordx4 v[2:3], off
	v_and_b32_e32 v2, 0x33c0, v13
	v_or3_b32 v133, v2, v11, s42
	v_bitop3_b32 v2, v182, 3, v10 bitop3:0x48
	v_lshlrev_b32_e32 v2, 4, v2
	v_or_b32_e32 v0, v0, v2
	v_or_b32_e32 v12, v183, v180
	v_or_b32_e32 v4, v4, v2
	s_waitcnt vmcnt(0)
	v_lshl_add_u64 v[130:131], s[90:91], 0, v[0:1]
	v_mov_b32_e32 v0, 0
	v_not_b32_e32 v252, 63
	v_mov_b32_e32 v251, 0x42800000
	v_mov_b32_e32 v250, 0x22000
	s_mov_b32 s17, 0
	v_lshl_or_b32 v132, v12, 6, v11
	v_lshl_add_u64 v[128:129], s[90:91], 0, v[4:5]
	s_mov_b64 s[12:13], 0
	v_mov_b32_e32 v1, v0
	v_mov_b32_e32 v2, v0
	v_mov_b32_e32 v3, v0
	v_mov_b32_e32 v32, v0
	v_mov_b32_e32 v33, v0
	v_mov_b32_e32 v34, v0
	v_mov_b32_e32 v35, v0
	v_mov_b32_e32 v28, v0
	v_mov_b32_e32 v29, v0
	v_mov_b32_e32 v30, v0
	v_mov_b32_e32 v31, v0
	v_mov_b32_e32 v36, v0
	v_mov_b32_e32 v37, v0
	v_mov_b32_e32 v38, v0
	v_mov_b32_e32 v39, v0
	v_mov_b32_e32 v24, v0
	v_mov_b32_e32 v25, v0
	v_mov_b32_e32 v26, v0
	v_mov_b32_e32 v27, v0
	v_mov_b32_e32 v40, v0
	v_mov_b32_e32 v41, v0
	v_mov_b32_e32 v42, v0
	v_mov_b32_e32 v43, v0
	v_mov_b32_e32 v20, v0
	v_mov_b32_e32 v21, v0
	v_mov_b32_e32 v22, v0
	v_mov_b32_e32 v23, v0
	v_mov_b32_e32 v44, v0
	v_mov_b32_e32 v45, v0
	v_mov_b32_e32 v46, v0
	v_mov_b32_e32 v47, v0
	v_mov_b32_e32 v16, v0
	v_mov_b32_e32 v17, v0
	v_mov_b32_e32 v18, v0
	v_mov_b32_e32 v19, v0
	v_mov_b32_e32 v48, v0
	v_mov_b32_e32 v49, v0
	v_mov_b32_e32 v50, v0
	v_mov_b32_e32 v51, v0
	v_mov_b32_e32 v12, v0
	v_mov_b32_e32 v13, v0
	v_mov_b32_e32 v14, v0
	v_mov_b32_e32 v15, v0
	v_mov_b32_e32 v52, v0
	v_mov_b32_e32 v53, v0
	v_mov_b32_e32 v54, v0
	v_mov_b32_e32 v55, v0
	v_mov_b32_e32 v8, v0
	v_mov_b32_e32 v9, v0
	v_mov_b32_e32 v10, v0
	v_mov_b32_e32 v11, v0
	v_mov_b32_e32 v56, v0
	v_mov_b32_e32 v57, v0
	v_mov_b32_e32 v58, v0
	v_mov_b32_e32 v59, v0
	v_mov_b32_e32 v4, v0
	v_mov_b32_e32 v5, v0
	v_mov_b32_e32 v6, v0
	v_mov_b32_e32 v7, v0
	v_mov_b32_e32 v60, v0
	v_mov_b32_e32 v61, v0
	v_mov_b32_e32 v62, v0
	v_mov_b32_e32 v63, v0
	v_mov_b32_e32 v64, v0
	v_mov_b32_e32 v65, v0
	v_mov_b32_e32 v66, v0
	v_mov_b32_e32 v67, v0
	v_mov_b32_e32 v68, v0
	v_mov_b32_e32 v69, v0
	v_mov_b32_e32 v70, v0
	v_mov_b32_e32 v71, v0
	v_mov_b32_e32 v72, v0
	v_mov_b32_e32 v73, v0
	v_mov_b32_e32 v74, v0
	v_mov_b32_e32 v75, v0
	v_mov_b32_e32 v76, v0
	v_mov_b32_e32 v77, v0
	v_mov_b32_e32 v78, v0
	v_mov_b32_e32 v79, v0
	v_mov_b32_e32 v80, v0
	v_mov_b32_e32 v81, v0
	v_mov_b32_e32 v82, v0
	v_mov_b32_e32 v83, v0
	v_mov_b32_e32 v84, v0
	v_mov_b32_e32 v85, v0
	v_mov_b32_e32 v86, v0
	v_mov_b32_e32 v87, v0
	v_mov_b32_e32 v88, v0
	v_mov_b32_e32 v89, v0
	v_mov_b32_e32 v90, v0
	v_mov_b32_e32 v91, v0
	v_mov_b32_e32 v92, v0
	v_mov_b32_e32 v93, v0
	v_mov_b32_e32 v94, v0
	v_mov_b32_e32 v95, v0
	v_mov_b32_e32 v96, v0
	v_mov_b32_e32 v97, v0
	v_mov_b32_e32 v98, v0
	v_mov_b32_e32 v99, v0
	v_mov_b32_e32 v100, v0
	v_mov_b32_e32 v101, v0
	v_mov_b32_e32 v102, v0
	v_mov_b32_e32 v103, v0
	v_mov_b32_e32 v104, v0
	v_mov_b32_e32 v105, v0
	v_mov_b32_e32 v106, v0
	v_mov_b32_e32 v107, v0
	v_mov_b32_e32 v108, v0
	v_mov_b32_e32 v109, v0
	v_mov_b32_e32 v110, v0
	v_mov_b32_e32 v111, v0
	v_mov_b32_e32 v116, v0
	v_mov_b32_e32 v117, v0
	v_mov_b32_e32 v118, v0
	v_mov_b32_e32 v119, v0
	v_mov_b32_e32 v120, v0
	v_mov_b32_e32 v121, v0
	v_mov_b32_e32 v122, v0
	v_mov_b32_e32 v123, v0
	v_mov_b32_e32 v124, v0
	v_mov_b32_e32 v125, v0
	v_mov_b32_e32 v126, v0
	v_mov_b32_e32 v127, v0
	v_mov_b32_e32 v112, v0
	v_mov_b32_e32 v113, v0
	v_mov_b32_e32 v114, v0
	v_mov_b32_e32 v115, v0
	s_getreg_b32 s32, hwreg(HW_REG_HW_ID, 0, 1)
	s_cmp_eq_u32 s32, 1
	s_cbranch_scc0 .Lgprio1_skip
	s_setprio 1
; #define ROW4(accv, r, av)                                                                              \
;     accv[r][0] = MFMA16(av, b0, accv[r][0]); accv[r][1] = MFMA16(av, b1, accv[r][1]);                      \
;     accv[r][2] = MFMA16(av, b2, accv[r][2]); accv[r][3] = MFMA16(av, b3, accv[r][3]);
; template <int EPI>
; __device__ __forceinline__ void gemm_tile_dma(const bft* __restrict__ A, int lda, const bft* __restrict__ Bt, int K, int row0, int col0,
;                                               char* smem, const EpiArgs& e) {
;     ...
;   for (int kt = 0; kt < nk; ++kt) {
;     if (kt + 2 < nk) asm volatile("s_waitcnt vmcnt(8)" ::: "memory");
;     else if (kt + 1 < nk) asm volatile("s_waitcnt vmcnt(4)" ::: "memory");
;     else asm volatile("s_waitcnt vmcnt(0)" ::: "memory");
;     __builtin_amdgcn_s_barrier();
;     asm volatile("" ::: "memory");
;     const bool pf = kt + 3 < nk;
;     const unsigned so = (unsigned)(kt & 3) * GST;
;     bf16x8 a0, a1, a2, a3, b0, b1, b2, b3;
;     asm volatile(
;         "ds_read_b128 %0, %8\n\t"
;         "ds_read_b128 %1, %8 offset:1024\n\t"
;         "ds_read_b128 %2, %8 offset:2048\n\t"
;         "ds_read_b128 %3, %8 offset:3072\n\t"
;         "ds_read_b128 %4, %9\n\t"
;         "ds_read_b128 %5, %9 offset:1024\n\t"
;         "ds_read_b128 %6, %9 offset:2048\n\t"
;         "ds_read_b128 %7, %9 offset:3072\n\t"
;         "s_waitcnt lgkmcnt(0)"
;         : "=&v"(a0), "=&v"(a1), "=&v"(a2), "=&v"(a3), "=&v"(b0), "=&v"(b1), "=&v"(b2), "=&v"(b3)
;         : "v"(lds_a + so), "v"(lds_b + so)
;         : "memory");
;     ...
;     ROW4(accL, 0, a0) ROW4(accL, 1, a1)
;     if (pf) GEMM_DMA_A(kt + 3)
;     ROW4(accL, 2, a2) ROW4(accL, 3, a3)
;     asm volatile(
;         "ds_read_b128 %0, %4 offset:4096\n\t"
;         "ds_read_b128 %1, %4 offset:5120\n\t"
;         "ds_read_b128 %2, %4 offset:6144\n\t"
;         "ds_read_b128 %3, %4 offset:7168\n\t"
;         "s_waitcnt lgkmcnt(0)"
;         : "=&v"(a0), "=&v"(a1), "=&v"(a2), "=&v"(a3)
;         : "v"(lds_a + so)
;         : "memory");
;     ROW4(accH, 0, a0) ROW4(accH, 1, a1)
;     if (pf) GEMM_DMA_B(kt + 3)
;     ROW4(accH, 2, a2) ROW4(accH, 3, a3)
;     ...
;   }
.Lgprio1_skip:
.LBB0_1312:
	s_and_b32 s27, s17, 0x18000
	v_add_u32_e32 v158, s27, v132
	v_or_b32_e32 v159, s27, v133
	s_add_i32 s27, s17, 0x18000
	s_waitcnt vmcnt(8)
	s_barrier
	s_and_b32 s27, s27, 0x18000
	ds_read_b128 v[134:137], v158
	ds_read_b128 v[138:141], v158 offset:1024
	ds_read_b128 v[142:145], v158 offset:2048
	ds_read_b128 v[146:149], v158 offset:3072
	ds_read_b128 v[150:153], v159
	ds_read_b128 v[154:157], v159 offset:1024
	ds_read_b128 v[162:165], v159 offset:2048
	ds_read_b128 v[166:169], v159 offset:3072
	s_waitcnt lgkmcnt(0)
	v_add_u32_e32 v159, s27, v184
	v_mfma_f32_16x16x32_bf16 v[124:127], v[134:137], v[150:153], v[124:127]
	v_readfirstlane_b32 s27, v159
	s_mov_b32 m0, s27
	s_mov_b64 s[38:39], 0x3bf800c0
	v_mfma_f32_16x16x32_bf16 v[120:123], v[134:137], v[154:157], v[120:123]
	v_mfma_f32_16x16x32_bf16 v[116:119], v[134:137], v[162:165], v[116:119]
	v_mfma_f32_16x16x32_bf16 v[108:111], v[134:137], v[166:169], v[108:111]
	v_lshl_add_u64 v[134:135], v[130:131], 0, s[12:13]
	v_lshl_add_u64 v[136:137], v[134:135], 0, s[28:29]
	v_lshl_add_u64 v[134:135], v[134:135], 0, s[20:21]
	v_mfma_f32_16x16x32_bf16 v[104:107], v[138:141], v[150:153], v[104:107]
	global_load_lds_dwordx4 v[136:137], off
	v_mfma_f32_16x16x32_bf16 v[100:103], v[138:141], v[154:157], v[100:103]
	v_mfma_f32_16x16x32_bf16 v[96:99], v[138:141], v[162:165], v[96:99]
	v_mfma_f32_16x16x32_bf16 v[92:95], v[138:141], v[166:169], v[92:95]
	v_add_u32_e32 v138, 0x2000, v159
	s_nop 0
	v_readfirstlane_b32 s34, v138
	s_mov_b32 m0, s34
	v_mfma_f32_16x16x32_bf16 v[88:91], v[142:145], v[150:153], v[88:91]
	global_load_lds_dwordx4 v[134:135], off
	v_mfma_f32_16x16x32_bf16 v[84:87], v[142:145], v[154:157], v[84:87]
	v_mfma_f32_16x16x32_bf16 v[80:83], v[142:145], v[162:165], v[80:83]
	v_mfma_f32_16x16x32_bf16 v[76:79], v[142:145], v[166:169], v[76:79]
	v_mfma_f32_16x16x32_bf16 v[72:75], v[146:149], v[150:153], v[72:75]
	v_mfma_f32_16x16x32_bf16 v[68:71], v[146:149], v[154:157], v[68:71]
	v_mfma_f32_16x16x32_bf16 v[64:67], v[146:149], v[162:165], v[64:67]
	v_mfma_f32_16x16x32_bf16 v[60:63], v[146:149], v[166:169], v[60:63]
	ds_read_b128 v[134:137], v158 offset:4096
	ds_read_b128 v[138:141], v158 offset:5120
	ds_read_b128 v[142:145], v158 offset:6144
	ds_read_b128 v[146:149], v158 offset:7168
	s_waitcnt lgkmcnt(0)
	s_nop 0
	v_mfma_f32_16x16x32_bf16 v[52:55], v[138:141], v[150:153], v[52:55]
	v_mfma_f32_16x16x32_bf16 v[12:15], v[138:141], v[154:157], v[12:15]
	v_mfma_f32_16x16x32_bf16 v[48:51], v[138:141], v[162:165], v[48:51]
	v_mfma_f32_16x16x32_bf16 v[16:19], v[138:141], v[166:169], v[16:19]
	v_add_u32_e32 v138, 0x4000, v159
	v_add_u32_e32 v139, 0x6000, v159
	v_readfirstlane_b32 s27, v138
	v_mfma_f32_16x16x32_bf16 v[112:115], v[134:137], v[150:153], v[112:115]
	v_readfirstlane_b32 s34, v139
	s_mov_b32 m0, s27
	v_mfma_f32_16x16x32_bf16 v[4:7], v[134:137], v[154:157], v[4:7]
	v_mfma_f32_16x16x32_bf16 v[56:59], v[134:137], v[162:165], v[56:59]
	v_mfma_f32_16x16x32_bf16 v[8:11], v[134:137], v[166:169], v[8:11]
	v_lshl_add_u64 v[134:135], v[128:129], 0, s[12:13]
	v_lshl_add_u64 v[136:137], v[134:135], 0, s[38:39]
	s_mov_b64 s[38:39], 0x3bfc00c0
	v_lshl_add_u64 v[134:135], v[134:135], 0, s[38:39]
	global_load_lds_dwordx4 v[136:137], off
	s_mov_b32 m0, s34
	v_mfma_f32_16x16x32_bf16 v[44:47], v[142:145], v[150:153], v[44:47]
	global_load_lds_dwordx4 v[134:135], off
	s_add_u32 s12, s12, 64
	v_mfma_f32_16x16x32_bf16 v[20:23], v[142:145], v[154:157], v[20:23]
	s_addc_u32 s13, s13, 0
	s_add_i32 s17, s17, 0x8000
	s_cmpk_eq_i32 s12, 0x740
	v_mfma_f32_16x16x32_bf16 v[40:43], v[142:145], v[162:165], v[40:43]
	v_mfma_f32_16x16x32_bf16 v[24:27], v[142:145], v[166:169], v[24:27]
	v_mfma_f32_16x16x32_bf16 v[36:39], v[146:149], v[150:153], v[36:39]
	v_mfma_f32_16x16x32_bf16 v[28:31], v[146:149], v[154:157], v[28:31]
	v_mfma_f32_16x16x32_bf16 v[32:35], v[146:149], v[162:165], v[32:35]
	v_mfma_f32_16x16x32_bf16 v[0:3], v[146:149], v[166:169], v[0:3]
	s_cbranch_scc0 .LBB0_1312
	s_setprio 0
	s_waitcnt vmcnt(8)
	s_barrier
	v_add_u32_e32 v158, 0x8000, v132
	v_or_b32_e32 v159, 0x8000, v133
	ds_read_b128 v[128:131], v158
	ds_read_b128 v[134:137], v158 offset:1024
	ds_read_b128 v[138:141], v158 offset:2048
	ds_read_b128 v[142:145], v158 offset:3072
	ds_read_b128 v[146:149], v159
	ds_read_b128 v[150:153], v159 offset:1024
	ds_read_b128 v[154:157], v159 offset:2048
	ds_read_b128 v[162:165], v159 offset:3072
	s_waitcnt lgkmcnt(0)
	v_or_b32_e32 v159, 0x10000, v133
	v_mfma_f32_16x16x32_bf16 v[124:127], v[128:131], v[146:149], v[124:127]
	v_add_u32_e32 v178, 0x18000, v132
	v_and_b32_e32 v160, 63, v182
	v_lshrrev_b32_e32 v179, 6, v182
	v_mfma_f32_16x16x32_bf16 v[120:123], v[128:131], v[150:153], v[120:123]
	s_movk_i32 s12, 0x4400
	v_mfma_f32_16x16x32_bf16 v[116:119], v[128:131], v[154:157], v[116:119]
	v_mfma_f32_16x16x32_bf16 v[108:111], v[128:131], v[162:165], v[108:111]
	v_mfma_f32_16x16x32_bf16 v[104:107], v[134:137], v[146:149], v[104:107]
	v_mfma_f32_16x16x32_bf16 v[100:103], v[134:137], v[150:153], v[100:103]
	v_mfma_f32_16x16x32_bf16 v[96:99], v[134:137], v[154:157], v[96:99]
	v_mfma_f32_16x16x32_bf16 v[88:91], v[138:141], v[146:149], v[88:91]
	v_mfma_f32_16x16x32_bf16 v[84:87], v[138:141], v[150:153], v[84:87]
	v_mfma_f32_16x16x32_bf16 v[80:83], v[138:141], v[154:157], v[80:83]
	v_mfma_f32_16x16x32_bf16 v[76:79], v[138:141], v[162:165], v[76:79]
	v_mfma_f32_16x16x32_bf16 v[92:95], v[134:137], v[162:165], v[92:95]
	v_mfma_f32_16x16x32_bf16 v[72:75], v[142:145], v[146:149], v[72:75]
	v_mfma_f32_16x16x32_bf16 v[68:71], v[142:145], v[150:153], v[68:71]
	v_mfma_f32_16x16x32_bf16 v[64:67], v[142:145], v[154:157], v[64:67]
	v_mfma_f32_16x16x32_bf16 v[60:63], v[142:145], v[162:165], v[60:63]
	ds_read_b128 v[128:131], v158 offset:4096
	ds_read_b128 v[134:137], v158 offset:5120
	ds_read_b128 v[138:141], v158 offset:6144
	ds_read_b128 v[142:145], v158 offset:7168
	s_waitcnt lgkmcnt(0)
	s_waitcnt vmcnt(4)
	s_barrier
; #define ROW4(accv, r, av)                                                                              \
;     accv[r][0] = MFMA16(av, b0, accv[r][0]); accv[r][1] = MFMA16(av, b1, accv[r][1]);                      \
;     accv[r][2] = MFMA16(av, b2, accv[r][2]); accv[r][3] = MFMA16(av, b3, accv[r][3]);
; template <int EPI>
; __device__ __forceinline__ void gemm_tile_dma(const bft* __restrict__ A, int lda, const bft* __restrict__ Bt, int K, int row0, int col0,
;                                               char* smem, const EpiArgs& e) {
;     ...
;   for (int kt = 0; kt < nk; ++kt) {
;     if (kt + 2 < nk) asm volatile("s_waitcnt vmcnt(8)" ::: "memory");
;     else if (kt + 1 < nk) asm volatile("s_waitcnt vmcnt(4)" ::: "memory");
;     else asm volatile("s_waitcnt vmcnt(0)" ::: "memory");
;     __builtin_amdgcn_s_barrier();
;     asm volatile("" ::: "memory");
;     const bool pf = kt + 3 < nk;
;     const unsigned so = (unsigned)(kt & 3) * GST;
;     bf16x8 a0, a1, a2, a3, b0, b1, b2, b3;
;     asm volatile(
;         "ds_read_b128 %0, %8\n\t"
;         "ds_read_b128 %1, %8 offset:1024\n\t"
;         "ds_read_b128 %2, %8 offset:2048\n\t"
;         "ds_read_b128 %3, %8 offset:3072\n\t"
;         "ds_read_b128 %4, %9\n\t"
;         "ds_read_b128 %5, %9 offset:1024\n\t"
;         "ds_read_b128 %6, %9 offset:2048\n\t"
;         "ds_read_b128 %7, %9 offset:3072\n\t"
;         "s_waitcnt lgkmcnt(0)"
;         : "=&v"(a0), "=&v"(a1), "=&v"(a2), "=&v"(a3), "=&v"(b0), "=&v"(b1), "=&v"(b2), "=&v"(b3)
;         : "v"(lds_a + so), "v"(lds_b + so)
;         : "memory");
;     ...
;     ROW4(accL, 0, a0) ROW4(accL, 1, a1)
;     if (pf) GEMM_DMA_A(kt + 3)
;     ROW4(accL, 2, a2) ROW4(accL, 3, a3)
;     asm volatile(
;         "ds_read_b128 %0, %4 offset:4096\n\t"
;         "ds_read_b128 %1, %4 offset:5120\n\t"
;         "ds_read_b128 %2, %4 offset:6144\n\t"
;         "ds_read_b128 %3, %4 offset:7168\n\t"
;         "s_waitcnt lgkmcnt(0)"
;         : "=&v"(a0), "=&v"(a1), "=&v"(a2), "=&v"(a3)
;         : "v"(lds_a + so)
;         : "memory");
;     ROW4(accH, 0, a0) ROW4(accH, 1, a1)
;     if (pf) GEMM_DMA_B(kt + 3)
;     ROW4(accH, 2, a2) ROW4(accH, 3, a3)
	v_mfma_f32_16x16x32_bf16 v[112:115], v[128:131], v[146:149], v[112:115]
	v_add_u32_e32 v158, 0x10000, v132
	v_mfma_f32_16x16x32_bf16 v[4:7], v[128:131], v[150:153], v[4:7]
	v_mfma_f32_16x16x32_bf16 v[166:169], v[128:131], v[154:157], v[56:59]
	v_mfma_f32_16x16x32_bf16 v[8:11], v[128:131], v[162:165], v[8:11]
	v_mfma_f32_16x16x32_bf16 v[52:55], v[134:137], v[146:149], v[52:55]
	v_mfma_f32_16x16x32_bf16 v[12:15], v[134:137], v[150:153], v[12:15]
	v_mfma_f32_16x16x32_bf16 v[48:51], v[134:137], v[154:157], v[48:51]
	v_mfma_f32_16x16x32_bf16 v[16:19], v[134:137], v[162:165], v[16:19]
	v_mfma_f32_16x16x32_bf16 v[128:131], v[138:141], v[146:149], v[44:47]
	v_mfma_f32_16x16x32_bf16 v[20:23], v[138:141], v[150:153], v[20:23]
	v_mfma_f32_16x16x32_bf16 v[134:137], v[138:141], v[154:157], v[40:43]
	v_mfma_f32_16x16x32_bf16 v[24:27], v[138:141], v[162:165], v[24:27]
	v_mfma_f32_16x16x32_bf16 v[36:39], v[142:145], v[146:149], v[36:39]
	v_mfma_f32_16x16x32_bf16 v[28:31], v[142:145], v[150:153], v[28:31]
	v_mfma_f32_16x16x32_bf16 v[138:141], v[142:145], v[154:157], v[32:35]
	v_mfma_f32_16x16x32_bf16 v[32:35], v[142:145], v[162:165], v[0:3]
	ds_read_b128 v[0:3], v158
	ds_read_b128 v[56:59], v158 offset:1024
	ds_read_b128 v[142:145], v158 offset:2048
	ds_read_b128 v[146:149], v158 offset:3072
	ds_read_b128 v[150:153], v159
	ds_read_b128 v[44:47], v159 offset:1024
	ds_read_b128 v[154:157], v159 offset:2048
	ds_read_b128 v[40:43], v159 offset:3072
	s_waitcnt lgkmcnt(0)
	s_nop 0
	v_mfma_f32_16x16x32_bf16 v[124:127], v[0:3], v[150:153], v[124:127]
	v_mfma_f32_16x16x32_bf16 v[120:123], v[0:3], v[44:47], v[120:123]
	v_mfma_f32_16x16x32_bf16 v[116:119], v[0:3], v[154:157], v[116:119]
	v_mfma_f32_16x16x32_bf16 v[0:3], v[0:3], v[40:43], v[108:111]
	v_mfma_f32_16x16x32_bf16 v[104:107], v[56:59], v[150:153], v[104:107]
	v_mfma_f32_16x16x32_bf16 v[108:111], v[56:59], v[44:47], v[100:103]
	v_mfma_f32_16x16x32_bf16 v[96:99], v[56:59], v[154:157], v[96:99]
	v_mfma_f32_16x16x32_bf16 v[186:189], v[142:145], v[150:153], v[88:91]
	v_mfma_f32_16x16x32_bf16 v[190:193], v[142:145], v[44:47], v[84:87]
	v_mfma_f32_16x16x32_bf16 v[210:213], v[142:145], v[154:157], v[80:83]
	v_mfma_f32_16x16x32_bf16 v[214:217], v[142:145], v[40:43], v[76:79]
	v_mfma_f32_16x16x32_bf16 v[92:95], v[56:59], v[40:43], v[92:95]
	v_mfma_f32_16x16x32_bf16 v[226:229], v[146:149], v[154:157], v[64:67]
	ds_read_b128 v[84:87], v158 offset:4096
	ds_read_b128 v[76:79], v158 offset:5120
	ds_read_b128 v[64:67], v158 offset:6144
	ds_read_b128 v[56:59], v158 offset:7168
	s_waitcnt lgkmcnt(0)
	s_waitcnt vmcnt(0)
	s_barrier
	v_mfma_f32_16x16x32_bf16 v[218:221], v[146:149], v[150:153], v[72:75]
	v_mfma_f32_16x16x32_bf16 v[222:225], v[146:149], v[44:47], v[68:71]
	v_mfma_f32_16x16x32_bf16 v[230:233], v[146:149], v[40:43], v[60:63]
	v_mfma_f32_16x16x32_bf16 v[234:237], v[84:87], v[150:153], v[112:115]
	v_mfma_f32_16x16x32_bf16 v[238:241], v[76:79], v[150:153], v[52:55]
	v_mfma_f32_16x16x32_bf16 v[68:71], v[76:79], v[154:157], v[48:51]
	v_mfma_f32_16x16x32_bf16 v[242:245], v[64:67], v[150:153], v[128:131]
	v_mfma_f32_16x16x32_bf16 v[246:249], v[56:59], v[150:153], v[36:39]
	s_nop 1
	v_or_b32_e32 v128, 0x18000, v133
	ds_read_b128 v[36:39], v178
	ds_read_b128 v[48:51], v178 offset:1024
	ds_read_b128 v[112:115], v178 offset:2048
	ds_read_b128 v[198:201], v178 offset:3072
	ds_read_b128 v[206:209], v128
	ds_read_b128 v[88:91], v128 offset:1024
	ds_read_b128 v[100:103], v128 offset:2048
	ds_read_b128 v[52:55], v128 offset:3072
	s_waitcnt lgkmcnt(0)
	v_mfma_f32_16x16x32_bf16 v[60:63], v[84:87], v[154:157], v[166:169]
	v_mfma_f32_16x16x32_bf16 v[72:75], v[64:67], v[154:157], v[134:137]
	v_mfma_f32_16x16x32_bf16 v[80:83], v[56:59], v[154:157], v[138:141]
	v_mfma_f32_16x16x32_bf16 v[162:165], v[48:51], v[206:209], v[104:107]
	v_mfma_f32_16x16x32_bf16 v[156:159], v[48:51], v[88:91], v[108:111]
	v_mfma_f32_16x16x32_bf16 v[152:155], v[48:51], v[100:103], v[96:99]
	v_mfma_f32_16x16x32_bf16 v[144:147], v[112:115], v[206:209], v[186:189]
	v_mfma_f32_16x16x32_bf16 v[140:143], v[112:115], v[88:91], v[190:193]
	s_nop 1
	v_mul_lo_u32 v189, v179, s12
	s_mov_b32 s12, 0
	v_mfma_f32_16x16x32_bf16 v[136:139], v[112:115], v[100:103], v[210:213]
	v_bfe_u32 v191, v182, 2, 4
	v_and_b32_e32 v195, 12, v191
	v_mul_u32_u24_e32 v187, 0x110, v195
	v_mfma_f32_16x16x32_bf16 v[132:135], v[112:115], v[52:55], v[214:217]
	ds_read_b128 v[112:115], v178 offset:4096
	ds_read_b128 v[108:111], v178 offset:5120
	ds_read_b128 v[104:107], v178 offset:6144
	ds_read_b128 v[96:99], v178 offset:7168
	s_waitcnt lgkmcnt(0)
	v_and_b32_e32 v178, 0xc0, v182
	v_or_b32_e32 v190, s16, v178
	v_mfma_f32_16x16x32_bf16 v[202:205], v[36:39], v[206:209], v[124:127]
	s_waitcnt vmcnt(0) lgkmcnt(0)
	s_barrier
; template <int EPI>
; DI void epilogue_tile(const EpiArgs& e, int row0, int wrow, int wcol, f32x4 (&acc)[4][4], char* smem, const float* rsm, int wave, int lane,
;                       bool final_sync = true) {
;     ...
;       if constexpr (EPI == EPI_FF1) {
;         const float bb = e.bias[col];
; #pragma unroll
;         for (int j = 0; j < 4; ++j) { const float t = fmaxf(v[j] + bb, 0.f); v[j] = t * t; }
;       }
;       if (transposed) {
;         *(f32x4*)(stage + lcol * STG + lrow) = (f32x4){v[0], v[1], v[2], v[3]};
;       } else {
; #pragma unroll
;         for (int j = 0; j < 4; ++j) stage[(lrow + j) * STG + lcol] = v[j];
;       }
	v_mfma_f32_16x16x32_bf16 v[174:177], v[36:39], v[88:91], v[120:123]
	v_or_b32_e32 v211, 3, v191
	v_mfma_f32_16x16x32_bf16 v[170:173], v[36:39], v[100:103], v[116:119]
	v_mfma_f32_16x16x32_bf16 v[128:131], v[198:201], v[206:209], v[218:221]
	v_mfma_f32_16x16x32_bf16 v[124:127], v[198:201], v[88:91], v[222:225]
	v_mfma_f32_16x16x32_bf16 v[120:123], v[198:201], v[100:103], v[226:229]
	v_mfma_f32_16x16x32_bf16 v[116:119], v[198:201], v[52:55], v[230:233]
	v_or_b32_e32 v198, 48, v160
	v_or_b32_e32 v160, v190, v180
	v_lshlrev_b32_e32 v160, 2, v160
	global_load_dword v193, v160, s[10:11]
	v_lshl_add_u64 v[178:179], s[10:11], 0, v[160:161]
	v_mfma_f32_16x16x32_bf16 v[166:169], v[36:39], v[52:55], v[0:3]
	v_lshl_or_b32 v185, v198, 2, v189
	s_waitcnt vmcnt(0)
	v_add_f32_e32 v186, v204, v193
	v_max_f32_e32 v186, 0, v186
	v_mul_f32_e32 v188, v186, v186
	v_add_f32_e32 v186, v205, v193
	v_add_f32_e32 v160, v202, v193
	v_max_f32_e32 v186, 0, v186
	v_max_f32_e32 v160, 0, v160
	v_add_f32_e32 v181, v203, v193
	v_mul_f32_e32 v194, v186, v186
	v_lshl_or_b32 v186, v180, 2, v189
	v_mul_f32_e32 v160, v160, v160
	v_max_f32_e32 v181, 0, v181
	v_mad_u32_u24 v192, v195, s35, v186
	v_mul_f32_e32 v181, v181, v181
	ds_write_b32 v192, v160
	ds_write_b32 v192, v181 offset:272
	ds_write_b32 v192, v188 offset:544
	v_mad_u32_u24 v199, v211, s35, v186
	v_add_lshl_u32 v160, v190, v180, 2
	ds_write_b32 v199, v194
	global_load_dword v194, v160, s[10:11] offset:64
	v_lshl_add_u64 v[180:181], s[10:11], 0, v[160:161]
	v_mfma_f32_16x16x32_bf16 v[148:151], v[48:51], v[52:55], v[92:95]
	v_add_f32_e32 v162, v162, v193
	v_add_f32_e32 v163, v163, v193
	v_max_f32_e32 v162, 0, v162
	v_max_f32_e32 v163, 0, v163
	v_add_f32_e32 v164, v164, v193
	v_mul_f32_e32 v162, v162, v162
	v_mul_f32_e32 v163, v163, v163
	v_max_f32_e32 v164, 0, v164
	v_add_f32_e32 v165, v165, v193
	v_mul_f32_e32 v164, v164, v164
	v_max_f32_e32 v165, 0, v165
	v_mul_f32_e32 v165, v165, v165
	v_add_f32_e32 v144, v144, v193
	v_add_f32_e32 v145, v145, v193
	v_max_f32_e32 v144, 0, v144
	v_max_f32_e32 v145, 0, v145
	v_add_f32_e32 v146, v146, v193
	v_mul_f32_e32 v144, v144, v144
	v_mul_f32_e32 v145, v145, v145
	v_max_f32_e32 v146, 0, v146
	v_add_f32_e32 v147, v147, v193
	v_mul_f32_e32 v146, v146, v146
	v_max_f32_e32 v147, 0, v147
	v_mul_f32_e32 v147, v147, v147
	v_add_f32_e32 v128, v128, v193
	v_add_f32_e32 v129, v129, v193
	v_max_f32_e32 v128, 0, v128
	v_max_f32_e32 v129, 0, v129
	v_add_f32_e32 v130, v130, v193
	v_mul_f32_e32 v128, v128, v128
	v_mul_f32_e32 v129, v129, v129
	v_max_f32_e32 v130, 0, v130
	v_add_f32_e32 v131, v131, v193
	v_mul_f32_e32 v130, v130, v130
	v_max_f32_e32 v131, 0, v131
	v_mul_f32_e32 v131, v131, v131
	v_mfma_f32_16x16x32_bf16 v[92:95], v[112:115], v[206:209], v[234:237]
	v_mul_u32_u24_e32 v188, 0x110, v211
	s_waitcnt vmcnt(0)
	v_add_f32_e32 v174, v174, v194
	v_max_f32_e32 v174, 0, v174
	v_add_f32_e32 v175, v175, v194
	v_add_f32_e32 v176, v176, v194
	v_add_f32_e32 v177, v177, v194
	v_mul_f32_e32 v174, v174, v174
	v_max_f32_e32 v175, 0, v175
	v_max_f32_e32 v176, 0, v176
	v_max_f32_e32 v177, 0, v177
	v_mul_f32_e32 v175, v175, v175
	v_mul_f32_e32 v176, v176, v176
	v_mul_f32_e32 v177, v177, v177
	ds_write_b32 v192, v174 offset:64
	ds_write_b32 v192, v175 offset:336
	ds_write_b32 v192, v176 offset:608
	ds_write_b32 v199, v177 offset:64
	global_load_dword v174, v160, s[10:11] offset:128
	v_add_f32_e32 v156, v156, v194
	v_max_f32_e32 v156, 0, v156
	v_add_f32_e32 v157, v157, v194
	v_add_f32_e32 v158, v158, v194
	v_add_f32_e32 v159, v159, v194
	v_mul_f32_e32 v156, v156, v156
	v_max_f32_e32 v157, 0, v157
	v_max_f32_e32 v158, 0, v158
	v_max_f32_e32 v159, 0, v159
	v_mul_f32_e32 v157, v157, v157
	v_mul_f32_e32 v158, v158, v158
	v_mul_f32_e32 v159, v159, v159
	v_add_f32_e32 v140, v140, v194
	v_max_f32_e32 v140, 0, v140
	v_add_f32_e32 v141, v141, v194
	v_add_f32_e32 v142, v142, v194
	v_add_f32_e32 v143, v143, v194
	v_mul_f32_e32 v140, v140, v140
	v_max_f32_e32 v141, 0, v141
	v_max_f32_e32 v142, 0, v142
	v_max_f32_e32 v143, 0, v143
	v_mul_f32_e32 v141, v141, v141
	v_mul_f32_e32 v142, v142, v142
	v_mul_f32_e32 v143, v143, v143
	v_add_f32_e32 v124, v124, v194
	v_max_f32_e32 v124, 0, v124
	v_add_f32_e32 v125, v125, v194
	v_add_f32_e32 v126, v126, v194
	v_add_f32_e32 v127, v127, v194
	v_mul_f32_e32 v124, v124, v124
	v_max_f32_e32 v125, 0, v125
	v_max_f32_e32 v126, 0, v126
	v_max_f32_e32 v127, 0, v127
	v_mul_f32_e32 v125, v125, v125
	v_mul_f32_e32 v126, v126, v126
	v_mul_f32_e32 v127, v127, v127
	v_mfma_f32_16x16x32_bf16 v[48:51], v[108:111], v[206:209], v[238:241]
	s_waitcnt vmcnt(0)
; template <int EPI>
; DI void epilogue_tile(const EpiArgs& e, int row0, int wrow, int wcol, f32x4 (&acc)[4][4], char* smem, const float* rsm, int wave, int lane,
;                       bool final_sync = true) {
;     ...
;       if constexpr (EPI == EPI_FF1) {
;         const float bb = e.bias[col];
; #pragma unroll
;         for (int j = 0; j < 4; ++j) { const float t = fmaxf(v[j] + bb, 0.f); v[j] = t * t; }
;       }
;       if (transposed) {
;         *(f32x4*)(stage + lcol * STG + lrow) = (f32x4){v[0], v[1], v[2], v[3]};
;       } else {
; #pragma unroll
;         for (int j = 0; j < 4; ++j) stage[(lrow + j) * STG + lcol] = v[j];
;       }
;     }
;   const int rr = lane >> 3, c8 = (lane & 7) * 8;
; #pragma unroll 4
;   for (int it = 0; it < 8; ++it) {
;     const int sr = it * 8 + rr;
;     const f32x4 v0 = *(const f32x4*)(stage + sr * STG + c8);
;     const f32x4 v1 = *(const f32x4*)(stage + sr * STG + c8 + 4);
;     if constexpr (EPI == EPI_RES) {
;       bft* px = (bft*)(e.ws + OFF_XS) + (size_t)(wrow + sr) * D + wcol + c8;
	v_add_f32_e32 v160, v170, v174
	v_max_f32_e32 v160, 0, v160
	v_add_f32_e32 v170, v171, v174
	v_add_f32_e32 v171, v172, v174
	v_add_f32_e32 v172, v173, v174
	v_mul_f32_e32 v160, v160, v160
	v_max_f32_e32 v170, 0, v170
	v_max_f32_e32 v171, 0, v171
	v_max_f32_e32 v172, 0, v172
	v_mul_f32_e32 v170, v170, v170
	v_mul_f32_e32 v171, v171, v171
	v_mul_f32_e32 v172, v172, v172
	ds_write_b32 v192, v160 offset:128
	ds_write_b32 v192, v170 offset:400
	ds_write_b32 v192, v171 offset:672
	ds_write_b32 v199, v172 offset:128
	v_or_b32_e32 v160, v190, v198
	v_lshlrev_b32_e32 v160, 2, v160
	v_lshl_add_u64 v[170:171], s[10:11], 0, v[160:161]
	global_load_dword v160, v160, s[10:11]
	v_mad_u32_u24 v172, v195, s35, v185
	v_add_f32_e32 v152, v152, v174
	v_max_f32_e32 v152, 0, v152
	v_add_f32_e32 v153, v153, v174
	v_add_f32_e32 v154, v154, v174
	v_add_f32_e32 v155, v155, v174
	v_mul_f32_e32 v152, v152, v152
	v_max_f32_e32 v153, 0, v153
	v_max_f32_e32 v154, 0, v154
	v_max_f32_e32 v155, 0, v155
	v_mul_f32_e32 v153, v153, v153
	v_mul_f32_e32 v154, v154, v154
	v_mul_f32_e32 v155, v155, v155
	v_add_f32_e32 v136, v136, v174
	v_max_f32_e32 v136, 0, v136
	v_add_f32_e32 v137, v137, v174
	v_add_f32_e32 v138, v138, v174
	v_add_f32_e32 v139, v139, v174
	v_mul_f32_e32 v136, v136, v136
	v_max_f32_e32 v137, 0, v137
	v_max_f32_e32 v138, 0, v138
	v_max_f32_e32 v139, 0, v139
	v_mul_f32_e32 v137, v137, v137
	v_mul_f32_e32 v138, v138, v138
	v_mul_f32_e32 v139, v139, v139
	v_add_f32_e32 v120, v120, v174
	v_max_f32_e32 v120, 0, v120
	v_add_f32_e32 v121, v121, v174
	v_add_f32_e32 v122, v122, v174
	v_add_f32_e32 v123, v123, v174
	v_mul_f32_e32 v120, v120, v120
	v_max_f32_e32 v121, 0, v121
	v_max_f32_e32 v122, 0, v122
	v_max_f32_e32 v123, 0, v123
	v_mul_f32_e32 v121, v121, v121
	v_mul_f32_e32 v122, v122, v122
	v_mul_f32_e32 v123, v123, v123
	v_mfma_f32_16x16x32_bf16 v[36:39], v[104:107], v[206:209], v[242:245]
	s_waitcnt vmcnt(0)
	v_add_f32_e32 v166, v166, v160
	v_add_f32_e32 v167, v167, v160
	v_max_f32_e32 v166, 0, v166
	v_max_f32_e32 v167, 0, v167
	v_add_f32_e32 v168, v168, v160
	v_add_f32_e32 v169, v169, v160
	v_mul_f32_e32 v166, v166, v166
	v_mul_f32_e32 v167, v167, v167
	v_max_f32_e32 v168, 0, v168
	v_max_f32_e32 v169, 0, v169
	v_mul_f32_e32 v168, v168, v168
	v_mul_f32_e32 v169, v169, v169
	ds_write2_b32 v172, v166, v167 offset1:68
	ds_write_b32 v172, v168 offset:544
	v_mad_u32_u24 v166, v211, s35, v185
	ds_write_b32 v166, v169
	ds_write_b32 v192, v162 offset:4352
	ds_write_b32 v192, v163 offset:4624
	ds_write_b32 v192, v164 offset:4896
	v_or_b32_e32 v163, 19, v191
	v_add_f32_e32 v148, v148, v160
	v_add_f32_e32 v149, v149, v160
	v_mad_u32_u24 v164, v163, s35, v186
	v_max_f32_e32 v148, 0, v148
	v_max_f32_e32 v149, 0, v149
	v_add_f32_e32 v150, v150, v160
	v_add_f32_e32 v151, v151, v160
	ds_write_b32 v164, v165
	ds_write_b32 v192, v156 offset:4416
	ds_write_b32 v192, v157 offset:4688
	ds_write_b32 v192, v158 offset:4960
	ds_write_b32 v164, v159 offset:64
	ds_write_b32 v192, v152 offset:4480
	ds_write_b32 v192, v153 offset:4752
	ds_write_b32 v192, v154 offset:5024
	ds_write_b32 v164, v155 offset:128
	v_mul_f32_e32 v148, v148, v148
	v_mul_f32_e32 v149, v149, v149
	v_max_f32_e32 v150, 0, v150
	v_max_f32_e32 v151, 0, v151
	v_add_u32_e32 v152, 0x1000, v172
	v_mul_f32_e32 v150, v150, v150
	v_mul_f32_e32 v151, v151, v151
	ds_write2_b32 v152, v148, v149 offset0:64 offset1:132
	ds_write_b32 v172, v150 offset:4896
	v_mad_u32_u24 v148, v163, s35, v185
	ds_write_b32 v148, v151
	ds_write_b32 v192, v144 offset:8704
	ds_write_b32 v192, v145 offset:8976
	ds_write_b32 v192, v146 offset:9248
	v_or_b32_e32 v145, 35, v191
	v_add_f32_e32 v132, v132, v160
	v_add_f32_e32 v133, v133, v160
	v_mad_u32_u24 v146, v145, s35, v186
	v_max_f32_e32 v132, 0, v132
	v_max_f32_e32 v133, 0, v133
	v_add_f32_e32 v134, v134, v160
	v_add_f32_e32 v135, v135, v160
	ds_write_b32 v146, v147
	ds_write_b32 v192, v140 offset:8768
	ds_write_b32 v192, v141 offset:9040
	ds_write_b32 v192, v142 offset:9312
	ds_write_b32 v146, v143 offset:64
	ds_write_b32 v192, v136 offset:8832
	ds_write_b32 v192, v137 offset:9104
	ds_write_b32 v192, v138 offset:9376
	ds_write_b32 v146, v139 offset:128
	v_mul_f32_e32 v132, v132, v132
	v_mul_f32_e32 v133, v133, v133
	v_max_f32_e32 v134, 0, v134
	v_max_f32_e32 v135, 0, v135
	v_add_u32_e32 v136, 0x2000, v172
	v_mul_f32_e32 v134, v134, v134
	v_mul_f32_e32 v135, v135, v135
	ds_write2_b32 v136, v132, v133 offset0:128 offset1:196
	ds_write_b32 v172, v134 offset:9248
	v_mad_u32_u24 v132, v145, s35, v185
	ds_write_b32 v132, v135
	ds_write_b32 v192, v128 offset:13056
	ds_write_b32 v192, v129 offset:13328
	ds_write_b32 v192, v130 offset:13600
	v_or_b32_e32 v129, 51, v191
	v_add_f32_e32 v116, v116, v160
	v_add_f32_e32 v117, v117, v160
	v_mad_u32_u24 v130, v129, s35, v186
	v_max_f32_e32 v116, 0, v116
	v_max_f32_e32 v117, 0, v117
	v_add_f32_e32 v118, v118, v160
	v_add_f32_e32 v119, v119, v160
	ds_write_b32 v130, v131
	ds_write_b32 v192, v124 offset:13120
	ds_write_b32 v192, v125 offset:13392
	ds_write_b32 v192, v126 offset:13664
	ds_write_b32 v130, v127 offset:64
	ds_write_b32 v192, v120 offset:13184
	ds_write_b32 v192, v121 offset:13456
	ds_write_b32 v192, v122 offset:13728
	ds_write_b32 v130, v123 offset:128
	v_mul_f32_e32 v116, v116, v116
	v_mul_f32_e32 v117, v117, v117
	v_max_f32_e32 v118, 0, v118
	v_max_f32_e32 v119, 0, v119
	v_add_u32_e32 v120, 0x3200, v172
	v_mul_f32_e32 v118, v118, v118
	v_mul_f32_e32 v119, v119, v119
	ds_write2_b32 v120, v116, v117 offset0:64 offset1:132
	ds_write_b32 v172, v118 offset:13600
	v_mad_u32_u24 v116, v129, s35, v185
	v_mfma_f32_16x16x32_bf16 v[0:3], v[96:99], v[206:209], v[246:249]
	ds_write_b32 v116, v119
	v_bfe_u32 v119, v182, 3, 3
	v_and_b32_e32 v120, 7, v182
	v_lshlrev_b32_e32 v160, 1, v190
	v_add3_u32 v118, v119, s15, v183
	v_mul_u32_u24_e32 v119, 0x110, v119
	v_lshlrev_b32_e32 v120, 5, v120
	v_lshl_add_u64 v[116:117], s[56:57], 0, v[160:161]
	v_and_b32_e32 v160, 0x70, v184
	v_add3_u32 v119, v189, v119, v120
	v_mul_u32_u24_e32 v162, 0x110, v163
	v_mul_u32_u24_e32 v144, 0x110, v145
	v_mul_u32_u24_e32 v128, 0x110, v129
	v_lshl_add_u64 v[116:117], v[116:117], 0, v[160:161]
	v_mov_b32_e32 v120, v119

; DI int otid() { int t = threadIdx.x; asm volatile("" : "+v"(t)); return t; }
; #define GEMM_DMA(kt) { GEMM_DMA_A(kt) GEMM_DMA_B(kt) }
; template <int EPI>
; __device__ __forceinline__ void gemm_tile_dma(const bft* __restrict__ A, int lda, const bft* __restrict__ Bt, int K, int row0, int col0,
;                                               char* smem, const EpiArgs& e) {
;   const int tid = otid(), wave = tid >> 6, lane = tid & 63;
;   const int wm = wave >> 2, wn = wave & 3, r16 = lane & 15, g = lane >> 4;
;   f32x4 accL[4][4], accH[4][4];
; #pragma unroll
;   for (int i = 0; i < 4; ++i)
; #pragma unroll
;     for (int j = 0; j < 4; ++j) { accL[i][j] = (f32x4){0.f, 0.f, 0.f, 0.f}; accH[i][j] = (f32x4){0.f, 0.f, 0.f, 0.f}; }
;   const int lr = tid >> 2, pc = tid & 3;
;   const int kcs = (pc ^ ((4 - ((lr >> 2) & 3)) & 3)) * 8;
;   const int rco = (g ^ ((4 - ((r16 >> 2) & 3)) & 3)) * 8;
;   const bft* ag = A + (size_t)(row0 + lr) * lda + kcs;
;   const bft* bg = Bt + (size_t)(col0 + lr) * K + kcs;
;   const unsigned lds_a = (unsigned)(size_t)smem + (unsigned)(((wm * 128 + r16) * 32 + rco) * 2);
;   const unsigned lds_b = (unsigned)(size_t)smem + 16384u + (unsigned)(((wn * 64 + r16) * 32 + rco) * 2);
;   const int nk = K / 32;
;     ...
;   GEMM_DMA(0);
;   GEMM_DMA(1);
;   GEMM_DMA(2);
; template <int EPI, bool RMS>
; __device__ __forceinline__ void gemm_phase(const bft* A, int lda, const bft* Bt, int K, int ntn, char* smem, const EpiArgs& e) {
;     ...
;   for (int idx = loc; idx < per; idx += G8) {
;     const int grp = idx / (8 * ntn);
;     const int within = idx - grp * (8 * ntn);
;     const int rig = (grp < RT / 8) ? 8 : RT % 8;
;     const int tm = xcd * RT + grp * 8 + within % rig, tn = within / rig;
;     if constexpr (RMS) gemm_tile<EPI, RMS>(A, lda, Bt, K, tm * 256, tn * 128, smem, e);
;     else gemm_tile_dma<EPI>(A, lda, Bt, K, tm * 256, tn * 256, smem, e);
.LBB0_1327:
	s_lshr_b32 s13, s14, 2
	s_and_b32 s12, s14, 31
	s_and_b32 s13, s13, 56
	s_cmpk_lt_u32 s14, 0x80
	s_cselect_b32 s15, 7, 1
	s_cselect_b32 s17, 3, 1
	s_and_b32 s15, s15, s14
	s_add_i32 s16, s3, s15
	s_add_i32 s16, s16, s13
	v_mov_b32_e32 v188, v196
	s_lshl_b32 s15, s16, 8
	s_lshr_b32 s12, s12, s17
	v_ashrrev_i32_e32 v4, 2, v188
	v_lshrrev_b32_e32 v0, 4, v188
	v_sub_u32_e32 v10, 0, v0
	v_add_u32_e32 v0, s15, v4
	v_xor_b32_e32 v5, v188, v10
	v_ashrrev_i32_e32 v1, 31, v0
	v_lshlrev_b64 v[0:1], 13, v[0:1]
	v_lshlrev_b32_e32 v5, 4, v5
	v_lshlrev_b32_e32 v190, 4, v188
	s_lshl_b32 s17, s12, 8
	v_lshl_add_u64 v[2:3], s[56:57], 0, v[0:1]
	v_and_b32_e32 v160, 48, v5
	v_readfirstlane_b32 s12, v190
	v_add_u32_e32 v11, 0x2000, v190
	v_lshl_add_u64 v[2:3], v[2:3], 0, v[160:161]
	v_add_u32_e32 v4, s17, v4
	v_ashrrev_i32_e32 v8, 1, v188
	s_mov_b32 m0, s12
	s_mov_b64 s[38:39], 0x100000
	v_readfirstlane_b32 s12, v11
	v_ashrrev_i32_e32 v5, 31, v4
	v_and_b32_e32 v189, 0xffffff80, v8
	global_load_lds_dwordx4 v[2:3], off
	v_lshl_add_u64 v[8:9], v[2:3], 0, s[38:39]
	s_mov_b32 m0, s12
	v_lshlrev_b64 v[4:5], 13, v[4:5]
	global_load_lds_dwordx4 v[8:9], off
	v_add_u32_e32 v8, 0x4000, v190
	v_lshl_add_u64 v[6:7], s[24:25], 0, v[4:5]
	v_readfirstlane_b32 s12, v8
	v_add_u32_e32 v11, 0x6000, v190
	v_lshl_add_u64 v[6:7], v[6:7], 0, v[160:161]
	s_mov_b32 m0, s12
	v_readfirstlane_b32 s12, v11
	v_add_u32_e32 v11, 0x8000, v190
	global_load_lds_dwordx4 v[6:7], off
	v_lshl_add_u64 v[8:9], v[6:7], 0, s[38:39]
	s_mov_b32 m0, s12
	v_readfirstlane_b32 s12, v11
	v_add_u32_e32 v11, 0xa000, v190
	global_load_lds_dwordx4 v[8:9], off
	v_lshl_add_u64 v[8:9], v[2:3], 0, 64
	s_mov_b32 m0, s12
	s_mov_b64 s[38:39], 0x100040
	v_readfirstlane_b32 s12, v11
	v_add_u32_e32 v11, 0xc000, v190
	global_load_lds_dwordx4 v[8:9], off
	v_lshl_add_u64 v[8:9], v[2:3], 0, s[38:39]
	s_mov_b32 m0, s12
	v_readfirstlane_b32 s12, v11
	v_add_u32_e32 v11, 0xe000, v190
	global_load_lds_dwordx4 v[8:9], off
	v_lshl_add_u64 v[8:9], v[6:7], 0, 64
	s_mov_b32 m0, s12
	v_readfirstlane_b32 s12, v11
	v_add_u32_e32 v11, 0x10000, v190
	global_load_lds_dwordx4 v[8:9], off
	v_lshl_add_u64 v[8:9], v[6:7], 0, s[38:39]
	s_mov_b32 m0, s12
	s_mov_b64 s[38:39], 0x80
	v_readfirstlane_b32 s12, v11
	global_load_lds_dwordx4 v[8:9], off
	v_lshl_add_u64 v[8:9], v[2:3], 0, s[38:39]
	s_mov_b32 m0, s12
	s_mov_b64 s[40:41], 0x100080
	global_load_lds_dwordx4 v[8:9], off
	v_add_u32_e32 v8, 0x12000, v190
	v_lshl_add_u64 v[2:3], v[2:3], 0, s[40:41]
	v_readfirstlane_b32 s12, v8
	v_add_u32_e32 v8, 0x14000, v190
	s_mov_b32 m0, s12
	v_readfirstlane_b32 s12, v8
	global_load_lds_dwordx4 v[2:3], off
	v_lshl_add_u64 v[2:3], v[6:7], 0, s[38:39]
	s_mov_b32 m0, s12
	v_and_b32_e32 v182, 15, v188
	global_load_lds_dwordx4 v[2:3], off
	v_lshl_add_u64 v[2:3], v[6:7], 0, s[40:41]
	v_add_u32_e32 v6, 0x16000, v190
	v_mov_b32_e32 v28, 0
	v_readfirstlane_b32 s12, v6
	s_mov_b32 m0, s12
	v_lshlrev_b32_e32 v6, 6, v188
	global_load_lds_dwordx4 v[2:3], off
	v_lshlrev_b32_e32 v2, 2, v188
	v_and_b32_e32 v2, 48, v2
	v_sub_u32_e32 v2, 0, v2
	v_bitop3_b32 v2, v188, 48, v2 bitop3:0x48
	v_or_b32_e32 v3, v189, v182
	v_and_b32_e32 v6, 0x33c0, v6
	v_lshl_or_b32 v133, v3, 6, v2
	v_or3_b32 v132, v6, v2, s42
	v_bitop3_b32 v2, v188, 3, v10 bitop3:0x48
	v_lshlrev_b32_e32 v2, 4, v2
	v_or_b32_e32 v4, v4, v2
	v_or_b32_e32 v0, v0, v2
	v_mov_b32_e32 v237, 0x2200
	v_not_b32_e32 v236, 63
	v_mov_b32_e32 v235, 0x42800000
	v_mov_b32_e32 v234, 0x22000
	s_mov_b32 s27, 0
	s_waitcnt vmcnt(0)
	v_lshl_add_u64 v[128:129], s[90:91], 0, v[4:5]
	v_lshl_add_u64 v[130:131], s[90:91], 0, v[0:1]
	s_mov_b64 s[12:13], 0
	v_mov_b32_e32 v29, v28
	v_mov_b32_e32 v30, v28
	v_mov_b32_e32 v31, v28
	v_mov_b32_e32 v32, v28
	v_mov_b32_e32 v33, v28
	v_mov_b32_e32 v34, v28
	v_mov_b32_e32 v35, v28
	v_mov_b32_e32 v24, v28
	v_mov_b32_e32 v25, v28
	v_mov_b32_e32 v26, v28
	v_mov_b32_e32 v27, v28
	v_mov_b32_e32 v36, v28
	v_mov_b32_e32 v37, v28
	v_mov_b32_e32 v38, v28
	v_mov_b32_e32 v39, v28
	v_mov_b32_e32 v20, v28
	v_mov_b32_e32 v21, v28
	v_mov_b32_e32 v22, v28
	v_mov_b32_e32 v23, v28
	v_mov_b32_e32 v40, v28
	v_mov_b32_e32 v41, v28
	v_mov_b32_e32 v42, v28
	v_mov_b32_e32 v43, v28
	v_mov_b32_e32 v16, v28
	v_mov_b32_e32 v17, v28
	v_mov_b32_e32 v18, v28
	v_mov_b32_e32 v19, v28
	v_mov_b32_e32 v44, v28
	v_mov_b32_e32 v45, v28
	v_mov_b32_e32 v46, v28
	v_mov_b32_e32 v47, v28
	v_mov_b32_e32 v12, v28
	v_mov_b32_e32 v13, v28
	v_mov_b32_e32 v14, v28
	v_mov_b32_e32 v15, v28
	v_mov_b32_e32 v48, v28
	v_mov_b32_e32 v49, v28
	v_mov_b32_e32 v50, v28
	v_mov_b32_e32 v51, v28
	v_mov_b32_e32 v8, v28
	v_mov_b32_e32 v9, v28
	v_mov_b32_e32 v10, v28
	v_mov_b32_e32 v11, v28
	v_mov_b32_e32 v52, v28
	v_mov_b32_e32 v53, v28
	v_mov_b32_e32 v54, v28
	v_mov_b32_e32 v55, v28
	v_mov_b32_e32 v4, v28
	v_mov_b32_e32 v5, v28
	v_mov_b32_e32 v6, v28
	v_mov_b32_e32 v7, v28
	v_mov_b32_e32 v56, v28
	v_mov_b32_e32 v57, v28
	v_mov_b32_e32 v58, v28
	v_mov_b32_e32 v59, v28
	v_mov_b32_e32 v0, v28
	v_mov_b32_e32 v1, v28
	v_mov_b32_e32 v2, v28
	v_mov_b32_e32 v3, v28
	v_mov_b32_e32 v60, v28
	v_mov_b32_e32 v61, v28
	v_mov_b32_e32 v62, v28
	v_mov_b32_e32 v63, v28
	v_mov_b32_e32 v64, v28
	v_mov_b32_e32 v65, v28
	v_mov_b32_e32 v66, v28
	v_mov_b32_e32 v67, v28
	v_mov_b32_e32 v68, v28
	v_mov_b32_e32 v69, v28
	v_mov_b32_e32 v70, v28
	v_mov_b32_e32 v71, v28
	v_mov_b32_e32 v72, v28
	v_mov_b32_e32 v73, v28
	v_mov_b32_e32 v74, v28
	v_mov_b32_e32 v75, v28
	v_mov_b32_e32 v76, v28
	v_mov_b32_e32 v77, v28
	v_mov_b32_e32 v78, v28
	v_mov_b32_e32 v79, v28
	v_mov_b32_e32 v80, v28
	v_mov_b32_e32 v81, v28
	v_mov_b32_e32 v82, v28
	v_mov_b32_e32 v83, v28
	v_mov_b32_e32 v84, v28
	v_mov_b32_e32 v85, v28
	v_mov_b32_e32 v86, v28
	v_mov_b32_e32 v87, v28
	v_mov_b32_e32 v88, v28
	v_mov_b32_e32 v89, v28
	v_mov_b32_e32 v90, v28
	v_mov_b32_e32 v91, v28
	v_mov_b32_e32 v92, v28
	v_mov_b32_e32 v93, v28
	v_mov_b32_e32 v94, v28
	v_mov_b32_e32 v95, v28
	v_mov_b32_e32 v96, v28
	v_mov_b32_e32 v97, v28
	v_mov_b32_e32 v98, v28
	v_mov_b32_e32 v99, v28
	v_mov_b32_e32 v100, v28
	v_mov_b32_e32 v101, v28
	v_mov_b32_e32 v102, v28
	v_mov_b32_e32 v103, v28
	v_mov_b32_e32 v104, v28
	v_mov_b32_e32 v105, v28
	v_mov_b32_e32 v106, v28
	v_mov_b32_e32 v107, v28
	v_mov_b32_e32 v108, v28
	v_mov_b32_e32 v109, v28
	v_mov_b32_e32 v110, v28
	v_mov_b32_e32 v111, v28
	v_mov_b32_e32 v116, v28
	v_mov_b32_e32 v117, v28
	v_mov_b32_e32 v118, v28
	v_mov_b32_e32 v119, v28
	v_mov_b32_e32 v120, v28
	v_mov_b32_e32 v121, v28
	v_mov_b32_e32 v122, v28
	v_mov_b32_e32 v123, v28
	v_mov_b32_e32 v124, v28
	v_mov_b32_e32 v125, v28
	v_mov_b32_e32 v126, v28
	v_mov_b32_e32 v127, v28
	v_mov_b32_e32 v112, v28
	v_mov_b32_e32 v113, v28
	v_mov_b32_e32 v114, v28
	v_mov_b32_e32 v115, v28
	s_getreg_b32 s32, hwreg(HW_REG_HW_ID, 0, 1)
	s_cmp_eq_u32 s32, 1
	s_cbranch_scc0 .Lgprio0_skip
	s_setprio 1
; #define ROW4(accv, r, av)                                                                              \
;     accv[r][0] = MFMA16(av, b0, accv[r][0]); accv[r][1] = MFMA16(av, b1, accv[r][1]);                      \
;     accv[r][2] = MFMA16(av, b2, accv[r][2]); accv[r][3] = MFMA16(av, b3, accv[r][3]);
; template <int EPI>
; __device__ __forceinline__ void gemm_tile_dma(const bft* __restrict__ A, int lda, const bft* __restrict__ Bt, int K, int row0, int col0,
;                                               char* smem, const EpiArgs& e) {
;     ...
;   for (int kt = 0; kt < nk; ++kt) {
;     if (kt + 2 < nk) asm volatile("s_waitcnt vmcnt(8)" ::: "memory");
;     else if (kt + 1 < nk) asm volatile("s_waitcnt vmcnt(4)" ::: "memory");
;     else asm volatile("s_waitcnt vmcnt(0)" ::: "memory");
;     __builtin_amdgcn_s_barrier();
;     asm volatile("" ::: "memory");
;     const bool pf = kt + 3 < nk;
;     const unsigned so = (unsigned)(kt & 3) * GST;
;     bf16x8 a0, a1, a2, a3, b0, b1, b2, b3;
;     asm volatile(
;         "ds_read_b128 %0, %8\n\t"
;         "ds_read_b128 %1, %8 offset:1024\n\t"
;         "ds_read_b128 %2, %8 offset:2048\n\t"
;         "ds_read_b128 %3, %8 offset:3072\n\t"
;         "ds_read_b128 %4, %9\n\t"
;         "ds_read_b128 %5, %9 offset:1024\n\t"
;         "ds_read_b128 %6, %9 offset:2048\n\t"
;         "ds_read_b128 %7, %9 offset:3072\n\t"
;         "s_waitcnt lgkmcnt(0)"
;         : "=&v"(a0), "=&v"(a1), "=&v"(a2), "=&v"(a3), "=&v"(b0), "=&v"(b1), "=&v"(b2), "=&v"(b3)
;         : "v"(lds_a + so), "v"(lds_b + so)
;         : "memory");
;     ...
;     ROW4(accL, 0, a0) ROW4(accL, 1, a1)
;     if (pf) GEMM_DMA_A(kt + 3)
;     ROW4(accL, 2, a2) ROW4(accL, 3, a3)
;     asm volatile(
;         "ds_read_b128 %0, %4 offset:4096\n\t"
;         "ds_read_b128 %1, %4 offset:5120\n\t"
;         "ds_read_b128 %2, %4 offset:6144\n\t"
;         "ds_read_b128 %3, %4 offset:7168\n\t"
;         "s_waitcnt lgkmcnt(0)"
;         : "=&v"(a0), "=&v"(a1), "=&v"(a2), "=&v"(a3)
;         : "v"(lds_a + so)
;         : "memory");
;     ROW4(accH, 0, a0) ROW4(accH, 1, a1)
;     if (pf) GEMM_DMA_B(kt + 3)
;     ROW4(accH, 2, a2) ROW4(accH, 3, a3)
.Lgprio0_skip:
.LBB0_1328:
	s_and_b32 s34, s27, 0x18000
	s_waitcnt vmcnt(8)
	s_barrier
	v_add_u32_e32 v158, s34, v133
	v_or_b32_e32 v159, s34, v132
	s_add_i32 s34, s27, 0x18000
	ds_read_b128 v[134:137], v158
	ds_read_b128 v[138:141], v158 offset:1024
	ds_read_b128 v[142:145], v158 offset:2048
	ds_read_b128 v[146:149], v158 offset:3072
	ds_read_b128 v[150:153], v159
	ds_read_b128 v[154:157], v159 offset:1024
	ds_read_b128 v[162:165], v159 offset:2048
	ds_read_b128 v[166:169], v159 offset:3072
	s_waitcnt lgkmcnt(0)
	s_and_b32 s34, s34, 0x18000
	v_mfma_f32_16x16x32_bf16 v[124:127], v[134:137], v[150:153], v[124:127]
	s_mov_b64 s[38:39], 0x198000c0
	v_add_u32_e32 v159, s34, v190
	v_mfma_f32_16x16x32_bf16 v[120:123], v[134:137], v[154:157], v[120:123]
	v_readfirstlane_b32 s34, v159
	s_mov_b32 m0, s34
	v_mfma_f32_16x16x32_bf16 v[116:119], v[134:137], v[162:165], v[116:119]
	v_mfma_f32_16x16x32_bf16 v[108:111], v[134:137], v[166:169], v[108:111]
	v_lshl_add_u64 v[134:135], v[130:131], 0, s[12:13]
	v_lshl_add_u64 v[136:137], v[134:135], 0, s[38:39]
	s_mov_b64 s[38:39], 0x199000c0
	v_mfma_f32_16x16x32_bf16 v[104:107], v[138:141], v[150:153], v[104:107]
	v_lshl_add_u64 v[134:135], v[134:135], 0, s[38:39]
	global_load_lds_dwordx4 v[136:137], off
	v_mfma_f32_16x16x32_bf16 v[100:103], v[138:141], v[154:157], v[100:103]
	v_mfma_f32_16x16x32_bf16 v[96:99], v[138:141], v[162:165], v[96:99]
	v_mfma_f32_16x16x32_bf16 v[92:95], v[138:141], v[166:169], v[92:95]
	v_add_u32_e32 v138, 0x2000, v159
	s_nop 0
	v_readfirstlane_b32 s38, v138
	s_mov_b32 m0, s38
	v_mfma_f32_16x16x32_bf16 v[88:91], v[142:145], v[150:153], v[88:91]
	global_load_lds_dwordx4 v[134:135], off
	s_mov_b64 s[38:39], 0x3c7800c0
	v_mfma_f32_16x16x32_bf16 v[84:87], v[142:145], v[154:157], v[84:87]
	v_mfma_f32_16x16x32_bf16 v[80:83], v[142:145], v[162:165], v[80:83]
	v_mfma_f32_16x16x32_bf16 v[76:79], v[142:145], v[166:169], v[76:79]
	v_mfma_f32_16x16x32_bf16 v[72:75], v[146:149], v[150:153], v[72:75]
	v_mfma_f32_16x16x32_bf16 v[68:71], v[146:149], v[154:157], v[68:71]
	v_mfma_f32_16x16x32_bf16 v[64:67], v[146:149], v[162:165], v[64:67]
	v_mfma_f32_16x16x32_bf16 v[60:63], v[146:149], v[166:169], v[60:63]
	ds_read_b128 v[134:137], v158 offset:4096
	ds_read_b128 v[138:141], v158 offset:5120
	ds_read_b128 v[142:145], v158 offset:6144
	ds_read_b128 v[146:149], v158 offset:7168
	s_waitcnt lgkmcnt(0)
	s_nop 0
	v_mfma_f32_16x16x32_bf16 v[112:115], v[134:137], v[150:153], v[112:115]
	v_mfma_f32_16x16x32_bf16 v[0:3], v[134:137], v[154:157], v[0:3]
	v_mfma_f32_16x16x32_bf16 v[56:59], v[134:137], v[162:165], v[56:59]
	v_mfma_f32_16x16x32_bf16 v[4:7], v[134:137], v[166:169], v[4:7]
	v_lshl_add_u64 v[134:135], v[128:129], 0, s[12:13]
	v_lshl_add_u64 v[136:137], v[134:135], 0, s[38:39]
	s_mov_b64 s[38:39], 0x3c8800c0
	v_mfma_f32_16x16x32_bf16 v[52:55], v[138:141], v[150:153], v[52:55]
	v_lshl_add_u64 v[134:135], v[134:135], 0, s[38:39]
	s_add_u32 s12, s12, 64
	s_addc_u32 s13, s13, 0
	v_mfma_f32_16x16x32_bf16 v[8:11], v[138:141], v[154:157], v[8:11]
	s_add_i32 s27, s27, 0x8000
	s_cmpk_eq_i32 s12, 0x1f40
	v_mfma_f32_16x16x32_bf16 v[48:51], v[138:141], v[162:165], v[48:51]
	v_mfma_f32_16x16x32_bf16 v[12:15], v[138:141], v[166:169], v[12:15]
	v_add_u32_e32 v138, 0x4000, v159
	v_add_u32_e32 v139, 0x6000, v159
	v_readfirstlane_b32 s34, v138
	v_readfirstlane_b32 s38, v139
	s_mov_b32 m0, s34
	v_mfma_f32_16x16x32_bf16 v[44:47], v[142:145], v[150:153], v[44:47]
	global_load_lds_dwordx4 v[136:137], off
	s_mov_b32 m0, s38
	v_mfma_f32_16x16x32_bf16 v[16:19], v[142:145], v[154:157], v[16:19]
	global_load_lds_dwordx4 v[134:135], off
	v_mfma_f32_16x16x32_bf16 v[40:43], v[142:145], v[162:165], v[40:43]
	v_mfma_f32_16x16x32_bf16 v[20:23], v[142:145], v[166:169], v[20:23]
	v_mfma_f32_16x16x32_bf16 v[36:39], v[146:149], v[150:153], v[36:39]
	v_mfma_f32_16x16x32_bf16 v[24:27], v[146:149], v[154:157], v[24:27]
	v_mfma_f32_16x16x32_bf16 v[32:35], v[146:149], v[162:165], v[32:35]
	v_mfma_f32_16x16x32_bf16 v[28:31], v[146:149], v[166:169], v[28:31]
	s_cbranch_scc0 .LBB0_1328
	s_setprio 0
	s_waitcnt vmcnt(8)
	s_barrier
	v_add_u32_e32 v158, 0x8000, v133
	v_or_b32_e32 v159, 0x8000, v132
	ds_read_b128 v[128:131], v158
	ds_read_b128 v[134:137], v158 offset:1024
	ds_read_b128 v[138:141], v158 offset:2048
	ds_read_b128 v[142:145], v158 offset:3072
	ds_read_b128 v[146:149], v159
	ds_read_b128 v[150:153], v159 offset:1024
	ds_read_b128 v[154:157], v159 offset:2048
	ds_read_b128 v[162:165], v159 offset:3072
	s_waitcnt lgkmcnt(0)
	v_or_b32_e32 v159, 0x10000, v132
	v_mfma_f32_16x16x32_bf16 v[124:127], v[128:131], v[146:149], v[124:127]
	v_add_u32_e32 v160, 0x18000, v133
	v_or_b32_e32 v132, 0x18000, v132
	s_movk_i32 s12, 0x4400
	v_mfma_f32_16x16x32_bf16 v[120:123], v[128:131], v[150:153], v[120:123]
	s_mul_i32 s13, s15, 0xf0f0f0f1
	v_and_b32_e32 v183, 63, v188
	v_mfma_f32_16x16x32_bf16 v[116:119], v[128:131], v[154:157], v[116:119]
	v_mfma_f32_16x16x32_bf16 v[108:111], v[128:131], v[162:165], v[108:111]
	v_mfma_f32_16x16x32_bf16 v[104:107], v[134:137], v[146:149], v[104:107]
	v_mfma_f32_16x16x32_bf16 v[100:103], v[134:137], v[150:153], v[100:103]
	v_mfma_f32_16x16x32_bf16 v[96:99], v[134:137], v[154:157], v[96:99]
	v_mfma_f32_16x16x32_bf16 v[92:95], v[134:137], v[162:165], v[92:95]
	v_mfma_f32_16x16x32_bf16 v[88:91], v[138:141], v[146:149], v[88:91]
	v_mfma_f32_16x16x32_bf16 v[84:87], v[138:141], v[150:153], v[84:87]
	v_mfma_f32_16x16x32_bf16 v[80:83], v[138:141], v[154:157], v[80:83]
	v_mfma_f32_16x16x32_bf16 v[76:79], v[138:141], v[162:165], v[76:79]
	v_mfma_f32_16x16x32_bf16 v[72:75], v[142:145], v[146:149], v[72:75]
	v_mfma_f32_16x16x32_bf16 v[68:71], v[142:145], v[150:153], v[68:71]
	v_mfma_f32_16x16x32_bf16 v[64:67], v[142:145], v[154:157], v[64:67]
	v_mfma_f32_16x16x32_bf16 v[60:63], v[142:145], v[162:165], v[60:63]
	ds_read_b128 v[128:131], v158 offset:4096
	ds_read_b128 v[134:137], v158 offset:5120
	ds_read_b128 v[138:141], v158 offset:6144
	ds_read_b128 v[142:145], v158 offset:7168
	s_waitcnt lgkmcnt(0)
	s_waitcnt vmcnt(4)
	s_barrier
; #define ROW4(accv, r, av)                                                                              \
;     accv[r][0] = MFMA16(av, b0, accv[r][0]); accv[r][1] = MFMA16(av, b1, accv[r][1]);                      \
;     accv[r][2] = MFMA16(av, b2, accv[r][2]); accv[r][3] = MFMA16(av, b3, accv[r][3]);
; template <int EPI>
; __device__ __forceinline__ void gemm_tile_dma(const bft* __restrict__ A, int lda, const bft* __restrict__ Bt, int K, int row0, int col0,
;                                               char* smem, const EpiArgs& e) {
;     ...
;   for (int kt = 0; kt < nk; ++kt) {
;     if (kt + 2 < nk) asm volatile("s_waitcnt vmcnt(8)" ::: "memory");
;     else if (kt + 1 < nk) asm volatile("s_waitcnt vmcnt(4)" ::: "memory");
;     else asm volatile("s_waitcnt vmcnt(0)" ::: "memory");
;     __builtin_amdgcn_s_barrier();
;     asm volatile("" ::: "memory");
;     const bool pf = kt + 3 < nk;
;     const unsigned so = (unsigned)(kt & 3) * GST;
;     bf16x8 a0, a1, a2, a3, b0, b1, b2, b3;
;     asm volatile(
;         "ds_read_b128 %0, %8\n\t"
;         "ds_read_b128 %1, %8 offset:1024\n\t"
;         "ds_read_b128 %2, %8 offset:2048\n\t"
;         "ds_read_b128 %3, %8 offset:3072\n\t"
;         "ds_read_b128 %4, %9\n\t"
;         "ds_read_b128 %5, %9 offset:1024\n\t"
;         "ds_read_b128 %6, %9 offset:2048\n\t"
;         "ds_read_b128 %7, %9 offset:3072\n\t"
;         "s_waitcnt lgkmcnt(0)"
;         : "=&v"(a0), "=&v"(a1), "=&v"(a2), "=&v"(a3), "=&v"(b0), "=&v"(b1), "=&v"(b2), "=&v"(b3)
;         : "v"(lds_a + so), "v"(lds_b + so)
;         : "memory");
;     ...
;     ROW4(accL, 0, a0) ROW4(accL, 1, a1)
;     if (pf) GEMM_DMA_A(kt + 3)
;     ROW4(accL, 2, a2) ROW4(accL, 3, a3)
;     asm volatile(
;         "ds_read_b128 %0, %4 offset:4096\n\t"
;         "ds_read_b128 %1, %4 offset:5120\n\t"
;         "ds_read_b128 %2, %4 offset:6144\n\t"
;         "ds_read_b128 %3, %4 offset:7168\n\t"
;         "s_waitcnt lgkmcnt(0)"
;         : "=&v"(a0), "=&v"(a1), "=&v"(a2), "=&v"(a3)
;         : "v"(lds_a + so)
;         : "memory");
;     ROW4(accH, 0, a0) ROW4(accH, 1, a1)
;     if (pf) GEMM_DMA_B(kt + 3)
;     ROW4(accH, 2, a2) ROW4(accH, 3, a3)
	v_mfma_f32_16x16x32_bf16 v[112:115], v[128:131], v[146:149], v[112:115]
	v_add_u32_e32 v158, 0x10000, v133
	v_mfma_f32_16x16x32_bf16 v[0:3], v[128:131], v[150:153], v[0:3]
	v_mfma_f32_16x16x32_bf16 v[56:59], v[128:131], v[154:157], v[56:59]
	v_mfma_f32_16x16x32_bf16 v[4:7], v[128:131], v[162:165], v[4:7]
	v_mfma_f32_16x16x32_bf16 v[52:55], v[134:137], v[146:149], v[52:55]
	v_mfma_f32_16x16x32_bf16 v[8:11], v[134:137], v[150:153], v[8:11]
	v_mfma_f32_16x16x32_bf16 v[48:51], v[134:137], v[154:157], v[48:51]
	v_mfma_f32_16x16x32_bf16 v[12:15], v[134:137], v[162:165], v[12:15]
	v_mfma_f32_16x16x32_bf16 v[44:47], v[138:141], v[146:149], v[44:47]
	v_mfma_f32_16x16x32_bf16 v[16:19], v[138:141], v[150:153], v[16:19]
	v_mfma_f32_16x16x32_bf16 v[128:131], v[138:141], v[154:157], v[40:43]
	v_mfma_f32_16x16x32_bf16 v[20:23], v[138:141], v[162:165], v[20:23]
	v_mfma_f32_16x16x32_bf16 v[134:137], v[142:145], v[146:149], v[36:39]
	v_mfma_f32_16x16x32_bf16 v[24:27], v[142:145], v[150:153], v[24:27]
	v_mfma_f32_16x16x32_bf16 v[32:35], v[142:145], v[154:157], v[32:35]
	v_mfma_f32_16x16x32_bf16 v[28:31], v[142:145], v[162:165], v[28:31]
	ds_read_b128 v[138:141], v158
	ds_read_b128 v[142:145], v158 offset:1024
	ds_read_b128 v[146:149], v158 offset:2048
	ds_read_b128 v[150:153], v158 offset:3072
	ds_read_b128 v[154:157], v159
	ds_read_b128 v[40:43], v159 offset:1024
	ds_read_b128 v[162:165], v159 offset:2048
	ds_read_b128 v[36:39], v159 offset:3072
	s_waitcnt lgkmcnt(0)
	s_nop 0
	v_mfma_f32_16x16x32_bf16 v[124:127], v[138:141], v[154:157], v[124:127]
	v_mfma_f32_16x16x32_bf16 v[120:123], v[138:141], v[40:43], v[120:123]
	v_mfma_f32_16x16x32_bf16 v[116:119], v[138:141], v[162:165], v[116:119]
	v_mfma_f32_16x16x32_bf16 v[108:111], v[138:141], v[36:39], v[108:111]
	v_mfma_f32_16x16x32_bf16 v[104:107], v[142:145], v[154:157], v[104:107]
	v_mfma_f32_16x16x32_bf16 v[100:103], v[142:145], v[40:43], v[100:103]
	v_mfma_f32_16x16x32_bf16 v[96:99], v[142:145], v[162:165], v[96:99]
	v_mfma_f32_16x16x32_bf16 v[138:141], v[142:145], v[36:39], v[92:95]
	v_mfma_f32_16x16x32_bf16 v[142:145], v[146:149], v[154:157], v[88:91]
	v_mfma_f32_16x16x32_bf16 v[178:181], v[146:149], v[40:43], v[84:87]
	v_mfma_f32_16x16x32_bf16 v[184:187], v[146:149], v[162:165], v[80:83]
	v_mfma_f32_16x16x32_bf16 v[76:79], v[146:149], v[36:39], v[76:79]
	v_mfma_f32_16x16x32_bf16 v[192:195], v[150:153], v[154:157], v[72:75]
	v_mfma_f32_16x16x32_bf16 v[198:201], v[150:153], v[40:43], v[68:71]
	v_mfma_f32_16x16x32_bf16 v[206:209], v[150:153], v[36:39], v[60:63]
	ds_read_b128 v[88:91], v158 offset:4096
	ds_read_b128 v[84:87], v158 offset:5120
	ds_read_b128 v[68:71], v158 offset:6144
	ds_read_b128 v[60:63], v158 offset:7168
	s_waitcnt lgkmcnt(0)
	s_waitcnt vmcnt(0)
	s_barrier
	v_mfma_f32_16x16x32_bf16 v[210:213], v[88:91], v[154:157], v[112:115]
	v_mfma_f32_16x16x32_bf16 v[202:205], v[150:153], v[162:165], v[64:67]
	v_mfma_f32_16x16x32_bf16 v[64:67], v[88:91], v[162:165], v[56:59]
	v_mfma_f32_16x16x32_bf16 v[214:217], v[84:87], v[154:157], v[52:55]
	v_mfma_f32_16x16x32_bf16 v[72:75], v[84:87], v[162:165], v[48:51]
	v_mfma_f32_16x16x32_bf16 v[80:83], v[68:71], v[162:165], v[128:131]
	v_mfma_f32_16x16x32_bf16 v[56:59], v[60:63], v[162:165], v[32:35]
	ds_read_b128 v[32:35], v160
	ds_read_b128 v[112:115], v160 offset:1024
	ds_read_b128 v[128:131], v160 offset:2048
	ds_read_b128 v[222:225], v160 offset:3072
	ds_read_b128 v[226:229], v132
	ds_read_b128 v[52:55], v132 offset:1024
	ds_read_b128 v[92:95], v132 offset:2048
	ds_read_b128 v[48:51], v132 offset:3072
	s_waitcnt lgkmcnt(0)
	s_nop 0
	v_mfma_f32_16x16x32_bf16 v[148:151], v[112:115], v[48:51], v[138:141]
	v_mfma_f32_16x16x32_bf16 v[144:147], v[128:131], v[226:229], v[142:145]
	v_mfma_f32_16x16x32_bf16 v[140:143], v[128:131], v[52:55], v[178:181]
	s_nop 2
	v_lshrrev_b32_e32 v178, 6, v188
	v_mfma_f32_16x16x32_bf16 v[44:47], v[68:71], v[154:157], v[44:47]
	v_mfma_f32_16x16x32_bf16 v[218:221], v[60:63], v[154:157], v[134:137]
	v_mfma_f32_16x16x32_bf16 v[166:169], v[32:35], v[48:51], v[108:111]
	v_mfma_f32_16x16x32_bf16 v[162:165], v[112:115], v[226:229], v[104:107]
	v_mfma_f32_16x16x32_bf16 v[156:159], v[112:115], v[52:55], v[100:103]
	v_mfma_f32_16x16x32_bf16 v[152:155], v[112:115], v[92:95], v[96:99]
	ds_read_b128 v[112:115], v160 offset:4096
	ds_read_b128 v[108:111], v160 offset:5120
	ds_read_b128 v[104:107], v160 offset:6144
	ds_read_b128 v[100:103], v160 offset:7168
	s_waitcnt lgkmcnt(0)
	v_and_b32_e32 v160, 0xc0, v188
	s_waitcnt vmcnt(0) lgkmcnt(0)
	v_mfma_f32_16x16x32_bf16 v[136:139], v[128:131], v[92:95], v[184:187]
	s_barrier
; template <int EPI>
; DI void epilogue_tile(const EpiArgs& e, int row0, int wrow, int wcol, f32x4 (&acc)[4][4], char* smem, const float* rsm, int wave, int lane,
;                       bool final_sync = true) {
;     ...
;       if constexpr (EPI == EPI_RES) {
;         const float gg = e.gate[(size_t)mi_mod * 6144 + col], bb = e.bias[col];
; #pragma unroll
;         for (int j = 0; j < 4; ++j) v[j] = gg * (v[j] + bb);
;       }
;       if constexpr (EPI == EPI_FF1) {
;         const float bb = e.bias[col];
; #pragma unroll
;         for (int j = 0; j < 4; ++j) { const float t = fmaxf(v[j] + bb, 0.f); v[j] = t * t; }
;       }
;       if (transposed) {
;         *(f32x4*)(stage + lcol * STG + lrow) = (f32x4){v[0], v[1], v[2], v[3]};
;       } else {
; #pragma unroll
;         for (int j = 0; j < 4; ++j) stage[(lrow + j) * STG + lcol] = v[j];
;       }
	v_mfma_f32_16x16x32_bf16 v[132:135], v[128:131], v[48:51], v[76:79]
	v_mfma_f32_16x16x32_bf16 v[128:131], v[222:225], v[226:229], v[192:195]
	s_nop 2
	v_mul_lo_u32 v195, v178, s12
	s_mul_hi_u32 s12, s16, 0xf0f0f10
	v_mfma_f32_16x16x32_bf16 v[96:99], v[112:115], v[226:229], v[210:213]
	s_mulk_i32 s12, 0x6000
	v_mov_b32_e32 v178, 0x60000
	v_lshl_or_b32 v192, v182, 2, v195
	v_or_b32_e32 v211, s17, v160
	v_alignbit_b32 v160, s13, s13, 8
	s_mov_b32 s13, 0xf0f0f
	v_cmp_lt_u32_e32 vcc, s13, v160
	v_mov_b32_e32 v160, s12
	v_mfma_f32_16x16x32_bf16 v[76:79], v[108:111], v[226:229], v[214:217]
	v_cndmask_b32_e32 v160, v178, v160, vcc
	v_lshl_add_u64 v[186:187], s[10:11], 0, v[160:161]
	v_or_b32_e32 v160, v211, v182
	v_lshlrev_b32_e32 v160, 2, v160
	v_readfirstlane_b32 s12, v186
	v_readfirstlane_b32 s13, v187
	global_load_dword v215, v160, s[6:7]
	v_mfma_f32_16x16x32_bf16 v[230:233], v[32:35], v[226:229], v[124:127]
	v_bfe_u32 v212, v188, 2, 4
	v_lshl_add_u64 v[178:179], v[186:187], 0, v[160:161]
	v_lshl_add_u64 v[180:181], s[6:7], 0, v[160:161]
	global_load_dword v214, v160, s[12:13]
	v_mfma_f32_16x16x32_bf16 v[124:127], v[222:225], v[52:55], v[198:201]
	s_waitcnt vmcnt(1)
	s_nop 1
	v_add_f32_e32 v160, v230, v215
	v_and_b32_e32 v198, 12, v212
	v_or_b32_e32 v199, 48, v183
	v_add_f32_e32 v183, v231, v215
	v_add_f32_e32 v184, v232, v215
	s_waitcnt vmcnt(0)
	v_mul_f32_e32 v160, v214, v160
	v_mad_u32_u24 v213, v198, s35, v192
	v_mul_f32_e32 v183, v214, v183
	v_mul_f32_e32 v184, v214, v184
	ds_write_b32 v213, v160
	ds_write_b32 v213, v183 offset:272
	ds_write_b32 v213, v184 offset:544
	v_add_lshl_u32 v160, v211, v182, 2
	global_load_dword v216, v160, s[12:13] offset:64
	global_load_dword v217, v160, s[6:7] offset:64
	v_mfma_f32_16x16x32_bf16 v[174:177], v[32:35], v[52:55], v[120:123]
	v_add_f32_e32 v185, v233, v215
	v_or_b32_e32 v200, 3, v212
	v_mul_f32_e32 v185, v214, v185
	v_mad_u32_u24 v201, v200, s35, v192
	ds_write_b32 v201, v185
	v_mfma_f32_16x16x32_bf16 v[170:173], v[32:35], v[92:95], v[116:119]
	v_lshl_add_u64 v[182:183], v[186:187], 0, v[160:161]
	v_lshl_add_u64 v[184:185], s[6:7], 0, v[160:161]
	v_lshl_or_b32 v191, v199, 2, v195
	v_add_f32_e32 v162, v162, v215
	v_add_f32_e32 v163, v163, v215
	v_mul_f32_e32 v162, v214, v162
	v_mul_f32_e32 v163, v214, v163
	v_add_f32_e32 v164, v164, v215
	v_mul_f32_e32 v164, v214, v164
	v_add_f32_e32 v165, v165, v215
	v_mul_f32_e32 v165, v214, v165
	v_add_f32_e32 v144, v144, v215
	v_add_f32_e32 v145, v145, v215
	v_mul_f32_e32 v144, v214, v144
	v_mul_f32_e32 v145, v214, v145
	v_add_f32_e32 v146, v146, v215
	v_mfma_f32_16x16x32_bf16 v[120:123], v[222:225], v[92:95], v[202:205]
	v_mul_f32_e32 v146, v214, v146
	v_add_f32_e32 v147, v147, v215
	v_mul_f32_e32 v147, v214, v147
	v_mfma_f32_16x16x32_bf16 v[116:119], v[222:225], v[48:51], v[206:209]
	v_add_f32_e32 v128, v128, v215
	v_add_f32_e32 v129, v129, v215
	v_mul_f32_e32 v128, v214, v128
	v_mul_f32_e32 v129, v214, v129
	v_add_f32_e32 v130, v130, v215
	v_mul_f32_e32 v130, v214, v130
	v_add_f32_e32 v131, v131, v215
	v_mul_f32_e32 v131, v214, v131
	v_mfma_f32_16x16x32_bf16 v[44:47], v[104:107], v[226:229], v[44:47]
	v_mul_u32_u24_e32 v193, 0x110, v198
	v_mul_u32_u24_e32 v194, 0x110, v200
	s_waitcnt vmcnt(0)
	v_add_f32_e32 v174, v174, v217
	v_mul_f32_e32 v174, v216, v174
	v_add_f32_e32 v175, v175, v217
	v_add_f32_e32 v176, v176, v217
	v_add_f32_e32 v177, v177, v217
	v_mul_f32_e32 v175, v216, v175
	v_mul_f32_e32 v176, v216, v176
	v_mul_f32_e32 v177, v216, v177
	ds_write_b32 v213, v174 offset:64
	ds_write_b32 v213, v175 offset:336
	ds_write_b32 v213, v176 offset:608
	ds_write_b32 v201, v177 offset:64
	global_load_dword v174, v160, s[12:13] offset:128
	global_load_dword v175, v160, s[6:7] offset:128
	v_mad_u32_u24 v177, v198, s35, v191
	v_add_f32_e32 v156, v156, v217
	v_mul_f32_e32 v156, v216, v156
	v_add_f32_e32 v157, v157, v217
	v_add_f32_e32 v158, v158, v217
	v_add_f32_e32 v159, v159, v217
	v_mul_f32_e32 v157, v216, v157
	v_mul_f32_e32 v158, v216, v158
	v_mul_f32_e32 v159, v216, v159
	v_add_f32_e32 v140, v140, v217
	v_mul_f32_e32 v140, v216, v140
	v_add_f32_e32 v141, v141, v217
	v_add_f32_e32 v142, v142, v217
	v_add_f32_e32 v143, v143, v217
	v_mul_f32_e32 v141, v216, v141
	v_mul_f32_e32 v142, v216, v142
	v_mul_f32_e32 v143, v216, v143
	v_add_f32_e32 v124, v124, v217
	v_mul_f32_e32 v124, v216, v124
	v_add_f32_e32 v125, v125, v217
	v_add_f32_e32 v126, v126, v217
	v_add_f32_e32 v127, v127, v217
	v_mul_f32_e32 v125, v216, v125
	v_mul_f32_e32 v126, v216, v126
	v_mul_f32_e32 v127, v216, v127
	v_mfma_f32_16x16x32_bf16 v[32:35], v[100:103], v[226:229], v[218:221]
	s_waitcnt vmcnt(0)
; template <int EPI>
; DI void epilogue_tile(const EpiArgs& e, int row0, int wrow, int wcol, f32x4 (&acc)[4][4], char* smem, const float* rsm, int wave, int lane,
;                       bool final_sync = true) {
;     ...
;       if constexpr (EPI == EPI_RES) {
;         const float gg = e.gate[(size_t)mi_mod * 6144 + col], bb = e.bias[col];
; #pragma unroll
;         for (int j = 0; j < 4; ++j) v[j] = gg * (v[j] + bb);
;       }
;       if constexpr (EPI == EPI_FF1) {
;         const float bb = e.bias[col];
; #pragma unroll
;         for (int j = 0; j < 4; ++j) { const float t = fmaxf(v[j] + bb, 0.f); v[j] = t * t; }
;       }
;       if (transposed) {
;         *(f32x4*)(stage + lcol * STG + lrow) = (f32x4){v[0], v[1], v[2], v[3]};
;       } else {
; #pragma unroll
;         for (int j = 0; j < 4; ++j) stage[(lrow + j) * STG + lcol] = v[j];
;       }
;     }
;   const int rr = lane >> 3, c8 = (lane & 7) * 8;
; #pragma unroll 4
;   for (int it = 0; it < 8; ++it) {
;     const int sr = it * 8 + rr;
;     const f32x4 v0 = *(const f32x4*)(stage + sr * STG + c8);
;     const f32x4 v1 = *(const f32x4*)(stage + sr * STG + c8 + 4);
;     if constexpr (EPI == EPI_RES) {
;       bft* px = (bft*)(e.ws + OFF_XS) + (size_t)(wrow + sr) * D + wcol + c8;
	v_add_f32_e32 v160, v170, v175
	v_mul_f32_e32 v160, v174, v160
	v_add_f32_e32 v170, v171, v175
	v_add_f32_e32 v171, v172, v175
	v_add_f32_e32 v172, v173, v175
	v_mul_f32_e32 v170, v174, v170
	v_mul_f32_e32 v171, v174, v171
	v_mul_f32_e32 v172, v174, v172
	ds_write_b32 v213, v160 offset:128
	ds_write_b32 v213, v170 offset:400
	ds_write_b32 v213, v171 offset:672
	ds_write_b32 v201, v172 offset:128
	v_or_b32_e32 v160, v211, v199
	v_lshlrev_b32_e32 v160, 2, v160
	v_lshl_add_u64 v[170:171], v[186:187], 0, v[160:161]
	global_load_dword v176, v160, s[12:13]
	v_lshl_add_u64 v[172:173], s[6:7], 0, v[160:161]
	global_load_dword v160, v160, s[6:7]
	v_add_f32_e32 v152, v152, v175
	v_mul_f32_e32 v152, v174, v152
	v_add_f32_e32 v153, v153, v175
	v_add_f32_e32 v154, v154, v175
	v_add_f32_e32 v155, v155, v175
	v_mul_f32_e32 v153, v174, v153
	v_mul_f32_e32 v154, v174, v154
	v_mul_f32_e32 v155, v174, v155
	v_add_f32_e32 v136, v136, v175
	v_mul_f32_e32 v136, v174, v136
	v_add_f32_e32 v137, v137, v175
	v_add_f32_e32 v138, v138, v175
	v_add_f32_e32 v139, v139, v175
	v_mul_f32_e32 v137, v174, v137
	v_mul_f32_e32 v138, v174, v138
	v_mul_f32_e32 v139, v174, v139
	v_add_f32_e32 v120, v120, v175
	v_mul_f32_e32 v120, v174, v120
	v_add_f32_e32 v121, v121, v175
	v_add_f32_e32 v122, v122, v175
	v_add_f32_e32 v123, v123, v175
	v_mul_f32_e32 v121, v174, v121
	v_mul_f32_e32 v122, v174, v122
	v_mul_f32_e32 v123, v174, v123
	s_mov_b32 s12, 0
	s_waitcnt vmcnt(0)
	v_add_f32_e32 v166, v166, v160
	v_add_f32_e32 v167, v167, v160
	v_mul_f32_e32 v166, v176, v166
	v_mul_f32_e32 v167, v176, v167
	v_add_f32_e32 v168, v168, v160
	v_add_f32_e32 v169, v169, v160
	v_mul_f32_e32 v168, v176, v168
	v_mul_f32_e32 v169, v176, v169
	ds_write2_b32 v177, v166, v167 offset1:68
	ds_write_b32 v177, v168 offset:544
	v_mad_u32_u24 v166, v200, s35, v191
	ds_write_b32 v166, v169
	ds_write_b32 v213, v162 offset:4352
	ds_write_b32 v213, v163 offset:4624
	ds_write_b32 v213, v164 offset:4896
	v_or_b32_e32 v163, 19, v212
	v_mad_u32_u24 v164, v163, s35, v192
	v_add_f32_e32 v148, v148, v160
	v_add_f32_e32 v149, v149, v160
	ds_write_b32 v164, v165
	ds_write_b32 v213, v156 offset:4416
	ds_write_b32 v213, v157 offset:4688
	ds_write_b32 v213, v158 offset:4960
	ds_write_b32 v164, v159 offset:64
	ds_write_b32 v213, v152 offset:4480
	ds_write_b32 v213, v153 offset:4752
	ds_write_b32 v213, v154 offset:5024
	ds_write_b32 v164, v155 offset:128
	v_mul_f32_e32 v148, v176, v148
	v_mul_f32_e32 v149, v176, v149
	v_add_f32_e32 v150, v150, v160
	v_add_f32_e32 v151, v151, v160
	v_add_u32_e32 v152, 0x1000, v177
	v_mul_f32_e32 v150, v176, v150
	v_mul_f32_e32 v151, v176, v151
	ds_write2_b32 v152, v148, v149 offset0:64 offset1:132
	ds_write_b32 v177, v150 offset:4896
	v_mad_u32_u24 v148, v163, s35, v191
	ds_write_b32 v148, v151
	ds_write_b32 v213, v144 offset:8704
	ds_write_b32 v213, v145 offset:8976
	ds_write_b32 v213, v146 offset:9248
	v_or_b32_e32 v145, 35, v212
	v_mad_u32_u24 v146, v145, s35, v192
	v_add_f32_e32 v132, v132, v160
	v_add_f32_e32 v133, v133, v160
	ds_write_b32 v146, v147
	ds_write_b32 v213, v140 offset:8768
	ds_write_b32 v213, v141 offset:9040
	ds_write_b32 v213, v142 offset:9312
	ds_write_b32 v146, v143 offset:64
	ds_write_b32 v213, v136 offset:8832
	ds_write_b32 v213, v137 offset:9104
	ds_write_b32 v213, v138 offset:9376
	ds_write_b32 v146, v139 offset:128
	v_mul_f32_e32 v132, v176, v132
	v_mul_f32_e32 v133, v176, v133
	v_add_f32_e32 v134, v134, v160
	v_add_f32_e32 v135, v135, v160
	v_add_u32_e32 v136, 0x2000, v177
	v_mul_f32_e32 v134, v176, v134
	v_mul_f32_e32 v135, v176, v135
	ds_write2_b32 v136, v132, v133 offset0:128 offset1:196
	ds_write_b32 v177, v134 offset:9248
	v_mad_u32_u24 v132, v145, s35, v191
	ds_write_b32 v132, v135
	ds_write_b32 v213, v128 offset:13056
	ds_write_b32 v213, v129 offset:13328
	ds_write_b32 v213, v130 offset:13600
	v_or_b32_e32 v129, 51, v212
	v_mad_u32_u24 v130, v129, s35, v192
	v_add_f32_e32 v116, v116, v160
	v_add_f32_e32 v117, v117, v160
	ds_write_b32 v130, v131
	ds_write_b32 v213, v124 offset:13120
	ds_write_b32 v213, v125 offset:13392
	ds_write_b32 v213, v126 offset:13664
	ds_write_b32 v130, v127 offset:64
	ds_write_b32 v213, v120 offset:13184
	ds_write_b32 v213, v121 offset:13456
	ds_write_b32 v213, v122 offset:13728
	ds_write_b32 v130, v123 offset:128
	v_mul_f32_e32 v116, v176, v116
	v_mul_f32_e32 v117, v176, v117
	v_add_f32_e32 v118, v118, v160
	v_add_f32_e32 v119, v119, v160
	v_add_u32_e32 v120, 0x3200, v177
	v_mul_f32_e32 v118, v176, v118
	v_mul_f32_e32 v119, v176, v119
	ds_write2_b32 v120, v116, v117 offset0:64 offset1:132
	ds_write_b32 v177, v118 offset:13600
	v_mad_u32_u24 v116, v129, s35, v191
	ds_write_b32 v116, v119
	v_bfe_u32 v118, v188, 3, 3
	v_and_b32_e32 v119, 7, v188
	v_lshlrev_b32_e32 v160, 1, v211
	v_add3_u32 v120, v118, s15, v189
	v_mul_u32_u24_e32 v118, 0x110, v118
	v_lshlrev_b32_e32 v119, 5, v119
	v_lshl_add_u64 v[116:117], s[90:91], 0, v[160:161]
	v_and_b32_e32 v160, 0x70, v190
	v_add3_u32 v121, v195, v118, v119
	v_mul_u32_u24_e32 v162, 0x110, v163
	v_mul_u32_u24_e32 v144, 0x110, v145
	v_mul_u32_u24_e32 v128, 0x110, v129
	v_lshl_add_u64 v[116:117], v[116:117], 0, v[160:161]
	v_mov_b32_e32 v122, v121
